# accumulators initialised by first MFMAs (srcC=0, peeled first K-loop trip) instead of 128 v_mov per unit
# speedup vs baseline: 1.0083x; 1.0083x over previous
.LBB0_74:
	s_ashr_i32 s27, s26, 31
	s_lshl_b64 s[28:29], s[26:27], 19
	s_add_u32 s28, s3, s28
	s_addc_u32 s29, s35, s29
	s_and_b64 s[30:31], s[4:5], exec
	s_cselect_b32 s27, s29, s49
	s_cselect_b32 s68, s28, s48
	s_ashr_i32 s23, s22, 31
	s_lshl_b64 s[30:31], s[22:23], 19
	s_add_u32 s30, s50, s30
	s_addc_u32 s31, s51, s31
	s_and_b64 s[70:71], s[4:5], exec
	s_cselect_b32 s69, s31, s47
	s_cselect_b32 s70, s30, s46
	s_lshl_b32 s23, s44, 8
	v_add_u32_e32 v0, s23, v148
	s_add_u32 s71, s46, 0x100
	v_ashrrev_i32_e32 v1, 31, v0
	s_addc_u32 s74, s47, 0
	v_lshl_add_u64 v[144:145], v[0:1], 4, s[12:13]
	s_add_u32 s44, s48, 0x40080
	s_addc_u32 s45, s49, 0
	s_mov_b32 s75, -2
	s_mov_b64 s[46:47], 0
	v_add_u32_e32 v153, s64, v147
	ds_read_b128 v[160:163], v153
	ds_read_b128 v[164:167], v153 offset:1024
	ds_read_b128 v[168:171], v153 offset:2048
	ds_read_b128 v[172:175], v153 offset:3072
	v_add_u32_e32 v153, s65, v147
	ds_read_b128 v[176:179], v153
	ds_read_b128 v[180:183], v153 offset:1024
	ds_read_b128 v[186:189], v153 offset:2048
	ds_read_b128 v[190:193], v153 offset:3072
	s_add_u32 s48, s44, 0xfffc0080
	s_addc_u32 s49, s45, -1
	s_and_b64 s[46:47], s[46:47], exec
	s_cselect_b32 s49, s27, s49
	s_cselect_b32 s48, s68, s48
	s_cselect_b32 s47, s69, s74
	s_cselect_b32 s46, s70, s71
	v_lshl_add_u64 v[154:155], s[44:45], 0, v[138:139]
	s_add_i32 m0, s55, 0xc000
	ds_read_b128 v[194:197], v150
	ds_read_b128 v[198:201], v150 offset:1024
	ds_read_b128 v[202:205], v150 offset:2048
	ds_read_b128 v[206:209], v150 offset:3072
	ds_read_b128 v[210:213], v150 offset:4096
	ds_read_b128 v[214:217], v150 offset:5120
	ds_read_b128 v[218:221], v150 offset:6144
	ds_read_b128 v[222:225], v150 offset:7168
	global_load_lds_dwordx4 v[154:155], off
	v_lshl_add_u64 v[154:155], s[44:45], 0, v[136:137]
	s_add_i32 m0, s55, 0xe000
	s_nop 0
	global_load_lds_dwordx4 v[154:155], off
	s_waitcnt vmcnt(8)
	s_waitcnt lgkmcnt(0)
	s_barrier
	s_setprio 1
	s_waitcnt lgkmcnt(0)
	v_mfma_f32_16x16x32_bf16 v[124:127], v[160:163], v[194:197], 0
	v_mfma_f32_16x16x32_bf16 v[116:119], v[168:171], v[194:197], 0
	v_mfma_f32_16x16x32_bf16 v[108:111], v[160:163], v[202:205], 0
	v_mfma_f32_16x16x32_bf16 v[100:103], v[168:171], v[202:205], 0
	v_mfma_f32_16x16x32_bf16 v[92:95], v[160:163], v[210:213], 0
	v_mfma_f32_16x16x32_bf16 v[84:87], v[168:171], v[210:213], 0
	v_mfma_f32_16x16x32_bf16 v[76:79], v[160:163], v[218:221], 0
	v_mfma_f32_16x16x32_bf16 v[68:71], v[168:171], v[218:221], 0
	v_mfma_f32_16x16x32_bf16 v[124:127], v[164:167], v[198:201], v[124:127]
	v_mfma_f32_16x16x32_bf16 v[116:119], v[172:175], v[198:201], v[116:119]
	v_mfma_f32_16x16x32_bf16 v[108:111], v[164:167], v[206:209], v[108:111]
	v_mfma_f32_16x16x32_bf16 v[100:103], v[172:175], v[206:209], v[100:103]
	v_mfma_f32_16x16x32_bf16 v[92:95], v[164:167], v[214:217], v[92:95]
	v_mfma_f32_16x16x32_bf16 v[84:87], v[172:175], v[214:217], v[84:87]
	v_mfma_f32_16x16x32_bf16 v[76:79], v[164:167], v[222:225], v[76:79]
	v_mfma_f32_16x16x32_bf16 v[68:71], v[172:175], v[222:225], v[68:71]
	s_setprio 0
	s_setprio 1
	v_mfma_f32_16x16x32_bf16 v[120:123], v[176:179], v[194:197], 0
	v_mfma_f32_16x16x32_bf16 v[112:115], v[186:189], v[194:197], 0
	v_mfma_f32_16x16x32_bf16 v[104:107], v[176:179], v[202:205], 0
	v_mfma_f32_16x16x32_bf16 v[96:99], v[186:189], v[202:205], 0
	v_mfma_f32_16x16x32_bf16 v[88:91], v[176:179], v[210:213], 0
	v_mfma_f32_16x16x32_bf16 v[80:83], v[186:189], v[210:213], 0
	v_mfma_f32_16x16x32_bf16 v[72:75], v[176:179], v[218:221], 0
	v_mfma_f32_16x16x32_bf16 v[64:67], v[186:189], v[218:221], 0
	v_mfma_f32_16x16x32_bf16 v[120:123], v[180:183], v[198:201], v[120:123]
	v_mfma_f32_16x16x32_bf16 v[112:115], v[190:193], v[198:201], v[112:115]
	v_mfma_f32_16x16x32_bf16 v[104:107], v[180:183], v[206:209], v[104:107]
	v_mfma_f32_16x16x32_bf16 v[96:99], v[190:193], v[206:209], v[96:99]
	v_mfma_f32_16x16x32_bf16 v[88:91], v[180:183], v[214:217], v[88:91]
	v_mfma_f32_16x16x32_bf16 v[80:83], v[190:193], v[214:217], v[80:83]
	v_mfma_f32_16x16x32_bf16 v[72:75], v[180:183], v[222:225], v[72:75]
	v_mfma_f32_16x16x32_bf16 v[64:67], v[190:193], v[222:225], v[64:67]
	s_setprio 0
	s_barrier
	s_add_i32 s76, s64, s52
	v_lshl_add_u64 v[154:155], s[46:47], 0, v[132:133]
	s_mov_b32 m0, s76
	ds_read_b128 v[194:197], v150 offset:16384
	ds_read_b128 v[198:201], v150 offset:17408
	ds_read_b128 v[202:205], v150 offset:18432
	ds_read_b128 v[206:209], v150 offset:19456
	ds_read_b128 v[210:213], v150 offset:20480
	ds_read_b128 v[214:217], v150 offset:21504
	ds_read_b128 v[218:221], v150 offset:22528
	ds_read_b128 v[222:225], v150 offset:23552
	global_load_lds_dwordx4 v[154:155], off
	s_add_i32 m0, s76, 0x2000
	s_add_u32 s76, s46, 0x40000
	v_lshl_add_u64 v[226:227], s[46:47], 0, v[128:129]
	s_addc_u32 s77, s47, 0
	s_add_i32 s78, s65, s52
	global_load_lds_dwordx4 v[226:227], off
	v_lshl_add_u64 v[228:229], s[76:77], 0, v[132:133]
	s_mov_b32 m0, s78
	v_lshl_add_u64 v[230:231], s[48:49], 0, v[130:131]
	global_load_lds_dwordx4 v[228:229], off
	v_lshl_add_u64 v[228:229], s[76:77], 0, v[128:129]
	s_add_i32 m0, s78, 0x2000
	s_nop 0
	global_load_lds_dwordx4 v[228:229], off
	v_lshl_add_u64 v[228:229], s[48:49], 0, v[134:135]
	s_mov_b32 m0, s55
	s_nop 0
	global_load_lds_dwordx4 v[228:229], off
	s_mov_b32 m0, s56
	s_nop 0
	global_load_lds_dwordx4 v[230:231], off
	s_waitcnt vmcnt(8)
	s_waitcnt lgkmcnt(0)
	s_barrier
	s_setprio 1
	s_waitcnt lgkmcnt(0)
	v_mfma_f32_16x16x32_bf16 v[60:63], v[160:163], v[194:197], 0
	v_mfma_f32_16x16x32_bf16 v[52:55], v[168:171], v[194:197], 0
	v_mfma_f32_16x16x32_bf16 v[44:47], v[160:163], v[202:205], 0
	v_mfma_f32_16x16x32_bf16 v[36:39], v[168:171], v[202:205], 0
	v_mfma_f32_16x16x32_bf16 v[28:31], v[160:163], v[210:213], 0
	v_mfma_f32_16x16x32_bf16 v[20:23], v[168:171], v[210:213], 0
	v_mfma_f32_16x16x32_bf16 v[12:15], v[160:163], v[218:221], 0
	v_mfma_f32_16x16x32_bf16 v[4:7], v[168:171], v[218:221], 0
	v_mfma_f32_16x16x32_bf16 v[60:63], v[164:167], v[198:201], v[60:63]
	v_mfma_f32_16x16x32_bf16 v[52:55], v[172:175], v[198:201], v[52:55]
	v_mfma_f32_16x16x32_bf16 v[44:47], v[164:167], v[206:209], v[44:47]
	v_mfma_f32_16x16x32_bf16 v[36:39], v[172:175], v[206:209], v[36:39]
	v_mfma_f32_16x16x32_bf16 v[28:31], v[164:167], v[214:217], v[28:31]
	v_mfma_f32_16x16x32_bf16 v[20:23], v[172:175], v[214:217], v[20:23]
	v_mfma_f32_16x16x32_bf16 v[12:15], v[164:167], v[222:225], v[12:15]
	v_mfma_f32_16x16x32_bf16 v[4:7], v[172:175], v[222:225], v[4:7]
	s_setprio 0
	s_setprio 1
	v_mfma_f32_16x16x32_bf16 v[56:59], v[176:179], v[194:197], 0
	v_mfma_f32_16x16x32_bf16 v[48:51], v[186:189], v[194:197], 0
	v_mfma_f32_16x16x32_bf16 v[40:43], v[176:179], v[202:205], 0
	v_mfma_f32_16x16x32_bf16 v[32:35], v[186:189], v[202:205], 0
	v_mfma_f32_16x16x32_bf16 v[24:27], v[176:179], v[210:213], 0
	v_mfma_f32_16x16x32_bf16 v[16:19], v[186:189], v[210:213], 0
	v_mfma_f32_16x16x32_bf16 v[8:11], v[176:179], v[218:221], 0
	v_mfma_f32_16x16x32_bf16 v[0:3], v[186:189], v[218:221], 0
	v_mfma_f32_16x16x32_bf16 v[56:59], v[180:183], v[198:201], v[56:59]
	v_mfma_f32_16x16x32_bf16 v[48:51], v[190:193], v[198:201], v[48:51]
	v_mfma_f32_16x16x32_bf16 v[40:43], v[180:183], v[206:209], v[40:43]
	v_mfma_f32_16x16x32_bf16 v[32:35], v[190:193], v[206:209], v[32:35]
	v_mfma_f32_16x16x32_bf16 v[24:27], v[180:183], v[214:217], v[24:27]
	v_mfma_f32_16x16x32_bf16 v[16:19], v[190:193], v[214:217], v[16:19]
	v_mfma_f32_16x16x32_bf16 v[8:11], v[180:183], v[222:225], v[8:11]
	v_mfma_f32_16x16x32_bf16 v[0:3], v[190:193], v[222:225], v[0:3]
	s_setprio 0
	s_barrier
	s_add_i32 s76, 0, 0x18000
	v_add_u32_e32 v153, s76, v147
	s_add_i32 s77, 0, 0x1c000
	ds_read_b128 v[160:163], v153
	ds_read_b128 v[164:167], v153 offset:1024
	ds_read_b128 v[168:171], v153 offset:2048
	ds_read_b128 v[172:175], v153 offset:3072
	v_add_u32_e32 v153, s77, v147
	ds_read_b128 v[176:179], v153
	ds_read_b128 v[180:183], v153 offset:1024
	ds_read_b128 v[186:189], v153 offset:2048
	ds_read_b128 v[190:193], v153 offset:3072
	s_add_u32 s48, s48, 0x40000
	s_addc_u32 s49, s49, 0
	s_mov_b32 m0, s57
	v_lshl_add_u64 v[232:233], s[48:49], 0, v[134:135]
	ds_read_b128 v[194:197], v150 offset:32768
	ds_read_b128 v[198:201], v150 offset:33792
	ds_read_b128 v[202:205], v150 offset:34816
	ds_read_b128 v[206:209], v150 offset:35840
	ds_read_b128 v[210:213], v150 offset:36864
	ds_read_b128 v[214:217], v150 offset:37888
	ds_read_b128 v[218:221], v150 offset:38912
	ds_read_b128 v[222:225], v150 offset:39936
	global_load_lds_dwordx4 v[232:233], off
	v_lshl_add_u64 v[232:233], s[48:49], 0, v[130:131]
	s_mov_b32 m0, s58
	s_nop 0
	global_load_lds_dwordx4 v[232:233], off
	s_waitcnt vmcnt(8)
	s_waitcnt lgkmcnt(0)
	s_barrier
	s_setprio 1
	s_waitcnt lgkmcnt(0)
	v_mfma_f32_16x16x32_bf16 v[124:127], v[160:163], v[194:197], v[124:127]
	v_mfma_f32_16x16x32_bf16 v[116:119], v[168:171], v[194:197], v[116:119]
	v_mfma_f32_16x16x32_bf16 v[108:111], v[160:163], v[202:205], v[108:111]
	v_mfma_f32_16x16x32_bf16 v[100:103], v[168:171], v[202:205], v[100:103]
	v_mfma_f32_16x16x32_bf16 v[92:95], v[160:163], v[210:213], v[92:95]
	v_mfma_f32_16x16x32_bf16 v[84:87], v[168:171], v[210:213], v[84:87]
	v_mfma_f32_16x16x32_bf16 v[76:79], v[160:163], v[218:221], v[76:79]
	v_mfma_f32_16x16x32_bf16 v[68:71], v[168:171], v[218:221], v[68:71]
	v_mfma_f32_16x16x32_bf16 v[124:127], v[164:167], v[198:201], v[124:127]
	v_mfma_f32_16x16x32_bf16 v[116:119], v[172:175], v[198:201], v[116:119]
	v_mfma_f32_16x16x32_bf16 v[108:111], v[164:167], v[206:209], v[108:111]
	v_mfma_f32_16x16x32_bf16 v[100:103], v[172:175], v[206:209], v[100:103]
	v_mfma_f32_16x16x32_bf16 v[92:95], v[164:167], v[214:217], v[92:95]
	v_mfma_f32_16x16x32_bf16 v[84:87], v[172:175], v[214:217], v[84:87]
	v_mfma_f32_16x16x32_bf16 v[76:79], v[164:167], v[222:225], v[76:79]
	v_mfma_f32_16x16x32_bf16 v[68:71], v[172:175], v[222:225], v[68:71]
	s_setprio 0
	s_setprio 1
	v_mfma_f32_16x16x32_bf16 v[120:123], v[176:179], v[194:197], v[120:123]
	v_mfma_f32_16x16x32_bf16 v[112:115], v[186:189], v[194:197], v[112:115]
	v_mfma_f32_16x16x32_bf16 v[104:107], v[176:179], v[202:205], v[104:107]
	v_mfma_f32_16x16x32_bf16 v[96:99], v[186:189], v[202:205], v[96:99]
	v_mfma_f32_16x16x32_bf16 v[88:91], v[176:179], v[210:213], v[88:91]
	v_mfma_f32_16x16x32_bf16 v[80:83], v[186:189], v[210:213], v[80:83]
	v_mfma_f32_16x16x32_bf16 v[72:75], v[176:179], v[218:221], v[72:75]
	v_mfma_f32_16x16x32_bf16 v[64:67], v[186:189], v[218:221], v[64:67]
	v_mfma_f32_16x16x32_bf16 v[120:123], v[180:183], v[198:201], v[120:123]
	v_mfma_f32_16x16x32_bf16 v[112:115], v[190:193], v[198:201], v[112:115]
	v_mfma_f32_16x16x32_bf16 v[104:107], v[180:183], v[206:209], v[104:107]
	v_mfma_f32_16x16x32_bf16 v[96:99], v[190:193], v[206:209], v[96:99]
	v_mfma_f32_16x16x32_bf16 v[88:91], v[180:183], v[214:217], v[88:91]
	v_mfma_f32_16x16x32_bf16 v[80:83], v[190:193], v[214:217], v[80:83]
	v_mfma_f32_16x16x32_bf16 v[72:75], v[180:183], v[222:225], v[72:75]
	v_mfma_f32_16x16x32_bf16 v[64:67], v[190:193], v[222:225], v[64:67]
	s_setprio 0
	s_barrier
	s_add_i32 s48, s76, s52
	v_lshl_add_u64 v[154:155], v[154:155], 0, s[14:15]
	s_mov_b32 m0, s48
	ds_read_b128 v[194:197], v150 offset:49152
	ds_read_b128 v[198:201], v150 offset:50176
	ds_read_b128 v[202:205], v150 offset:51200
	ds_read_b128 v[206:209], v150 offset:52224
	ds_read_b128 v[210:213], v150 offset:53248
	ds_read_b128 v[214:217], v150 offset:54272
	ds_read_b128 v[218:221], v150 offset:55296
	ds_read_b128 v[222:225], v150 offset:56320
	global_load_lds_dwordx4 v[154:155], off
	s_add_i32 m0, s48, 0x2000
	s_add_u32 s46, s46, 0x40080
	v_lshl_add_u64 v[154:155], v[226:227], 0, s[14:15]
	s_addc_u32 s47, s47, 0
	s_add_i32 s48, s77, s52
	global_load_lds_dwordx4 v[154:155], off
	v_lshl_add_u64 v[154:155], s[46:47], 0, v[132:133]
	s_mov_b32 m0, s48
	s_nop 0
	global_load_lds_dwordx4 v[154:155], off
	v_lshl_add_u64 v[154:155], s[46:47], 0, v[128:129]
	s_add_i32 m0, s48, 0x2000
	s_nop 0
	global_load_lds_dwordx4 v[154:155], off
	v_lshl_add_u64 v[154:155], v[228:229], 0, s[14:15]
	s_mov_b32 m0, s60
	s_nop 0
	global_load_lds_dwordx4 v[154:155], off
	v_lshl_add_u64 v[154:155], v[230:231], 0, s[14:15]
	s_mov_b32 m0, s61
	s_nop 0
	global_load_lds_dwordx4 v[154:155], off
	s_waitcnt vmcnt(8)
	s_waitcnt lgkmcnt(0)
	s_barrier
	s_setprio 1
	s_waitcnt lgkmcnt(0)
	v_mfma_f32_16x16x32_bf16 v[60:63], v[160:163], v[194:197], v[60:63]
	v_mfma_f32_16x16x32_bf16 v[52:55], v[168:171], v[194:197], v[52:55]
	v_mfma_f32_16x16x32_bf16 v[44:47], v[160:163], v[202:205], v[44:47]
	v_mfma_f32_16x16x32_bf16 v[36:39], v[168:171], v[202:205], v[36:39]
	v_mfma_f32_16x16x32_bf16 v[28:31], v[160:163], v[210:213], v[28:31]
	v_mfma_f32_16x16x32_bf16 v[20:23], v[168:171], v[210:213], v[20:23]
	v_mfma_f32_16x16x32_bf16 v[12:15], v[160:163], v[218:221], v[12:15]
	v_mfma_f32_16x16x32_bf16 v[4:7], v[168:171], v[218:221], v[4:7]
	v_mfma_f32_16x16x32_bf16 v[60:63], v[164:167], v[198:201], v[60:63]
	v_mfma_f32_16x16x32_bf16 v[52:55], v[172:175], v[198:201], v[52:55]
	v_mfma_f32_16x16x32_bf16 v[44:47], v[164:167], v[206:209], v[44:47]
	v_mfma_f32_16x16x32_bf16 v[36:39], v[172:175], v[206:209], v[36:39]
	v_mfma_f32_16x16x32_bf16 v[28:31], v[164:167], v[214:217], v[28:31]
	v_mfma_f32_16x16x32_bf16 v[20:23], v[172:175], v[214:217], v[20:23]
	v_mfma_f32_16x16x32_bf16 v[12:15], v[164:167], v[222:225], v[12:15]
	v_mfma_f32_16x16x32_bf16 v[4:7], v[172:175], v[222:225], v[4:7]
	s_setprio 0
	s_setprio 1
	v_mfma_f32_16x16x32_bf16 v[56:59], v[176:179], v[194:197], v[56:59]
	v_mfma_f32_16x16x32_bf16 v[48:51], v[186:189], v[194:197], v[48:51]
	v_mfma_f32_16x16x32_bf16 v[40:43], v[176:179], v[202:205], v[40:43]
	v_mfma_f32_16x16x32_bf16 v[32:35], v[186:189], v[202:205], v[32:35]
	v_mfma_f32_16x16x32_bf16 v[24:27], v[176:179], v[210:213], v[24:27]
	v_mfma_f32_16x16x32_bf16 v[16:19], v[186:189], v[210:213], v[16:19]
	v_mfma_f32_16x16x32_bf16 v[8:11], v[176:179], v[218:221], v[8:11]
	v_mfma_f32_16x16x32_bf16 v[0:3], v[186:189], v[218:221], v[0:3]
	v_mfma_f32_16x16x32_bf16 v[56:59], v[180:183], v[198:201], v[56:59]
	v_mfma_f32_16x16x32_bf16 v[48:51], v[190:193], v[198:201], v[48:51]
	v_mfma_f32_16x16x32_bf16 v[40:43], v[180:183], v[206:209], v[40:43]
	v_mfma_f32_16x16x32_bf16 v[32:35], v[190:193], v[206:209], v[32:35]
	v_mfma_f32_16x16x32_bf16 v[24:27], v[180:183], v[214:217], v[24:27]
	v_mfma_f32_16x16x32_bf16 v[16:19], v[190:193], v[214:217], v[16:19]
	v_mfma_f32_16x16x32_bf16 v[8:11], v[180:183], v[222:225], v[8:11]
	v_mfma_f32_16x16x32_bf16 v[0:3], v[190:193], v[222:225], v[0:3]
	s_setprio 0
	s_barrier
	s_add_i32 s75, s75, 2
	s_add_u32 s71, s71, 0x100
	s_addc_u32 s74, s74, 0
	s_add_u32 s44, s44, 0x100
	s_addc_u32 s45, s45, 0
	s_branch .LBB0_76

.LBB0_158:
	s_add_u32 s81, s56, 0x100
	s_addc_u32 s82, s57, 0
	s_mov_b32 s83, -2
	s_waitcnt lgkmcnt(0)
	ds_read_b128 v[128:131], v189
	ds_read_b128 v[132:135], v189 offset:1024
	ds_read_b128 v[136:139], v189 offset:2048
	ds_read_b128 v[140:143], v189 offset:3072
	ds_read_b128 v[144:147], v190
	ds_read_b128 v[148:151], v190 offset:1024
	ds_read_b128 v[172:175], v190 offset:2048
	ds_read_b128 v[176:179], v190 offset:3072
	s_add_u32 s56, s54, 0x100
	s_addc_u32 s57, s55, 0
	s_cmp_eq_u32 s83, 40
	s_cselect_b32 s61, s15, s57
	s_cselect_b32 s60, s14, s56
	s_cselect_b32 s59, s53, s82
	s_cselect_b32 s58, s52, s81
	v_lshl_add_u64 v[222:223], s[54:55], 0, v[166:167]
	s_add_i32 m0, s66, 0xc000
	ds_read_b128 v[180:183], v191
	ds_read_b128 v[194:197], v191 offset:1024
	ds_read_b128 v[198:201], v191 offset:2048
	ds_read_b128 v[202:205], v191 offset:3072
	ds_read_b128 v[206:209], v191 offset:4096
	ds_read_b128 v[210:213], v191 offset:5120
	ds_read_b128 v[214:217], v191 offset:6144
	ds_read_b128 v[218:221], v191 offset:7168
	global_load_lds_dwordx4 v[222:223], off
	v_lshl_add_u64 v[222:223], s[54:55], 0, v[164:165]
	s_add_i32 m0, s66, 0xe000
	s_nop 0
	global_load_lds_dwordx4 v[222:223], off
	s_waitcnt vmcnt(8)
	s_waitcnt lgkmcnt(0)
	s_barrier
	s_setprio 1
	s_waitcnt lgkmcnt(0)
	v_mfma_f32_16x16x32_bf16 v[124:127], v[128:131], v[180:183], 0
	v_mfma_f32_16x16x32_bf16 v[120:123], v[136:139], v[180:183], 0
	v_mfma_f32_16x16x32_bf16 v[108:111], v[128:131], v[198:201], 0
	v_mfma_f32_16x16x32_bf16 v[104:107], v[136:139], v[198:201], 0
	v_mfma_f32_16x16x32_bf16 v[92:95], v[128:131], v[206:209], 0
	v_mfma_f32_16x16x32_bf16 v[88:91], v[136:139], v[206:209], 0
	v_mfma_f32_16x16x32_bf16 v[76:79], v[128:131], v[214:217], 0
	v_mfma_f32_16x16x32_bf16 v[72:75], v[136:139], v[214:217], 0
	v_mfma_f32_16x16x32_bf16 v[124:127], v[132:135], v[194:197], v[124:127]
	v_mfma_f32_16x16x32_bf16 v[120:123], v[140:143], v[194:197], v[120:123]
	v_mfma_f32_16x16x32_bf16 v[108:111], v[132:135], v[202:205], v[108:111]
	v_mfma_f32_16x16x32_bf16 v[104:107], v[140:143], v[202:205], v[104:107]
	v_mfma_f32_16x16x32_bf16 v[92:95], v[132:135], v[210:213], v[92:95]
	v_mfma_f32_16x16x32_bf16 v[88:91], v[140:143], v[210:213], v[88:91]
	v_mfma_f32_16x16x32_bf16 v[76:79], v[132:135], v[218:221], v[76:79]
	v_mfma_f32_16x16x32_bf16 v[72:75], v[140:143], v[218:221], v[72:75]
	s_setprio 0
	s_setprio 1
	v_mfma_f32_16x16x32_bf16 v[116:119], v[144:147], v[180:183], 0
	v_mfma_f32_16x16x32_bf16 v[112:115], v[172:175], v[180:183], 0
	v_mfma_f32_16x16x32_bf16 v[100:103], v[144:147], v[198:201], 0
	v_mfma_f32_16x16x32_bf16 v[96:99], v[172:175], v[198:201], 0
	v_mfma_f32_16x16x32_bf16 v[84:87], v[144:147], v[206:209], 0
	v_mfma_f32_16x16x32_bf16 v[80:83], v[172:175], v[206:209], 0
	v_mfma_f32_16x16x32_bf16 v[68:71], v[144:147], v[214:217], 0
	v_mfma_f32_16x16x32_bf16 v[64:67], v[172:175], v[214:217], 0
	v_mfma_f32_16x16x32_bf16 v[116:119], v[148:151], v[194:197], v[116:119]
	v_mfma_f32_16x16x32_bf16 v[112:115], v[176:179], v[194:197], v[112:115]
	v_mfma_f32_16x16x32_bf16 v[100:103], v[148:151], v[202:205], v[100:103]
	v_mfma_f32_16x16x32_bf16 v[96:99], v[176:179], v[202:205], v[96:99]
	v_mfma_f32_16x16x32_bf16 v[84:87], v[148:151], v[210:213], v[84:87]
	v_mfma_f32_16x16x32_bf16 v[80:83], v[176:179], v[210:213], v[80:83]
	v_mfma_f32_16x16x32_bf16 v[68:71], v[148:151], v[218:221], v[68:71]
	v_mfma_f32_16x16x32_bf16 v[64:67], v[176:179], v[218:221], v[64:67]
	s_setprio 0
	s_barrier
	s_add_i32 s54, s77, s65
	v_lshl_add_u64 v[222:223], s[58:59], 0, v[154:155]
	s_mov_b32 m0, s54
	ds_read_b128 v[180:183], v191 offset:16384
	ds_read_b128 v[194:197], v191 offset:17408
	ds_read_b128 v[198:201], v191 offset:18432
	ds_read_b128 v[202:205], v191 offset:19456
	ds_read_b128 v[206:209], v191 offset:20480
	ds_read_b128 v[210:213], v191 offset:21504
	ds_read_b128 v[214:217], v191 offset:22528
	ds_read_b128 v[218:221], v191 offset:23552
	global_load_lds_dwordx4 v[222:223], off
	s_add_i32 m0, s54, 0x2000
	s_add_u32 s54, s58, 0xb0000
	v_lshl_add_u64 v[224:225], s[58:59], 0, v[162:163]
	s_addc_u32 s55, s59, 0
	s_add_i32 s84, s78, s65
	global_load_lds_dwordx4 v[224:225], off
	v_lshl_add_u64 v[226:227], s[54:55], 0, v[154:155]
	s_mov_b32 m0, s84
	v_lshl_add_u64 v[228:229], s[60:61], 0, v[160:161]
	global_load_lds_dwordx4 v[226:227], off
	v_lshl_add_u64 v[226:227], s[54:55], 0, v[162:163]
	s_add_i32 m0, s84, 0x2000
	s_nop 0
	global_load_lds_dwordx4 v[226:227], off
	v_lshl_add_u64 v[226:227], s[60:61], 0, v[152:153]
	s_mov_b32 m0, s66
	s_nop 0
	global_load_lds_dwordx4 v[226:227], off
	s_mov_b32 m0, s67
	s_nop 0
	global_load_lds_dwordx4 v[228:229], off
	s_waitcnt vmcnt(8)
	s_waitcnt lgkmcnt(0)
	s_barrier
	s_setprio 1
	s_waitcnt lgkmcnt(0)
	v_mfma_f32_16x16x32_bf16 v[60:63], v[128:131], v[180:183], 0
	v_mfma_f32_16x16x32_bf16 v[56:59], v[136:139], v[180:183], 0
	v_mfma_f32_16x16x32_bf16 v[44:47], v[128:131], v[198:201], 0
	v_mfma_f32_16x16x32_bf16 v[40:43], v[136:139], v[198:201], 0
	v_mfma_f32_16x16x32_bf16 v[28:31], v[128:131], v[206:209], 0
	v_mfma_f32_16x16x32_bf16 v[24:27], v[136:139], v[206:209], 0
	v_mfma_f32_16x16x32_bf16 v[12:15], v[128:131], v[214:217], 0
	v_mfma_f32_16x16x32_bf16 v[8:11], v[136:139], v[214:217], 0
	v_mfma_f32_16x16x32_bf16 v[60:63], v[132:135], v[194:197], v[60:63]
	v_mfma_f32_16x16x32_bf16 v[56:59], v[140:143], v[194:197], v[56:59]
	v_mfma_f32_16x16x32_bf16 v[44:47], v[132:135], v[202:205], v[44:47]
	v_mfma_f32_16x16x32_bf16 v[40:43], v[140:143], v[202:205], v[40:43]
	v_mfma_f32_16x16x32_bf16 v[28:31], v[132:135], v[210:213], v[28:31]
	v_mfma_f32_16x16x32_bf16 v[24:27], v[140:143], v[210:213], v[24:27]
	v_mfma_f32_16x16x32_bf16 v[12:15], v[132:135], v[218:221], v[12:15]
	v_mfma_f32_16x16x32_bf16 v[8:11], v[140:143], v[218:221], v[8:11]
	s_setprio 0
	s_setprio 1
	v_mfma_f32_16x16x32_bf16 v[52:55], v[144:147], v[180:183], 0
	v_mfma_f32_16x16x32_bf16 v[48:51], v[172:175], v[180:183], 0
	v_mfma_f32_16x16x32_bf16 v[36:39], v[144:147], v[198:201], 0
	v_mfma_f32_16x16x32_bf16 v[32:35], v[172:175], v[198:201], 0
	v_mfma_f32_16x16x32_bf16 v[20:23], v[144:147], v[206:209], 0
	v_mfma_f32_16x16x32_bf16 v[16:19], v[172:175], v[206:209], 0
	v_mfma_f32_16x16x32_bf16 v[4:7], v[144:147], v[214:217], 0
	v_mfma_f32_16x16x32_bf16 v[0:3], v[172:175], v[214:217], 0
	v_mfma_f32_16x16x32_bf16 v[52:55], v[148:151], v[194:197], v[52:55]
	v_mfma_f32_16x16x32_bf16 v[48:51], v[176:179], v[194:197], v[48:51]
	v_mfma_f32_16x16x32_bf16 v[36:39], v[148:151], v[202:205], v[36:39]
	v_mfma_f32_16x16x32_bf16 v[32:35], v[176:179], v[202:205], v[32:35]
	v_mfma_f32_16x16x32_bf16 v[20:23], v[148:151], v[210:213], v[20:23]
	v_mfma_f32_16x16x32_bf16 v[16:19], v[176:179], v[210:213], v[16:19]
	v_mfma_f32_16x16x32_bf16 v[4:7], v[148:151], v[218:221], v[4:7]
	v_mfma_f32_16x16x32_bf16 v[0:3], v[176:179], v[218:221], v[0:3]
	s_setprio 0
	s_barrier
	s_add_i32 s84, 0, 0x18000
	s_add_i32 s85, 0, 0x1c000
	v_add_u32_e32 v140, s84, v186
	v_add_u32_e32 v176, s85, v186
	ds_read_b128 v[128:131], v140
	ds_read_b128 v[132:135], v140 offset:1024
	ds_read_b128 v[136:139], v140 offset:2048
	ds_read_b128 v[140:143], v140 offset:3072
	ds_read_b128 v[144:147], v176
	ds_read_b128 v[148:151], v176 offset:1024
	ds_read_b128 v[172:175], v176 offset:2048
	ds_read_b128 v[176:179], v176 offset:3072
	s_add_u32 s54, s60, 0xb0000
	s_addc_u32 s55, s61, 0
	s_mov_b32 m0, s68
	v_lshl_add_u64 v[230:231], s[54:55], 0, v[152:153]
	ds_read_b128 v[180:183], v191 offset:32768
	ds_read_b128 v[194:197], v191 offset:33792
	ds_read_b128 v[198:201], v191 offset:34816
	ds_read_b128 v[202:205], v191 offset:35840
	ds_read_b128 v[206:209], v191 offset:36864
	ds_read_b128 v[210:213], v191 offset:37888
	ds_read_b128 v[214:217], v191 offset:38912
	ds_read_b128 v[218:221], v191 offset:39936
	global_load_lds_dwordx4 v[230:231], off
	v_lshl_add_u64 v[230:231], s[54:55], 0, v[160:161]
	s_mov_b32 m0, s69
	s_nop 0
	global_load_lds_dwordx4 v[230:231], off
	s_waitcnt vmcnt(8)
	s_waitcnt lgkmcnt(0)
	s_barrier
	s_setprio 1
	s_waitcnt lgkmcnt(0)
	v_mfma_f32_16x16x32_bf16 v[124:127], v[128:131], v[180:183], v[124:127]
	v_mfma_f32_16x16x32_bf16 v[120:123], v[136:139], v[180:183], v[120:123]
	v_mfma_f32_16x16x32_bf16 v[108:111], v[128:131], v[198:201], v[108:111]
	v_mfma_f32_16x16x32_bf16 v[104:107], v[136:139], v[198:201], v[104:107]
	v_mfma_f32_16x16x32_bf16 v[92:95], v[128:131], v[206:209], v[92:95]
	v_mfma_f32_16x16x32_bf16 v[88:91], v[136:139], v[206:209], v[88:91]
	v_mfma_f32_16x16x32_bf16 v[76:79], v[128:131], v[214:217], v[76:79]
	v_mfma_f32_16x16x32_bf16 v[72:75], v[136:139], v[214:217], v[72:75]
	v_mfma_f32_16x16x32_bf16 v[124:127], v[132:135], v[194:197], v[124:127]
	v_mfma_f32_16x16x32_bf16 v[120:123], v[140:143], v[194:197], v[120:123]
	v_mfma_f32_16x16x32_bf16 v[108:111], v[132:135], v[202:205], v[108:111]
	v_mfma_f32_16x16x32_bf16 v[104:107], v[140:143], v[202:205], v[104:107]
	v_mfma_f32_16x16x32_bf16 v[92:95], v[132:135], v[210:213], v[92:95]
	v_mfma_f32_16x16x32_bf16 v[88:91], v[140:143], v[210:213], v[88:91]
	v_mfma_f32_16x16x32_bf16 v[76:79], v[132:135], v[218:221], v[76:79]
	v_mfma_f32_16x16x32_bf16 v[72:75], v[140:143], v[218:221], v[72:75]
	s_setprio 0
	s_setprio 1
	v_mfma_f32_16x16x32_bf16 v[116:119], v[144:147], v[180:183], v[116:119]
	v_mfma_f32_16x16x32_bf16 v[112:115], v[172:175], v[180:183], v[112:115]
	v_mfma_f32_16x16x32_bf16 v[100:103], v[144:147], v[198:201], v[100:103]
	v_mfma_f32_16x16x32_bf16 v[96:99], v[172:175], v[198:201], v[96:99]
	v_mfma_f32_16x16x32_bf16 v[84:87], v[144:147], v[206:209], v[84:87]
	v_mfma_f32_16x16x32_bf16 v[80:83], v[172:175], v[206:209], v[80:83]
	v_mfma_f32_16x16x32_bf16 v[68:71], v[144:147], v[214:217], v[68:71]
	v_mfma_f32_16x16x32_bf16 v[64:67], v[172:175], v[214:217], v[64:67]
	v_mfma_f32_16x16x32_bf16 v[116:119], v[148:151], v[194:197], v[116:119]
	v_mfma_f32_16x16x32_bf16 v[112:115], v[176:179], v[194:197], v[112:115]
	v_mfma_f32_16x16x32_bf16 v[100:103], v[148:151], v[202:205], v[100:103]
	v_mfma_f32_16x16x32_bf16 v[96:99], v[176:179], v[202:205], v[96:99]
	v_mfma_f32_16x16x32_bf16 v[84:87], v[148:151], v[210:213], v[84:87]
	v_mfma_f32_16x16x32_bf16 v[80:83], v[176:179], v[210:213], v[80:83]
	v_mfma_f32_16x16x32_bf16 v[68:71], v[148:151], v[218:221], v[68:71]
	v_mfma_f32_16x16x32_bf16 v[64:67], v[176:179], v[218:221], v[64:67]
	s_setprio 0
	s_barrier
	s_add_i32 s54, s84, s65
	v_lshl_add_u64 v[222:223], v[222:223], 0, s[28:29]
	s_mov_b32 m0, s54
	ds_read_b128 v[180:183], v191 offset:49152
	ds_read_b128 v[194:197], v191 offset:50176
	ds_read_b128 v[198:201], v191 offset:51200
	ds_read_b128 v[202:205], v191 offset:52224
	ds_read_b128 v[206:209], v191 offset:53248
	ds_read_b128 v[210:213], v191 offset:54272
	ds_read_b128 v[214:217], v191 offset:55296
	ds_read_b128 v[218:221], v191 offset:56320
	global_load_lds_dwordx4 v[222:223], off
	s_add_i32 m0, s54, 0x2000
	s_add_u32 s54, s58, 0xb0080
	v_lshl_add_u64 v[222:223], v[224:225], 0, s[28:29]
	s_addc_u32 s55, s59, 0
	s_add_i32 s58, s85, s65
	global_load_lds_dwordx4 v[222:223], off
	v_lshl_add_u64 v[222:223], s[54:55], 0, v[154:155]
	s_mov_b32 m0, s58
	s_nop 0
	global_load_lds_dwordx4 v[222:223], off
	v_lshl_add_u64 v[222:223], s[54:55], 0, v[162:163]
	s_add_i32 m0, s58, 0x2000
	s_nop 0
	global_load_lds_dwordx4 v[222:223], off
	v_lshl_add_u64 v[222:223], v[226:227], 0, s[28:29]
	s_mov_b32 m0, s3
	s_nop 0
	global_load_lds_dwordx4 v[222:223], off
	v_lshl_add_u64 v[222:223], v[228:229], 0, s[28:29]
	s_mov_b32 m0, s71
	s_nop 0
	global_load_lds_dwordx4 v[222:223], off
	s_waitcnt vmcnt(8)
	s_waitcnt lgkmcnt(0)
	s_barrier
	s_setprio 1
	s_waitcnt lgkmcnt(0)
	v_mfma_f32_16x16x32_bf16 v[60:63], v[128:131], v[180:183], v[60:63]
	v_mfma_f32_16x16x32_bf16 v[56:59], v[136:139], v[180:183], v[56:59]
	v_mfma_f32_16x16x32_bf16 v[44:47], v[128:131], v[198:201], v[44:47]
	v_mfma_f32_16x16x32_bf16 v[40:43], v[136:139], v[198:201], v[40:43]
	v_mfma_f32_16x16x32_bf16 v[28:31], v[128:131], v[206:209], v[28:31]
	v_mfma_f32_16x16x32_bf16 v[24:27], v[136:139], v[206:209], v[24:27]
	v_mfma_f32_16x16x32_bf16 v[12:15], v[128:131], v[214:217], v[12:15]
	v_mfma_f32_16x16x32_bf16 v[8:11], v[136:139], v[214:217], v[8:11]
	v_mfma_f32_16x16x32_bf16 v[60:63], v[132:135], v[194:197], v[60:63]
	v_mfma_f32_16x16x32_bf16 v[56:59], v[140:143], v[194:197], v[56:59]
	v_mfma_f32_16x16x32_bf16 v[44:47], v[132:135], v[202:205], v[44:47]
	v_mfma_f32_16x16x32_bf16 v[40:43], v[140:143], v[202:205], v[40:43]
	v_mfma_f32_16x16x32_bf16 v[28:31], v[132:135], v[210:213], v[28:31]
	v_mfma_f32_16x16x32_bf16 v[24:27], v[140:143], v[210:213], v[24:27]
	v_mfma_f32_16x16x32_bf16 v[12:15], v[132:135], v[218:221], v[12:15]
	v_mfma_f32_16x16x32_bf16 v[8:11], v[140:143], v[218:221], v[8:11]
	s_setprio 0
	s_setprio 1
	v_mfma_f32_16x16x32_bf16 v[52:55], v[144:147], v[180:183], v[52:55]
	v_mfma_f32_16x16x32_bf16 v[48:51], v[172:175], v[180:183], v[48:51]
	v_mfma_f32_16x16x32_bf16 v[36:39], v[144:147], v[198:201], v[36:39]
	v_mfma_f32_16x16x32_bf16 v[32:35], v[172:175], v[198:201], v[32:35]
	v_mfma_f32_16x16x32_bf16 v[20:23], v[144:147], v[206:209], v[20:23]
	v_mfma_f32_16x16x32_bf16 v[16:19], v[172:175], v[206:209], v[16:19]
	v_mfma_f32_16x16x32_bf16 v[4:7], v[144:147], v[214:217], v[4:7]
	v_mfma_f32_16x16x32_bf16 v[0:3], v[172:175], v[214:217], v[0:3]
	v_mfma_f32_16x16x32_bf16 v[52:55], v[148:151], v[194:197], v[52:55]
	v_mfma_f32_16x16x32_bf16 v[48:51], v[176:179], v[194:197], v[48:51]
	v_mfma_f32_16x16x32_bf16 v[36:39], v[148:151], v[202:205], v[36:39]
	v_mfma_f32_16x16x32_bf16 v[32:35], v[176:179], v[202:205], v[32:35]
	v_mfma_f32_16x16x32_bf16 v[20:23], v[148:151], v[210:213], v[20:23]
	v_mfma_f32_16x16x32_bf16 v[16:19], v[176:179], v[210:213], v[16:19]
	v_mfma_f32_16x16x32_bf16 v[4:7], v[148:151], v[218:221], v[4:7]
	v_mfma_f32_16x16x32_bf16 v[0:3], v[176:179], v[218:221], v[0:3]
	s_setprio 0
	s_barrier
	s_add_i32 s83, s83, 2
	s_add_u32 s81, s81, 0x100
	s_addc_u32 s82, s82, 0
	s_cmp_gt_u32 s83, 41
	s_mov_b64 s[54:55], s[56:57]

.LBB0_254:
	s_ashr_i32 s61, s60, 31
	s_lshl_b64 s[62:63], s[60:61], 19
	s_add_u32 s62, s35, s62
	s_addc_u32 s63, s47, s63
	s_and_b64 s[64:65], s[12:13], exec
	s_cselect_b32 s3, s63, s69
	s_cselect_b32 s61, s62, s68
	s_ashr_i32 s59, s58, 31
	s_lshl_b64 s[64:65], s[58:59], 19
	s_add_u32 s64, s49, s64
	s_addc_u32 s65, s70, s65
	s_and_b64 s[92:93], s[12:13], exec
	s_cselect_b32 s91, s65, s67
	s_cselect_b32 s92, s64, s66
	s_lshl_b32 s59, s14, 8
	v_add_u32_e32 v0, s59, v182
	s_add_u32 s93, s66, 0x100
	s_waitcnt lgkmcnt(0)
	v_ashrrev_i32_e32 v1, 31, v0
	s_addc_u32 s94, s67, 0
	v_lshl_add_u64 v[72:73], v[0:1], 4, s[26:27]
	s_add_u32 s14, s68, 0x40080
	s_addc_u32 s15, s69, 0
	s_mov_b32 s95, -2
	s_mov_b64 s[66:67], 0
	v_add_u32_e32 v74, s83, v181
	ds_read_b128 v[88:91], v74
	ds_read_b128 v[108:111], v74 offset:1024
	ds_read_b128 v[128:131], v74 offset:2048
	ds_read_b128 v[144:147], v74 offset:3072
	v_add_u32_e32 v74, s84, v181
	ds_read_b128 v[148:151], v74
	ds_read_b128 v[152:155], v74 offset:1024
	ds_read_b128 v[176:179], v74 offset:2048
	ds_read_b128 v[190:193], v74 offset:3072
	s_add_u32 s68, s14, 0xfffc0080
	s_addc_u32 s69, s15, -1
	s_and_b64 s[66:67], s[66:67], exec
	s_cselect_b32 s69, s3, s69
	s_cselect_b32 s68, s61, s68
	s_cselect_b32 s67, s91, s94
	s_cselect_b32 s66, s92, s93
	v_lshl_add_u64 v[74:75], s[14:15], 0, v[170:171]
	s_add_i32 m0, s74, 0xc000
	ds_read_b128 v[194:197], v187
	ds_read_b128 v[198:201], v187 offset:1024
	ds_read_b128 v[202:205], v187 offset:2048
	ds_read_b128 v[206:209], v187 offset:3072
	ds_read_b128 v[210:213], v187 offset:4096
	ds_read_b128 v[214:217], v187 offset:5120
	ds_read_b128 v[218:221], v187 offset:6144
	ds_read_b128 v[222:225], v187 offset:7168
	global_load_lds_dwordx4 v[74:75], off
	v_lshl_add_u64 v[74:75], s[14:15], 0, v[168:169]
	s_add_i32 m0, s74, 0xe000
	s_nop 0
	global_load_lds_dwordx4 v[74:75], off
	s_waitcnt vmcnt(8)
	s_waitcnt lgkmcnt(0)
	s_barrier
	s_setprio 1
	s_waitcnt lgkmcnt(0)
	v_mfma_f32_16x16x32_bf16 v[140:143], v[88:91], v[194:197], 0
	v_mfma_f32_16x16x32_bf16 v[136:139], v[128:131], v[194:197], 0
	v_mfma_f32_16x16x32_bf16 v[120:123], v[88:91], v[202:205], 0
	v_mfma_f32_16x16x32_bf16 v[116:119], v[128:131], v[202:205], 0
	v_mfma_f32_16x16x32_bf16 v[100:103], v[88:91], v[210:213], 0
	v_mfma_f32_16x16x32_bf16 v[96:99], v[128:131], v[210:213], 0
	v_mfma_f32_16x16x32_bf16 v[80:83], v[88:91], v[218:221], 0
	v_mfma_f32_16x16x32_bf16 v[74:77], v[128:131], v[218:221], 0
	v_mfma_f32_16x16x32_bf16 v[140:143], v[108:111], v[198:201], v[140:143]
	v_mfma_f32_16x16x32_bf16 v[136:139], v[144:147], v[198:201], v[136:139]
	v_mfma_f32_16x16x32_bf16 v[120:123], v[108:111], v[206:209], v[120:123]
	v_mfma_f32_16x16x32_bf16 v[116:119], v[144:147], v[206:209], v[116:119]
	v_mfma_f32_16x16x32_bf16 v[100:103], v[108:111], v[214:217], v[100:103]
	v_mfma_f32_16x16x32_bf16 v[96:99], v[144:147], v[214:217], v[96:99]
	v_mfma_f32_16x16x32_bf16 v[80:83], v[108:111], v[222:225], v[80:83]
	v_mfma_f32_16x16x32_bf16 v[74:77], v[144:147], v[222:225], v[74:77]
	s_setprio 0
	s_setprio 1
	v_mfma_f32_16x16x32_bf16 v[132:135], v[148:151], v[194:197], 0
	v_mfma_f32_16x16x32_bf16 v[124:127], v[176:179], v[194:197], 0
	v_mfma_f32_16x16x32_bf16 v[112:115], v[148:151], v[202:205], 0
	v_mfma_f32_16x16x32_bf16 v[104:107], v[176:179], v[202:205], 0
	v_mfma_f32_16x16x32_bf16 v[92:95], v[148:151], v[210:213], 0
	v_mfma_f32_16x16x32_bf16 v[84:87], v[176:179], v[210:213], 0
	v_mfma_f32_16x16x32_bf16 v[68:71], v[148:151], v[218:221], 0
	v_mfma_f32_16x16x32_bf16 v[64:67], v[176:179], v[218:221], 0
	v_mfma_f32_16x16x32_bf16 v[132:135], v[152:155], v[198:201], v[132:135]
	v_mfma_f32_16x16x32_bf16 v[124:127], v[190:193], v[198:201], v[124:127]
	v_mfma_f32_16x16x32_bf16 v[112:115], v[152:155], v[206:209], v[112:115]
	v_mfma_f32_16x16x32_bf16 v[104:107], v[190:193], v[206:209], v[104:107]
	v_mfma_f32_16x16x32_bf16 v[92:95], v[152:155], v[214:217], v[92:95]
	v_mfma_f32_16x16x32_bf16 v[84:87], v[190:193], v[214:217], v[84:87]
	v_mfma_f32_16x16x32_bf16 v[68:71], v[152:155], v[222:225], v[68:71]
	v_mfma_f32_16x16x32_bf16 v[64:67], v[190:193], v[222:225], v[64:67]
	s_setprio 0
	s_barrier
	s_add_i32 s96, s83, s71
	v_lshl_add_u64 v[226:227], s[66:67], 0, v[162:163]
	s_mov_b32 m0, s96
	ds_read_b128 v[194:197], v187 offset:16384
	ds_read_b128 v[198:201], v187 offset:17408
	ds_read_b128 v[202:205], v187 offset:18432
	ds_read_b128 v[206:209], v187 offset:19456
	ds_read_b128 v[210:213], v187 offset:20480
	ds_read_b128 v[214:217], v187 offset:21504
	ds_read_b128 v[218:221], v187 offset:22528
	ds_read_b128 v[222:225], v187 offset:23552
	global_load_lds_dwordx4 v[226:227], off
	s_add_i32 m0, s96, 0x2000
	s_add_u32 s96, s66, 0x40000
	v_lshl_add_u64 v[228:229], s[66:67], 0, v[166:167]
	s_addc_u32 s97, s67, 0
	s_add_i32 vcc_lo, s84, s71
	global_load_lds_dwordx4 v[228:229], off
	v_lshl_add_u64 v[78:79], s[96:97], 0, v[162:163]
	s_mov_b32 m0, vcc_lo
	v_lshl_add_u64 v[230:231], s[68:69], 0, v[160:161]
	global_load_lds_dwordx4 v[78:79], off
	v_lshl_add_u64 v[78:79], s[96:97], 0, v[166:167]
	s_add_i32 m0, vcc_lo, 0x2000
	v_lshl_add_u64 v[232:233], s[68:69], 0, v[164:165]
	global_load_lds_dwordx4 v[78:79], off
	s_mov_b32 m0, s74
	s_nop 0
	global_load_lds_dwordx4 v[230:231], off
	s_mov_b32 m0, s75
	s_nop 0
	global_load_lds_dwordx4 v[232:233], off
	s_waitcnt vmcnt(8)
	s_waitcnt lgkmcnt(0)
	s_barrier
	s_setprio 1
	s_waitcnt lgkmcnt(0)
	v_mfma_f32_16x16x32_bf16 v[60:63], v[88:91], v[194:197], 0
	v_mfma_f32_16x16x32_bf16 v[56:59], v[128:131], v[194:197], 0
	v_mfma_f32_16x16x32_bf16 v[44:47], v[88:91], v[202:205], 0
	v_mfma_f32_16x16x32_bf16 v[40:43], v[128:131], v[202:205], 0
	v_mfma_f32_16x16x32_bf16 v[28:31], v[88:91], v[210:213], 0
	v_mfma_f32_16x16x32_bf16 v[24:27], v[128:131], v[210:213], 0
	v_mfma_f32_16x16x32_bf16 v[12:15], v[88:91], v[218:221], 0
	v_mfma_f32_16x16x32_bf16 v[8:11], v[128:131], v[218:221], 0
	v_mfma_f32_16x16x32_bf16 v[60:63], v[108:111], v[198:201], v[60:63]
	v_mfma_f32_16x16x32_bf16 v[56:59], v[144:147], v[198:201], v[56:59]
	v_mfma_f32_16x16x32_bf16 v[44:47], v[108:111], v[206:209], v[44:47]
	v_mfma_f32_16x16x32_bf16 v[40:43], v[144:147], v[206:209], v[40:43]
	v_mfma_f32_16x16x32_bf16 v[28:31], v[108:111], v[214:217], v[28:31]
	v_mfma_f32_16x16x32_bf16 v[24:27], v[144:147], v[214:217], v[24:27]
	v_mfma_f32_16x16x32_bf16 v[12:15], v[108:111], v[222:225], v[12:15]
	v_mfma_f32_16x16x32_bf16 v[8:11], v[144:147], v[222:225], v[8:11]
	s_setprio 0
	s_setprio 1
	v_mfma_f32_16x16x32_bf16 v[52:55], v[148:151], v[194:197], 0
	v_mfma_f32_16x16x32_bf16 v[48:51], v[176:179], v[194:197], 0
	v_mfma_f32_16x16x32_bf16 v[36:39], v[148:151], v[202:205], 0
	v_mfma_f32_16x16x32_bf16 v[32:35], v[176:179], v[202:205], 0
	v_mfma_f32_16x16x32_bf16 v[20:23], v[148:151], v[210:213], 0
	v_mfma_f32_16x16x32_bf16 v[16:19], v[176:179], v[210:213], 0
	v_mfma_f32_16x16x32_bf16 v[4:7], v[148:151], v[218:221], 0
	v_mfma_f32_16x16x32_bf16 v[0:3], v[176:179], v[218:221], 0
	v_mfma_f32_16x16x32_bf16 v[52:55], v[152:155], v[198:201], v[52:55]
	v_mfma_f32_16x16x32_bf16 v[48:51], v[190:193], v[198:201], v[48:51]
	v_mfma_f32_16x16x32_bf16 v[36:39], v[152:155], v[206:209], v[36:39]
	v_mfma_f32_16x16x32_bf16 v[32:35], v[190:193], v[206:209], v[32:35]
	v_mfma_f32_16x16x32_bf16 v[20:23], v[152:155], v[214:217], v[20:23]
	v_mfma_f32_16x16x32_bf16 v[16:19], v[190:193], v[214:217], v[16:19]
	v_mfma_f32_16x16x32_bf16 v[4:7], v[152:155], v[222:225], v[4:7]
	v_mfma_f32_16x16x32_bf16 v[0:3], v[190:193], v[222:225], v[0:3]
	s_setprio 0
	s_barrier
	s_add_i32 s96, 0, 0x18000
	v_add_u32_e32 v78, s96, v181
	s_add_i32 s97, 0, 0x1c000
	ds_read_b128 v[88:91], v78
	ds_read_b128 v[108:111], v78 offset:1024
	ds_read_b128 v[128:131], v78 offset:2048
	ds_read_b128 v[144:147], v78 offset:3072
	v_add_u32_e32 v78, s97, v181
	ds_read_b128 v[148:151], v78
	ds_read_b128 v[152:155], v78 offset:1024
	ds_read_b128 v[176:179], v78 offset:2048
	ds_read_b128 v[190:193], v78 offset:3072
	s_add_u32 s68, s68, 0x40000
	s_addc_u32 s69, s69, 0
	s_mov_b32 m0, s76
	v_lshl_add_u64 v[78:79], s[68:69], 0, v[160:161]
	ds_read_b128 v[194:197], v187 offset:32768
	ds_read_b128 v[198:201], v187 offset:33792
	ds_read_b128 v[202:205], v187 offset:34816
	ds_read_b128 v[206:209], v187 offset:35840
	ds_read_b128 v[210:213], v187 offset:36864
	ds_read_b128 v[214:217], v187 offset:37888
	ds_read_b128 v[218:221], v187 offset:38912
	ds_read_b128 v[222:225], v187 offset:39936
	global_load_lds_dwordx4 v[78:79], off
	v_lshl_add_u64 v[78:79], s[68:69], 0, v[164:165]
	s_mov_b32 m0, s77
	s_nop 0
	global_load_lds_dwordx4 v[78:79], off
	s_waitcnt vmcnt(8)
	s_waitcnt lgkmcnt(0)
	s_barrier
	s_setprio 1
	s_waitcnt lgkmcnt(0)
	v_mfma_f32_16x16x32_bf16 v[140:143], v[88:91], v[194:197], v[140:143]
	v_mfma_f32_16x16x32_bf16 v[136:139], v[128:131], v[194:197], v[136:139]
	v_mfma_f32_16x16x32_bf16 v[120:123], v[88:91], v[202:205], v[120:123]
	v_mfma_f32_16x16x32_bf16 v[116:119], v[128:131], v[202:205], v[116:119]
	v_mfma_f32_16x16x32_bf16 v[100:103], v[88:91], v[210:213], v[100:103]
	v_mfma_f32_16x16x32_bf16 v[96:99], v[128:131], v[210:213], v[96:99]
	v_mfma_f32_16x16x32_bf16 v[78:81], v[88:91], v[218:221], v[80:83]
	v_mfma_f32_16x16x32_bf16 v[74:77], v[128:131], v[218:221], v[74:77]
	v_mfma_f32_16x16x32_bf16 v[140:143], v[108:111], v[198:201], v[140:143]
	v_mfma_f32_16x16x32_bf16 v[136:139], v[144:147], v[198:201], v[136:139]
	v_mfma_f32_16x16x32_bf16 v[120:123], v[108:111], v[206:209], v[120:123]
	v_mfma_f32_16x16x32_bf16 v[116:119], v[144:147], v[206:209], v[116:119]
	v_mfma_f32_16x16x32_bf16 v[100:103], v[108:111], v[214:217], v[100:103]
	v_mfma_f32_16x16x32_bf16 v[96:99], v[144:147], v[214:217], v[96:99]
	v_mfma_f32_16x16x32_bf16 v[80:83], v[108:111], v[222:225], v[78:81]
	v_mfma_f32_16x16x32_bf16 v[76:79], v[144:147], v[222:225], v[74:77]
	s_setprio 0
	s_setprio 1
	v_mfma_f32_16x16x32_bf16 v[132:135], v[148:151], v[194:197], v[132:135]
	v_mfma_f32_16x16x32_bf16 v[124:127], v[176:179], v[194:197], v[124:127]
	v_mfma_f32_16x16x32_bf16 v[112:115], v[148:151], v[202:205], v[112:115]
	v_mfma_f32_16x16x32_bf16 v[104:107], v[176:179], v[202:205], v[104:107]
	v_mfma_f32_16x16x32_bf16 v[92:95], v[148:151], v[210:213], v[92:95]
	v_mfma_f32_16x16x32_bf16 v[84:87], v[176:179], v[210:213], v[84:87]
	v_mfma_f32_16x16x32_bf16 v[68:71], v[148:151], v[218:221], v[68:71]
	v_mfma_f32_16x16x32_bf16 v[64:67], v[176:179], v[218:221], v[64:67]
	v_mfma_f32_16x16x32_bf16 v[132:135], v[152:155], v[198:201], v[132:135]
	v_mfma_f32_16x16x32_bf16 v[124:127], v[190:193], v[198:201], v[124:127]
	v_mfma_f32_16x16x32_bf16 v[112:115], v[152:155], v[206:209], v[112:115]
	v_mfma_f32_16x16x32_bf16 v[104:107], v[190:193], v[206:209], v[104:107]
	v_mfma_f32_16x16x32_bf16 v[92:95], v[152:155], v[214:217], v[92:95]
	v_mfma_f32_16x16x32_bf16 v[84:87], v[190:193], v[214:217], v[84:87]
	v_mfma_f32_16x16x32_bf16 v[68:71], v[152:155], v[222:225], v[68:71]
	v_mfma_f32_16x16x32_bf16 v[64:67], v[190:193], v[222:225], v[64:67]
	s_setprio 0
	s_barrier
	s_add_i32 s68, s96, s71
	v_lshl_add_u64 v[74:75], v[226:227], 0, s[28:29]
	s_mov_b32 m0, s68
	ds_read_b128 v[194:197], v187 offset:49152
	ds_read_b128 v[198:201], v187 offset:50176
	ds_read_b128 v[202:205], v187 offset:51200
	ds_read_b128 v[206:209], v187 offset:52224
	ds_read_b128 v[210:213], v187 offset:53248
	ds_read_b128 v[214:217], v187 offset:54272
	ds_read_b128 v[218:221], v187 offset:55296
	ds_read_b128 v[222:225], v187 offset:56320
	global_load_lds_dwordx4 v[74:75], off
	s_add_i32 m0, s68, 0x2000
	s_add_u32 s66, s66, 0x40080
	v_lshl_add_u64 v[74:75], v[228:229], 0, s[28:29]
	s_addc_u32 s67, s67, 0
	s_add_i32 s68, s97, s71
	global_load_lds_dwordx4 v[74:75], off
	v_lshl_add_u64 v[74:75], s[66:67], 0, v[162:163]
	s_mov_b32 m0, s68
	s_nop 0
	global_load_lds_dwordx4 v[74:75], off
	v_lshl_add_u64 v[74:75], s[66:67], 0, v[166:167]
	s_add_i32 m0, s68, 0x2000
	s_nop 0
	global_load_lds_dwordx4 v[74:75], off
	v_lshl_add_u64 v[74:75], v[230:231], 0, s[28:29]
	s_mov_b32 m0, s78
	s_nop 0
	global_load_lds_dwordx4 v[74:75], off
	v_lshl_add_u64 v[74:75], v[232:233], 0, s[28:29]
	s_mov_b32 m0, s79
	s_nop 0
	global_load_lds_dwordx4 v[74:75], off
	s_waitcnt vmcnt(8)
	s_waitcnt lgkmcnt(0)
	s_barrier
	s_setprio 1
	s_waitcnt lgkmcnt(0)
	v_mfma_f32_16x16x32_bf16 v[60:63], v[88:91], v[194:197], v[60:63]
	v_mfma_f32_16x16x32_bf16 v[56:59], v[128:131], v[194:197], v[56:59]
	v_mfma_f32_16x16x32_bf16 v[44:47], v[88:91], v[202:205], v[44:47]
	v_mfma_f32_16x16x32_bf16 v[40:43], v[128:131], v[202:205], v[40:43]
	v_mfma_f32_16x16x32_bf16 v[28:31], v[88:91], v[210:213], v[28:31]
	v_mfma_f32_16x16x32_bf16 v[24:27], v[128:131], v[210:213], v[24:27]
	v_mfma_f32_16x16x32_bf16 v[12:15], v[88:91], v[218:221], v[12:15]
	v_mfma_f32_16x16x32_bf16 v[8:11], v[128:131], v[218:221], v[8:11]
	v_mfma_f32_16x16x32_bf16 v[60:63], v[108:111], v[198:201], v[60:63]
	v_mfma_f32_16x16x32_bf16 v[56:59], v[144:147], v[198:201], v[56:59]
	v_mfma_f32_16x16x32_bf16 v[44:47], v[108:111], v[206:209], v[44:47]
	v_mfma_f32_16x16x32_bf16 v[40:43], v[144:147], v[206:209], v[40:43]
	v_mfma_f32_16x16x32_bf16 v[28:31], v[108:111], v[214:217], v[28:31]
	v_mfma_f32_16x16x32_bf16 v[24:27], v[144:147], v[214:217], v[24:27]
	v_mfma_f32_16x16x32_bf16 v[12:15], v[108:111], v[222:225], v[12:15]
	v_mfma_f32_16x16x32_bf16 v[8:11], v[144:147], v[222:225], v[8:11]
	s_setprio 0
	s_setprio 1
	v_mfma_f32_16x16x32_bf16 v[52:55], v[148:151], v[194:197], v[52:55]
	v_mfma_f32_16x16x32_bf16 v[48:51], v[176:179], v[194:197], v[48:51]
	v_mfma_f32_16x16x32_bf16 v[36:39], v[148:151], v[202:205], v[36:39]
	v_mfma_f32_16x16x32_bf16 v[32:35], v[176:179], v[202:205], v[32:35]
	v_mfma_f32_16x16x32_bf16 v[20:23], v[148:151], v[210:213], v[20:23]
	v_mfma_f32_16x16x32_bf16 v[16:19], v[176:179], v[210:213], v[16:19]
	v_mfma_f32_16x16x32_bf16 v[4:7], v[148:151], v[218:221], v[4:7]
	v_mfma_f32_16x16x32_bf16 v[0:3], v[176:179], v[218:221], v[0:3]
	v_mfma_f32_16x16x32_bf16 v[52:55], v[152:155], v[198:201], v[52:55]
	v_mfma_f32_16x16x32_bf16 v[48:51], v[190:193], v[198:201], v[48:51]
	v_mfma_f32_16x16x32_bf16 v[36:39], v[152:155], v[206:209], v[36:39]
	v_mfma_f32_16x16x32_bf16 v[32:35], v[190:193], v[206:209], v[32:35]
	v_mfma_f32_16x16x32_bf16 v[20:23], v[152:155], v[214:217], v[20:23]
	v_mfma_f32_16x16x32_bf16 v[16:19], v[190:193], v[214:217], v[16:19]
	v_mfma_f32_16x16x32_bf16 v[4:7], v[152:155], v[222:225], v[4:7]
	v_mfma_f32_16x16x32_bf16 v[0:3], v[190:193], v[222:225], v[0:3]
	s_setprio 0
	s_barrier
	s_add_i32 s95, s95, 2
	s_add_u32 s93, s93, 0x100
	s_addc_u32 s94, s94, 0
	s_add_u32 s14, s14, 0x100
	s_addc_u32 s15, s15, 0
	s_branch .LBB0_256

.LBB0_439:
	s_ashr_i32 s53, s52, 31
	s_lshl_b64 s[54:55], s[52:53], 20
	s_add_u32 s54, s35, s54
	s_addc_u32 s55, s66, s55
	s_and_b64 s[56:57], s[12:13], exec
	s_cselect_b32 s15, s55, s63
	s_cselect_b32 s53, s54, s62
	s_ashr_i32 s51, s50, 31
	s_lshl_b64 s[56:57], s[50:51], 20
	s_add_u32 s56, s67, s56
	s_addc_u32 s57, s68, s57
	s_and_b64 s[64:65], s[12:13], exec
	s_cselect_b32 s51, s57, s61
	s_cselect_b32 s59, s56, s60
	s_add_u32 s81, s60, 0x100
	s_addc_u32 s82, s61, 0
	s_add_u32 s60, s62, 0x80080
	s_addc_u32 s61, s63, 0
	s_mov_b32 s83, -2
	s_waitcnt lgkmcnt(0)
	ds_read_b128 v[128:131], v189
	ds_read_b128 v[132:135], v189 offset:1024
	ds_read_b128 v[136:139], v189 offset:2048
	ds_read_b128 v[140:143], v189 offset:3072
	ds_read_b128 v[144:147], v190
	ds_read_b128 v[148:151], v190 offset:1024
	ds_read_b128 v[172:175], v190 offset:2048
	ds_read_b128 v[176:179], v190 offset:3072
	s_add_u32 s62, s60, 0xfff80080
	s_addc_u32 s63, s61, -1
	s_cmp_eq_u32 s83, 28
	s_cselect_b32 s65, s15, s63
	s_cselect_b32 s64, s53, s62
	s_cselect_b32 s63, s51, s82
	s_cselect_b32 s62, s59, s81
	v_lshl_add_u64 v[222:223], s[60:61], 0, v[166:167]
	s_add_i32 m0, s70, 0xc000
	ds_read_b128 v[180:183], v191
	ds_read_b128 v[194:197], v191 offset:1024
	ds_read_b128 v[198:201], v191 offset:2048
	ds_read_b128 v[202:205], v191 offset:3072
	ds_read_b128 v[206:209], v191 offset:4096
	ds_read_b128 v[210:213], v191 offset:5120
	ds_read_b128 v[214:217], v191 offset:6144
	ds_read_b128 v[218:221], v191 offset:7168
	global_load_lds_dwordx4 v[222:223], off
	v_lshl_add_u64 v[222:223], s[60:61], 0, v[164:165]
	s_add_i32 m0, s70, 0xe000
	s_nop 0
	global_load_lds_dwordx4 v[222:223], off
	s_waitcnt vmcnt(8)
	s_waitcnt lgkmcnt(0)
	s_barrier
	s_setprio 1
	s_waitcnt lgkmcnt(0)
	v_mfma_f32_16x16x32_bf16 v[124:127], v[128:131], v[180:183], 0
	v_mfma_f32_16x16x32_bf16 v[120:123], v[136:139], v[180:183], 0
	v_mfma_f32_16x16x32_bf16 v[108:111], v[128:131], v[198:201], 0
	v_mfma_f32_16x16x32_bf16 v[104:107], v[136:139], v[198:201], 0
	v_mfma_f32_16x16x32_bf16 v[92:95], v[128:131], v[206:209], 0
	v_mfma_f32_16x16x32_bf16 v[88:91], v[136:139], v[206:209], 0
	v_mfma_f32_16x16x32_bf16 v[76:79], v[128:131], v[214:217], 0
	v_mfma_f32_16x16x32_bf16 v[72:75], v[136:139], v[214:217], 0
	v_mfma_f32_16x16x32_bf16 v[124:127], v[132:135], v[194:197], v[124:127]
	v_mfma_f32_16x16x32_bf16 v[120:123], v[140:143], v[194:197], v[120:123]
	v_mfma_f32_16x16x32_bf16 v[108:111], v[132:135], v[202:205], v[108:111]
	v_mfma_f32_16x16x32_bf16 v[104:107], v[140:143], v[202:205], v[104:107]
	v_mfma_f32_16x16x32_bf16 v[92:95], v[132:135], v[210:213], v[92:95]
	v_mfma_f32_16x16x32_bf16 v[88:91], v[140:143], v[210:213], v[88:91]
	v_mfma_f32_16x16x32_bf16 v[76:79], v[132:135], v[218:221], v[76:79]
	v_mfma_f32_16x16x32_bf16 v[72:75], v[140:143], v[218:221], v[72:75]
	s_setprio 0
	s_setprio 1
	v_mfma_f32_16x16x32_bf16 v[116:119], v[144:147], v[180:183], 0
	v_mfma_f32_16x16x32_bf16 v[112:115], v[172:175], v[180:183], 0
	v_mfma_f32_16x16x32_bf16 v[100:103], v[144:147], v[198:201], 0
	v_mfma_f32_16x16x32_bf16 v[96:99], v[172:175], v[198:201], 0
	v_mfma_f32_16x16x32_bf16 v[84:87], v[144:147], v[206:209], 0
	v_mfma_f32_16x16x32_bf16 v[80:83], v[172:175], v[206:209], 0
	v_mfma_f32_16x16x32_bf16 v[68:71], v[144:147], v[214:217], 0
	v_mfma_f32_16x16x32_bf16 v[64:67], v[172:175], v[214:217], 0
	v_mfma_f32_16x16x32_bf16 v[116:119], v[148:151], v[194:197], v[116:119]
	v_mfma_f32_16x16x32_bf16 v[112:115], v[176:179], v[194:197], v[112:115]
	v_mfma_f32_16x16x32_bf16 v[100:103], v[148:151], v[202:205], v[100:103]
	v_mfma_f32_16x16x32_bf16 v[96:99], v[176:179], v[202:205], v[96:99]
	v_mfma_f32_16x16x32_bf16 v[84:87], v[148:151], v[210:213], v[84:87]
	v_mfma_f32_16x16x32_bf16 v[80:83], v[176:179], v[210:213], v[80:83]
	v_mfma_f32_16x16x32_bf16 v[68:71], v[148:151], v[218:221], v[68:71]
	v_mfma_f32_16x16x32_bf16 v[64:67], v[176:179], v[218:221], v[64:67]
	s_setprio 0
	s_barrier
	s_add_i32 s84, s79, s69
	v_lshl_add_u64 v[222:223], s[62:63], 0, v[154:155]
	s_mov_b32 m0, s84
	ds_read_b128 v[180:183], v191 offset:16384
	ds_read_b128 v[194:197], v191 offset:17408
	ds_read_b128 v[198:201], v191 offset:18432
	ds_read_b128 v[202:205], v191 offset:19456
	ds_read_b128 v[206:209], v191 offset:20480
	ds_read_b128 v[210:213], v191 offset:21504
	ds_read_b128 v[214:217], v191 offset:22528
	ds_read_b128 v[218:221], v191 offset:23552
	global_load_lds_dwordx4 v[222:223], off
	s_add_i32 m0, s84, 0x2000
	s_add_u32 s84, s62, 0x80000
	v_lshl_add_u64 v[224:225], s[62:63], 0, v[162:163]
	s_addc_u32 s85, s63, 0
	s_add_i32 s86, s80, s69
	global_load_lds_dwordx4 v[224:225], off
	v_lshl_add_u64 v[226:227], s[84:85], 0, v[154:155]
	s_mov_b32 m0, s86
	v_lshl_add_u64 v[228:229], s[64:65], 0, v[160:161]
	global_load_lds_dwordx4 v[226:227], off
	v_lshl_add_u64 v[226:227], s[84:85], 0, v[162:163]
	s_add_i32 m0, s86, 0x2000
	s_nop 0
	global_load_lds_dwordx4 v[226:227], off
	v_lshl_add_u64 v[226:227], s[64:65], 0, v[152:153]
	s_mov_b32 m0, s70
	s_nop 0
	global_load_lds_dwordx4 v[226:227], off
	s_mov_b32 m0, s71
	s_nop 0
	global_load_lds_dwordx4 v[228:229], off
	s_waitcnt vmcnt(8)
	s_waitcnt lgkmcnt(0)
	s_barrier
	s_setprio 1
	s_waitcnt lgkmcnt(0)
	v_mfma_f32_16x16x32_bf16 v[60:63], v[128:131], v[180:183], 0
	v_mfma_f32_16x16x32_bf16 v[56:59], v[136:139], v[180:183], 0
	v_mfma_f32_16x16x32_bf16 v[44:47], v[128:131], v[198:201], 0
	v_mfma_f32_16x16x32_bf16 v[40:43], v[136:139], v[198:201], 0
	v_mfma_f32_16x16x32_bf16 v[28:31], v[128:131], v[206:209], 0
	v_mfma_f32_16x16x32_bf16 v[24:27], v[136:139], v[206:209], 0
	v_mfma_f32_16x16x32_bf16 v[12:15], v[128:131], v[214:217], 0
	v_mfma_f32_16x16x32_bf16 v[8:11], v[136:139], v[214:217], 0
	v_mfma_f32_16x16x32_bf16 v[60:63], v[132:135], v[194:197], v[60:63]
	v_mfma_f32_16x16x32_bf16 v[56:59], v[140:143], v[194:197], v[56:59]
	v_mfma_f32_16x16x32_bf16 v[44:47], v[132:135], v[202:205], v[44:47]
	v_mfma_f32_16x16x32_bf16 v[40:43], v[140:143], v[202:205], v[40:43]
	v_mfma_f32_16x16x32_bf16 v[28:31], v[132:135], v[210:213], v[28:31]
	v_mfma_f32_16x16x32_bf16 v[24:27], v[140:143], v[210:213], v[24:27]
	v_mfma_f32_16x16x32_bf16 v[12:15], v[132:135], v[218:221], v[12:15]
	v_mfma_f32_16x16x32_bf16 v[8:11], v[140:143], v[218:221], v[8:11]
	s_setprio 0
	s_setprio 1
	v_mfma_f32_16x16x32_bf16 v[52:55], v[144:147], v[180:183], 0
	v_mfma_f32_16x16x32_bf16 v[48:51], v[172:175], v[180:183], 0
	v_mfma_f32_16x16x32_bf16 v[36:39], v[144:147], v[198:201], 0
	v_mfma_f32_16x16x32_bf16 v[32:35], v[172:175], v[198:201], 0
	v_mfma_f32_16x16x32_bf16 v[20:23], v[144:147], v[206:209], 0
	v_mfma_f32_16x16x32_bf16 v[16:19], v[172:175], v[206:209], 0
	v_mfma_f32_16x16x32_bf16 v[4:7], v[144:147], v[214:217], 0
	v_mfma_f32_16x16x32_bf16 v[0:3], v[172:175], v[214:217], 0
	v_mfma_f32_16x16x32_bf16 v[52:55], v[148:151], v[194:197], v[52:55]
	v_mfma_f32_16x16x32_bf16 v[48:51], v[176:179], v[194:197], v[48:51]
	v_mfma_f32_16x16x32_bf16 v[36:39], v[148:151], v[202:205], v[36:39]
	v_mfma_f32_16x16x32_bf16 v[32:35], v[176:179], v[202:205], v[32:35]
	v_mfma_f32_16x16x32_bf16 v[20:23], v[148:151], v[210:213], v[20:23]
	v_mfma_f32_16x16x32_bf16 v[16:19], v[176:179], v[210:213], v[16:19]
	v_mfma_f32_16x16x32_bf16 v[4:7], v[148:151], v[218:221], v[4:7]
	v_mfma_f32_16x16x32_bf16 v[0:3], v[176:179], v[218:221], v[0:3]
	s_setprio 0
	s_barrier
	s_add_i32 s84, 0, 0x18000
	s_add_i32 s85, 0, 0x1c000
	v_add_u32_e32 v140, s84, v186
	v_add_u32_e32 v176, s85, v186
	ds_read_b128 v[128:131], v140
	ds_read_b128 v[132:135], v140 offset:1024
	ds_read_b128 v[136:139], v140 offset:2048
	ds_read_b128 v[140:143], v140 offset:3072
	ds_read_b128 v[144:147], v176
	ds_read_b128 v[148:151], v176 offset:1024
	ds_read_b128 v[172:175], v176 offset:2048
	ds_read_b128 v[176:179], v176 offset:3072
	s_add_u32 s64, s64, 0x80000
	s_addc_u32 s65, s65, 0
	s_mov_b32 m0, s72
	v_lshl_add_u64 v[230:231], s[64:65], 0, v[152:153]
	ds_read_b128 v[180:183], v191 offset:32768
	ds_read_b128 v[194:197], v191 offset:33792
	ds_read_b128 v[198:201], v191 offset:34816
	ds_read_b128 v[202:205], v191 offset:35840
	ds_read_b128 v[206:209], v191 offset:36864
	ds_read_b128 v[210:213], v191 offset:37888
	ds_read_b128 v[214:217], v191 offset:38912
	ds_read_b128 v[218:221], v191 offset:39936
	global_load_lds_dwordx4 v[230:231], off
	v_lshl_add_u64 v[230:231], s[64:65], 0, v[160:161]
	s_mov_b32 m0, s73
	s_nop 0
	global_load_lds_dwordx4 v[230:231], off
	s_waitcnt vmcnt(8)
	s_waitcnt lgkmcnt(0)
	s_barrier
	s_setprio 1
	s_waitcnt lgkmcnt(0)
	v_mfma_f32_16x16x32_bf16 v[124:127], v[128:131], v[180:183], v[124:127]
	v_mfma_f32_16x16x32_bf16 v[120:123], v[136:139], v[180:183], v[120:123]
	v_mfma_f32_16x16x32_bf16 v[108:111], v[128:131], v[198:201], v[108:111]
	v_mfma_f32_16x16x32_bf16 v[104:107], v[136:139], v[198:201], v[104:107]
	v_mfma_f32_16x16x32_bf16 v[92:95], v[128:131], v[206:209], v[92:95]
	v_mfma_f32_16x16x32_bf16 v[88:91], v[136:139], v[206:209], v[88:91]
	v_mfma_f32_16x16x32_bf16 v[76:79], v[128:131], v[214:217], v[76:79]
	v_mfma_f32_16x16x32_bf16 v[72:75], v[136:139], v[214:217], v[72:75]
	v_mfma_f32_16x16x32_bf16 v[124:127], v[132:135], v[194:197], v[124:127]
	v_mfma_f32_16x16x32_bf16 v[120:123], v[140:143], v[194:197], v[120:123]
	v_mfma_f32_16x16x32_bf16 v[108:111], v[132:135], v[202:205], v[108:111]
	v_mfma_f32_16x16x32_bf16 v[104:107], v[140:143], v[202:205], v[104:107]
	v_mfma_f32_16x16x32_bf16 v[92:95], v[132:135], v[210:213], v[92:95]
	v_mfma_f32_16x16x32_bf16 v[88:91], v[140:143], v[210:213], v[88:91]
	v_mfma_f32_16x16x32_bf16 v[76:79], v[132:135], v[218:221], v[76:79]
	v_mfma_f32_16x16x32_bf16 v[72:75], v[140:143], v[218:221], v[72:75]
	s_setprio 0
	s_setprio 1
	v_mfma_f32_16x16x32_bf16 v[116:119], v[144:147], v[180:183], v[116:119]
	v_mfma_f32_16x16x32_bf16 v[112:115], v[172:175], v[180:183], v[112:115]
	v_mfma_f32_16x16x32_bf16 v[100:103], v[144:147], v[198:201], v[100:103]
	v_mfma_f32_16x16x32_bf16 v[96:99], v[172:175], v[198:201], v[96:99]
	v_mfma_f32_16x16x32_bf16 v[84:87], v[144:147], v[206:209], v[84:87]
	v_mfma_f32_16x16x32_bf16 v[80:83], v[172:175], v[206:209], v[80:83]
	v_mfma_f32_16x16x32_bf16 v[68:71], v[144:147], v[214:217], v[68:71]
	v_mfma_f32_16x16x32_bf16 v[64:67], v[172:175], v[214:217], v[64:67]
	v_mfma_f32_16x16x32_bf16 v[116:119], v[148:151], v[194:197], v[116:119]
	v_mfma_f32_16x16x32_bf16 v[112:115], v[176:179], v[194:197], v[112:115]
	v_mfma_f32_16x16x32_bf16 v[100:103], v[148:151], v[202:205], v[100:103]
	v_mfma_f32_16x16x32_bf16 v[96:99], v[176:179], v[202:205], v[96:99]
	v_mfma_f32_16x16x32_bf16 v[84:87], v[148:151], v[210:213], v[84:87]
	v_mfma_f32_16x16x32_bf16 v[80:83], v[176:179], v[210:213], v[80:83]
	v_mfma_f32_16x16x32_bf16 v[68:71], v[148:151], v[218:221], v[68:71]
	v_mfma_f32_16x16x32_bf16 v[64:67], v[176:179], v[218:221], v[64:67]
	s_setprio 0
	s_barrier
	s_add_i32 s64, s84, s69
	v_lshl_add_u64 v[222:223], v[222:223], 0, s[26:27]
	s_mov_b32 m0, s64
	ds_read_b128 v[180:183], v191 offset:49152
	ds_read_b128 v[194:197], v191 offset:50176
	ds_read_b128 v[198:201], v191 offset:51200
	ds_read_b128 v[202:205], v191 offset:52224
	ds_read_b128 v[206:209], v191 offset:53248
	ds_read_b128 v[210:213], v191 offset:54272
	ds_read_b128 v[214:217], v191 offset:55296
	ds_read_b128 v[218:221], v191 offset:56320
	global_load_lds_dwordx4 v[222:223], off
	s_add_i32 m0, s64, 0x2000
	s_add_u32 s62, s62, 0x80080
	v_lshl_add_u64 v[222:223], v[224:225], 0, s[26:27]
	s_addc_u32 s63, s63, 0
	s_add_i32 s64, s85, s69
	global_load_lds_dwordx4 v[222:223], off
	v_lshl_add_u64 v[222:223], s[62:63], 0, v[154:155]
	s_mov_b32 m0, s64
	s_nop 0
	global_load_lds_dwordx4 v[222:223], off
	v_lshl_add_u64 v[222:223], s[62:63], 0, v[162:163]
	s_add_i32 m0, s64, 0x2000
	s_nop 0
	global_load_lds_dwordx4 v[222:223], off
	v_lshl_add_u64 v[222:223], v[226:227], 0, s[26:27]
	s_mov_b32 m0, s3
	s_nop 0
	global_load_lds_dwordx4 v[222:223], off
	v_lshl_add_u64 v[222:223], v[228:229], 0, s[26:27]
	s_mov_b32 m0, s75
	s_nop 0
	global_load_lds_dwordx4 v[222:223], off
	s_waitcnt vmcnt(8)
	s_waitcnt lgkmcnt(0)
	s_barrier
	s_setprio 1
	s_waitcnt lgkmcnt(0)
	v_mfma_f32_16x16x32_bf16 v[60:63], v[128:131], v[180:183], v[60:63]
	v_mfma_f32_16x16x32_bf16 v[56:59], v[136:139], v[180:183], v[56:59]
	v_mfma_f32_16x16x32_bf16 v[44:47], v[128:131], v[198:201], v[44:47]
	v_mfma_f32_16x16x32_bf16 v[40:43], v[136:139], v[198:201], v[40:43]
	v_mfma_f32_16x16x32_bf16 v[28:31], v[128:131], v[206:209], v[28:31]
	v_mfma_f32_16x16x32_bf16 v[24:27], v[136:139], v[206:209], v[24:27]
	v_mfma_f32_16x16x32_bf16 v[12:15], v[128:131], v[214:217], v[12:15]
	v_mfma_f32_16x16x32_bf16 v[8:11], v[136:139], v[214:217], v[8:11]
	v_mfma_f32_16x16x32_bf16 v[60:63], v[132:135], v[194:197], v[60:63]
	v_mfma_f32_16x16x32_bf16 v[56:59], v[140:143], v[194:197], v[56:59]
	v_mfma_f32_16x16x32_bf16 v[44:47], v[132:135], v[202:205], v[44:47]
	v_mfma_f32_16x16x32_bf16 v[40:43], v[140:143], v[202:205], v[40:43]
	v_mfma_f32_16x16x32_bf16 v[28:31], v[132:135], v[210:213], v[28:31]
	v_mfma_f32_16x16x32_bf16 v[24:27], v[140:143], v[210:213], v[24:27]
	v_mfma_f32_16x16x32_bf16 v[12:15], v[132:135], v[218:221], v[12:15]
	v_mfma_f32_16x16x32_bf16 v[8:11], v[140:143], v[218:221], v[8:11]
	s_setprio 0
	s_setprio 1
	v_mfma_f32_16x16x32_bf16 v[52:55], v[144:147], v[180:183], v[52:55]
	v_mfma_f32_16x16x32_bf16 v[48:51], v[172:175], v[180:183], v[48:51]
	v_mfma_f32_16x16x32_bf16 v[36:39], v[144:147], v[198:201], v[36:39]
	v_mfma_f32_16x16x32_bf16 v[32:35], v[172:175], v[198:201], v[32:35]
	v_mfma_f32_16x16x32_bf16 v[20:23], v[144:147], v[206:209], v[20:23]
	v_mfma_f32_16x16x32_bf16 v[16:19], v[172:175], v[206:209], v[16:19]
	v_mfma_f32_16x16x32_bf16 v[4:7], v[144:147], v[214:217], v[4:7]
	v_mfma_f32_16x16x32_bf16 v[0:3], v[172:175], v[214:217], v[0:3]
	v_mfma_f32_16x16x32_bf16 v[52:55], v[148:151], v[194:197], v[52:55]
	v_mfma_f32_16x16x32_bf16 v[48:51], v[176:179], v[194:197], v[48:51]
	v_mfma_f32_16x16x32_bf16 v[36:39], v[148:151], v[202:205], v[36:39]
	v_mfma_f32_16x16x32_bf16 v[32:35], v[176:179], v[202:205], v[32:35]
	v_mfma_f32_16x16x32_bf16 v[20:23], v[148:151], v[210:213], v[20:23]
	v_mfma_f32_16x16x32_bf16 v[16:19], v[176:179], v[210:213], v[16:19]
	v_mfma_f32_16x16x32_bf16 v[4:7], v[148:151], v[218:221], v[4:7]
	v_mfma_f32_16x16x32_bf16 v[0:3], v[176:179], v[218:221], v[0:3]
	s_setprio 0
	s_barrier
	s_add_i32 s83, s83, 2
	s_add_u32 s81, s81, 0x100
	s_addc_u32 s82, s82, 0
	s_add_u32 s60, s60, 0x100
	s_addc_u32 s61, s61, 0
	s_cmp_gt_u32 s83, 29

.LBB0_525:
	s_ashr_i32 s29, s28, 31
	s_lshl_b64 s[30:31], s[28:29], 19
	s_add_u32 s30, s3, s30
	s_addc_u32 s31, s35, s31
	s_and_b64 s[44:45], s[10:11], exec
	s_cselect_b32 s29, s31, s51
	s_cselect_b32 s70, s30, s50
	s_ashr_i32 s27, s26, 31
	s_lshl_b64 s[44:45], s[26:27], 19
	s_add_u32 s44, s52, s44
	s_addc_u32 s45, s53, s45
	s_and_b64 s[72:73], s[10:11], exec
	s_cselect_b32 s71, s45, s49
	s_cselect_b32 s72, s44, s48
	s_lshl_b32 s27, s46, 8
	v_add_u32_e32 v0, s27, v148
	s_add_u32 s73, s48, 0x100
	v_ashrrev_i32_e32 v1, 31, v0
	s_addc_u32 s74, s49, 0
	v_lshl_add_u64 v[144:145], v[0:1], 4, s[16:17]
	s_add_u32 s46, s50, 0x40080
	s_addc_u32 s47, s51, 0
	s_mov_b32 s75, -2
	s_mov_b64 s[48:49], 0
	v_add_u32_e32 v153, s66, v147
	ds_read_b128 v[160:163], v153
	ds_read_b128 v[164:167], v153 offset:1024
	ds_read_b128 v[168:171], v153 offset:2048
	ds_read_b128 v[172:175], v153 offset:3072
	v_add_u32_e32 v153, s67, v147
	ds_read_b128 v[176:179], v153
	ds_read_b128 v[180:183], v153 offset:1024
	ds_read_b128 v[186:189], v153 offset:2048
	ds_read_b128 v[190:193], v153 offset:3072
	s_add_u32 s50, s46, 0xfffc0080
	s_addc_u32 s51, s47, -1
	s_and_b64 s[48:49], s[48:49], exec
	s_cselect_b32 s51, s29, s51
	s_cselect_b32 s50, s70, s50
	s_cselect_b32 s49, s71, s74
	s_cselect_b32 s48, s72, s73
	v_lshl_add_u64 v[154:155], s[46:47], 0, v[138:139]
	s_add_i32 m0, s57, 0xc000
	ds_read_b128 v[194:197], v150
	ds_read_b128 v[198:201], v150 offset:1024
	ds_read_b128 v[202:205], v150 offset:2048
	ds_read_b128 v[206:209], v150 offset:3072
	ds_read_b128 v[210:213], v150 offset:4096
	ds_read_b128 v[214:217], v150 offset:5120
	ds_read_b128 v[218:221], v150 offset:6144
	ds_read_b128 v[222:225], v150 offset:7168
	global_load_lds_dwordx4 v[154:155], off
	v_lshl_add_u64 v[154:155], s[46:47], 0, v[136:137]
	s_add_i32 m0, s57, 0xe000
	s_nop 0
	global_load_lds_dwordx4 v[154:155], off
	s_waitcnt vmcnt(8)
	s_waitcnt lgkmcnt(0)
	s_barrier
	s_setprio 1
	s_waitcnt lgkmcnt(0)
	v_mfma_f32_16x16x32_bf16 v[124:127], v[160:163], v[194:197], 0
	v_mfma_f32_16x16x32_bf16 v[116:119], v[168:171], v[194:197], 0
	v_mfma_f32_16x16x32_bf16 v[108:111], v[160:163], v[202:205], 0
	v_mfma_f32_16x16x32_bf16 v[100:103], v[168:171], v[202:205], 0
	v_mfma_f32_16x16x32_bf16 v[92:95], v[160:163], v[210:213], 0
	v_mfma_f32_16x16x32_bf16 v[84:87], v[168:171], v[210:213], 0
	v_mfma_f32_16x16x32_bf16 v[76:79], v[160:163], v[218:221], 0
	v_mfma_f32_16x16x32_bf16 v[68:71], v[168:171], v[218:221], 0
	v_mfma_f32_16x16x32_bf16 v[124:127], v[164:167], v[198:201], v[124:127]
	v_mfma_f32_16x16x32_bf16 v[116:119], v[172:175], v[198:201], v[116:119]
	v_mfma_f32_16x16x32_bf16 v[108:111], v[164:167], v[206:209], v[108:111]
	v_mfma_f32_16x16x32_bf16 v[100:103], v[172:175], v[206:209], v[100:103]
	v_mfma_f32_16x16x32_bf16 v[92:95], v[164:167], v[214:217], v[92:95]
	v_mfma_f32_16x16x32_bf16 v[84:87], v[172:175], v[214:217], v[84:87]
	v_mfma_f32_16x16x32_bf16 v[76:79], v[164:167], v[222:225], v[76:79]
	v_mfma_f32_16x16x32_bf16 v[68:71], v[172:175], v[222:225], v[68:71]
	s_setprio 0
	s_setprio 1
	v_mfma_f32_16x16x32_bf16 v[120:123], v[176:179], v[194:197], 0
	v_mfma_f32_16x16x32_bf16 v[112:115], v[186:189], v[194:197], 0
	v_mfma_f32_16x16x32_bf16 v[104:107], v[176:179], v[202:205], 0
	v_mfma_f32_16x16x32_bf16 v[96:99], v[186:189], v[202:205], 0
	v_mfma_f32_16x16x32_bf16 v[88:91], v[176:179], v[210:213], 0
	v_mfma_f32_16x16x32_bf16 v[80:83], v[186:189], v[210:213], 0
	v_mfma_f32_16x16x32_bf16 v[72:75], v[176:179], v[218:221], 0
	v_mfma_f32_16x16x32_bf16 v[64:67], v[186:189], v[218:221], 0
	v_mfma_f32_16x16x32_bf16 v[120:123], v[180:183], v[198:201], v[120:123]
	v_mfma_f32_16x16x32_bf16 v[112:115], v[190:193], v[198:201], v[112:115]
	v_mfma_f32_16x16x32_bf16 v[104:107], v[180:183], v[206:209], v[104:107]
	v_mfma_f32_16x16x32_bf16 v[96:99], v[190:193], v[206:209], v[96:99]
	v_mfma_f32_16x16x32_bf16 v[88:91], v[180:183], v[214:217], v[88:91]
	v_mfma_f32_16x16x32_bf16 v[80:83], v[190:193], v[214:217], v[80:83]
	v_mfma_f32_16x16x32_bf16 v[72:75], v[180:183], v[222:225], v[72:75]
	v_mfma_f32_16x16x32_bf16 v[64:67], v[190:193], v[222:225], v[64:67]
	s_setprio 0
	s_barrier
	s_add_i32 s76, s66, s54
	v_lshl_add_u64 v[154:155], s[48:49], 0, v[132:133]
	s_mov_b32 m0, s76
	ds_read_b128 v[194:197], v150 offset:16384
	ds_read_b128 v[198:201], v150 offset:17408
	ds_read_b128 v[202:205], v150 offset:18432
	ds_read_b128 v[206:209], v150 offset:19456
	ds_read_b128 v[210:213], v150 offset:20480
	ds_read_b128 v[214:217], v150 offset:21504
	ds_read_b128 v[218:221], v150 offset:22528
	ds_read_b128 v[222:225], v150 offset:23552
	global_load_lds_dwordx4 v[154:155], off
	s_add_i32 m0, s76, 0x2000
	s_add_u32 s76, s48, 0x40000
	v_lshl_add_u64 v[226:227], s[48:49], 0, v[128:129]
	s_addc_u32 s77, s49, 0
	s_add_i32 s78, s67, s54
	global_load_lds_dwordx4 v[226:227], off
	v_lshl_add_u64 v[228:229], s[76:77], 0, v[132:133]
	s_mov_b32 m0, s78
	v_lshl_add_u64 v[230:231], s[50:51], 0, v[130:131]
	global_load_lds_dwordx4 v[228:229], off
	v_lshl_add_u64 v[228:229], s[76:77], 0, v[128:129]
	s_add_i32 m0, s78, 0x2000
	s_nop 0
	global_load_lds_dwordx4 v[228:229], off
	v_lshl_add_u64 v[228:229], s[50:51], 0, v[134:135]
	s_mov_b32 m0, s57
	s_nop 0
	global_load_lds_dwordx4 v[228:229], off
	s_mov_b32 m0, s58
	s_nop 0
	global_load_lds_dwordx4 v[230:231], off
	s_waitcnt vmcnt(8)
	s_waitcnt lgkmcnt(0)
	s_barrier
	s_setprio 1
	s_waitcnt lgkmcnt(0)
	v_mfma_f32_16x16x32_bf16 v[60:63], v[160:163], v[194:197], 0
	v_mfma_f32_16x16x32_bf16 v[52:55], v[168:171], v[194:197], 0
	v_mfma_f32_16x16x32_bf16 v[44:47], v[160:163], v[202:205], 0
	v_mfma_f32_16x16x32_bf16 v[36:39], v[168:171], v[202:205], 0
	v_mfma_f32_16x16x32_bf16 v[28:31], v[160:163], v[210:213], 0
	v_mfma_f32_16x16x32_bf16 v[20:23], v[168:171], v[210:213], 0
	v_mfma_f32_16x16x32_bf16 v[12:15], v[160:163], v[218:221], 0
	v_mfma_f32_16x16x32_bf16 v[4:7], v[168:171], v[218:221], 0
	v_mfma_f32_16x16x32_bf16 v[60:63], v[164:167], v[198:201], v[60:63]
	v_mfma_f32_16x16x32_bf16 v[52:55], v[172:175], v[198:201], v[52:55]
	v_mfma_f32_16x16x32_bf16 v[44:47], v[164:167], v[206:209], v[44:47]
	v_mfma_f32_16x16x32_bf16 v[36:39], v[172:175], v[206:209], v[36:39]
	v_mfma_f32_16x16x32_bf16 v[28:31], v[164:167], v[214:217], v[28:31]
	v_mfma_f32_16x16x32_bf16 v[20:23], v[172:175], v[214:217], v[20:23]
	v_mfma_f32_16x16x32_bf16 v[12:15], v[164:167], v[222:225], v[12:15]
	v_mfma_f32_16x16x32_bf16 v[4:7], v[172:175], v[222:225], v[4:7]
	s_setprio 0
	s_setprio 1
	v_mfma_f32_16x16x32_bf16 v[56:59], v[176:179], v[194:197], 0
	v_mfma_f32_16x16x32_bf16 v[48:51], v[186:189], v[194:197], 0
	v_mfma_f32_16x16x32_bf16 v[40:43], v[176:179], v[202:205], 0
	v_mfma_f32_16x16x32_bf16 v[32:35], v[186:189], v[202:205], 0
	v_mfma_f32_16x16x32_bf16 v[24:27], v[176:179], v[210:213], 0
	v_mfma_f32_16x16x32_bf16 v[16:19], v[186:189], v[210:213], 0
	v_mfma_f32_16x16x32_bf16 v[8:11], v[176:179], v[218:221], 0
	v_mfma_f32_16x16x32_bf16 v[0:3], v[186:189], v[218:221], 0
	v_mfma_f32_16x16x32_bf16 v[56:59], v[180:183], v[198:201], v[56:59]
	v_mfma_f32_16x16x32_bf16 v[48:51], v[190:193], v[198:201], v[48:51]
	v_mfma_f32_16x16x32_bf16 v[40:43], v[180:183], v[206:209], v[40:43]
	v_mfma_f32_16x16x32_bf16 v[32:35], v[190:193], v[206:209], v[32:35]
	v_mfma_f32_16x16x32_bf16 v[24:27], v[180:183], v[214:217], v[24:27]
	v_mfma_f32_16x16x32_bf16 v[16:19], v[190:193], v[214:217], v[16:19]
	v_mfma_f32_16x16x32_bf16 v[8:11], v[180:183], v[222:225], v[8:11]
	v_mfma_f32_16x16x32_bf16 v[0:3], v[190:193], v[222:225], v[0:3]
	s_setprio 0
	s_barrier
	s_add_i32 s76, 0, 0x18000
	v_add_u32_e32 v153, s76, v147
	s_add_i32 s77, 0, 0x1c000
	ds_read_b128 v[160:163], v153
	ds_read_b128 v[164:167], v153 offset:1024
	ds_read_b128 v[168:171], v153 offset:2048
	ds_read_b128 v[172:175], v153 offset:3072
	v_add_u32_e32 v153, s77, v147
	ds_read_b128 v[176:179], v153
	ds_read_b128 v[180:183], v153 offset:1024
	ds_read_b128 v[186:189], v153 offset:2048
	ds_read_b128 v[190:193], v153 offset:3072
	s_add_u32 s50, s50, 0x40000
	s_addc_u32 s51, s51, 0
	s_mov_b32 m0, s59
	v_lshl_add_u64 v[232:233], s[50:51], 0, v[134:135]
	ds_read_b128 v[194:197], v150 offset:32768
	ds_read_b128 v[198:201], v150 offset:33792
	ds_read_b128 v[202:205], v150 offset:34816
	ds_read_b128 v[206:209], v150 offset:35840
	ds_read_b128 v[210:213], v150 offset:36864
	ds_read_b128 v[214:217], v150 offset:37888
	ds_read_b128 v[218:221], v150 offset:38912
	ds_read_b128 v[222:225], v150 offset:39936
	global_load_lds_dwordx4 v[232:233], off
	v_lshl_add_u64 v[232:233], s[50:51], 0, v[130:131]
	s_mov_b32 m0, s60
	s_nop 0
	global_load_lds_dwordx4 v[232:233], off
	s_waitcnt vmcnt(8)
	s_waitcnt lgkmcnt(0)
	s_barrier
	s_setprio 1
	s_waitcnt lgkmcnt(0)
	v_mfma_f32_16x16x32_bf16 v[124:127], v[160:163], v[194:197], v[124:127]
	v_mfma_f32_16x16x32_bf16 v[116:119], v[168:171], v[194:197], v[116:119]
	v_mfma_f32_16x16x32_bf16 v[108:111], v[160:163], v[202:205], v[108:111]
	v_mfma_f32_16x16x32_bf16 v[100:103], v[168:171], v[202:205], v[100:103]
	v_mfma_f32_16x16x32_bf16 v[92:95], v[160:163], v[210:213], v[92:95]
	v_mfma_f32_16x16x32_bf16 v[84:87], v[168:171], v[210:213], v[84:87]
	v_mfma_f32_16x16x32_bf16 v[76:79], v[160:163], v[218:221], v[76:79]
	v_mfma_f32_16x16x32_bf16 v[68:71], v[168:171], v[218:221], v[68:71]
	v_mfma_f32_16x16x32_bf16 v[124:127], v[164:167], v[198:201], v[124:127]
	v_mfma_f32_16x16x32_bf16 v[116:119], v[172:175], v[198:201], v[116:119]
	v_mfma_f32_16x16x32_bf16 v[108:111], v[164:167], v[206:209], v[108:111]
	v_mfma_f32_16x16x32_bf16 v[100:103], v[172:175], v[206:209], v[100:103]
	v_mfma_f32_16x16x32_bf16 v[92:95], v[164:167], v[214:217], v[92:95]
	v_mfma_f32_16x16x32_bf16 v[84:87], v[172:175], v[214:217], v[84:87]
	v_mfma_f32_16x16x32_bf16 v[76:79], v[164:167], v[222:225], v[76:79]
	v_mfma_f32_16x16x32_bf16 v[68:71], v[172:175], v[222:225], v[68:71]
	s_setprio 0
	s_setprio 1
	v_mfma_f32_16x16x32_bf16 v[120:123], v[176:179], v[194:197], v[120:123]
	v_mfma_f32_16x16x32_bf16 v[112:115], v[186:189], v[194:197], v[112:115]
	v_mfma_f32_16x16x32_bf16 v[104:107], v[176:179], v[202:205], v[104:107]
	v_mfma_f32_16x16x32_bf16 v[96:99], v[186:189], v[202:205], v[96:99]
	v_mfma_f32_16x16x32_bf16 v[88:91], v[176:179], v[210:213], v[88:91]
	v_mfma_f32_16x16x32_bf16 v[80:83], v[186:189], v[210:213], v[80:83]
	v_mfma_f32_16x16x32_bf16 v[72:75], v[176:179], v[218:221], v[72:75]
	v_mfma_f32_16x16x32_bf16 v[64:67], v[186:189], v[218:221], v[64:67]
	v_mfma_f32_16x16x32_bf16 v[120:123], v[180:183], v[198:201], v[120:123]
	v_mfma_f32_16x16x32_bf16 v[112:115], v[190:193], v[198:201], v[112:115]
	v_mfma_f32_16x16x32_bf16 v[104:107], v[180:183], v[206:209], v[104:107]
	v_mfma_f32_16x16x32_bf16 v[96:99], v[190:193], v[206:209], v[96:99]
	v_mfma_f32_16x16x32_bf16 v[88:91], v[180:183], v[214:217], v[88:91]
	v_mfma_f32_16x16x32_bf16 v[80:83], v[190:193], v[214:217], v[80:83]
	v_mfma_f32_16x16x32_bf16 v[72:75], v[180:183], v[222:225], v[72:75]
	v_mfma_f32_16x16x32_bf16 v[64:67], v[190:193], v[222:225], v[64:67]
	s_setprio 0
	s_barrier
	s_add_i32 s50, s76, s54
	v_lshl_add_u64 v[154:155], v[154:155], 0, s[20:21]
	s_mov_b32 m0, s50
	ds_read_b128 v[194:197], v150 offset:49152
	ds_read_b128 v[198:201], v150 offset:50176
	ds_read_b128 v[202:205], v150 offset:51200
	ds_read_b128 v[206:209], v150 offset:52224
	ds_read_b128 v[210:213], v150 offset:53248
	ds_read_b128 v[214:217], v150 offset:54272
	ds_read_b128 v[218:221], v150 offset:55296
	ds_read_b128 v[222:225], v150 offset:56320
	global_load_lds_dwordx4 v[154:155], off
	s_add_i32 m0, s50, 0x2000
	s_add_u32 s48, s48, 0x40080
	v_lshl_add_u64 v[154:155], v[226:227], 0, s[20:21]
	s_addc_u32 s49, s49, 0
	s_add_i32 s50, s77, s54
	global_load_lds_dwordx4 v[154:155], off
	v_lshl_add_u64 v[154:155], s[48:49], 0, v[132:133]
	s_mov_b32 m0, s50
	s_nop 0
	global_load_lds_dwordx4 v[154:155], off
	v_lshl_add_u64 v[154:155], s[48:49], 0, v[128:129]
	s_add_i32 m0, s50, 0x2000
	s_nop 0
	global_load_lds_dwordx4 v[154:155], off
	v_lshl_add_u64 v[154:155], v[228:229], 0, s[20:21]
	s_mov_b32 m0, s62
	s_nop 0
	global_load_lds_dwordx4 v[154:155], off
	v_lshl_add_u64 v[154:155], v[230:231], 0, s[20:21]
	s_mov_b32 m0, s63
	s_nop 0
	global_load_lds_dwordx4 v[154:155], off
	s_waitcnt vmcnt(8)
	s_waitcnt lgkmcnt(0)
	s_barrier
	s_setprio 1
	s_waitcnt lgkmcnt(0)
	v_mfma_f32_16x16x32_bf16 v[60:63], v[160:163], v[194:197], v[60:63]
	v_mfma_f32_16x16x32_bf16 v[52:55], v[168:171], v[194:197], v[52:55]
	v_mfma_f32_16x16x32_bf16 v[44:47], v[160:163], v[202:205], v[44:47]
	v_mfma_f32_16x16x32_bf16 v[36:39], v[168:171], v[202:205], v[36:39]
	v_mfma_f32_16x16x32_bf16 v[28:31], v[160:163], v[210:213], v[28:31]
	v_mfma_f32_16x16x32_bf16 v[20:23], v[168:171], v[210:213], v[20:23]
	v_mfma_f32_16x16x32_bf16 v[12:15], v[160:163], v[218:221], v[12:15]
	v_mfma_f32_16x16x32_bf16 v[4:7], v[168:171], v[218:221], v[4:7]
	v_mfma_f32_16x16x32_bf16 v[60:63], v[164:167], v[198:201], v[60:63]
	v_mfma_f32_16x16x32_bf16 v[52:55], v[172:175], v[198:201], v[52:55]
	v_mfma_f32_16x16x32_bf16 v[44:47], v[164:167], v[206:209], v[44:47]
	v_mfma_f32_16x16x32_bf16 v[36:39], v[172:175], v[206:209], v[36:39]
	v_mfma_f32_16x16x32_bf16 v[28:31], v[164:167], v[214:217], v[28:31]
	v_mfma_f32_16x16x32_bf16 v[20:23], v[172:175], v[214:217], v[20:23]
	v_mfma_f32_16x16x32_bf16 v[12:15], v[164:167], v[222:225], v[12:15]
	v_mfma_f32_16x16x32_bf16 v[4:7], v[172:175], v[222:225], v[4:7]
	s_setprio 0
	s_setprio 1
	v_mfma_f32_16x16x32_bf16 v[56:59], v[176:179], v[194:197], v[56:59]
	v_mfma_f32_16x16x32_bf16 v[48:51], v[186:189], v[194:197], v[48:51]
	v_mfma_f32_16x16x32_bf16 v[40:43], v[176:179], v[202:205], v[40:43]
	v_mfma_f32_16x16x32_bf16 v[32:35], v[186:189], v[202:205], v[32:35]
	v_mfma_f32_16x16x32_bf16 v[24:27], v[176:179], v[210:213], v[24:27]
	v_mfma_f32_16x16x32_bf16 v[16:19], v[186:189], v[210:213], v[16:19]
	v_mfma_f32_16x16x32_bf16 v[8:11], v[176:179], v[218:221], v[8:11]
	v_mfma_f32_16x16x32_bf16 v[0:3], v[186:189], v[218:221], v[0:3]
	v_mfma_f32_16x16x32_bf16 v[56:59], v[180:183], v[198:201], v[56:59]
	v_mfma_f32_16x16x32_bf16 v[48:51], v[190:193], v[198:201], v[48:51]
	v_mfma_f32_16x16x32_bf16 v[40:43], v[180:183], v[206:209], v[40:43]
	v_mfma_f32_16x16x32_bf16 v[32:35], v[190:193], v[206:209], v[32:35]
	v_mfma_f32_16x16x32_bf16 v[24:27], v[180:183], v[214:217], v[24:27]
	v_mfma_f32_16x16x32_bf16 v[16:19], v[190:193], v[214:217], v[16:19]
	v_mfma_f32_16x16x32_bf16 v[8:11], v[180:183], v[222:225], v[8:11]
	v_mfma_f32_16x16x32_bf16 v[0:3], v[190:193], v[222:225], v[0:3]
	s_setprio 0
	s_barrier
	s_add_i32 s75, s75, 2
	s_add_u32 s73, s73, 0x100
	s_addc_u32 s74, s74, 0
	s_add_u32 s46, s46, 0x100
	s_addc_u32 s47, s47, 0
	s_branch .LBB0_527

.LBB0_609:
	s_add_u32 s79, s56, 0x100
	s_addc_u32 s80, s57, 0
	s_mov_b32 s81, -2
	s_waitcnt lgkmcnt(0)
	ds_read_b128 v[128:131], v189
	ds_read_b128 v[132:135], v189 offset:1024
	ds_read_b128 v[136:139], v189 offset:2048
	ds_read_b128 v[140:143], v189 offset:3072
	ds_read_b128 v[144:147], v190
	ds_read_b128 v[148:151], v190 offset:1024
	ds_read_b128 v[172:175], v190 offset:2048
	ds_read_b128 v[176:179], v190 offset:3072
	s_add_u32 s56, s54, 0x100
	s_addc_u32 s57, s55, 0
	s_cmp_eq_u32 s81, 40
	s_cselect_b32 s61, s17, s57
	s_cselect_b32 s60, s16, s56
	s_cselect_b32 s59, s53, s80
	s_cselect_b32 s58, s52, s79
	v_lshl_add_u64 v[222:223], s[54:55], 0, v[166:167]
	s_add_i32 m0, s66, 0xc000
	ds_read_b128 v[180:183], v191
	ds_read_b128 v[194:197], v191 offset:1024
	ds_read_b128 v[198:201], v191 offset:2048
	ds_read_b128 v[202:205], v191 offset:3072
	ds_read_b128 v[206:209], v191 offset:4096
	ds_read_b128 v[210:213], v191 offset:5120
	ds_read_b128 v[214:217], v191 offset:6144
	ds_read_b128 v[218:221], v191 offset:7168
	global_load_lds_dwordx4 v[222:223], off
	v_lshl_add_u64 v[222:223], s[54:55], 0, v[164:165]
	s_add_i32 m0, s66, 0xe000
	s_nop 0
	global_load_lds_dwordx4 v[222:223], off
	s_waitcnt vmcnt(8)
	s_waitcnt lgkmcnt(0)
	s_barrier
	s_setprio 1
	s_waitcnt lgkmcnt(0)
	v_mfma_f32_16x16x32_bf16 v[124:127], v[128:131], v[180:183], 0
	v_mfma_f32_16x16x32_bf16 v[120:123], v[136:139], v[180:183], 0
	v_mfma_f32_16x16x32_bf16 v[108:111], v[128:131], v[198:201], 0
	v_mfma_f32_16x16x32_bf16 v[104:107], v[136:139], v[198:201], 0
	v_mfma_f32_16x16x32_bf16 v[92:95], v[128:131], v[206:209], 0
	v_mfma_f32_16x16x32_bf16 v[88:91], v[136:139], v[206:209], 0
	v_mfma_f32_16x16x32_bf16 v[76:79], v[128:131], v[214:217], 0
	v_mfma_f32_16x16x32_bf16 v[72:75], v[136:139], v[214:217], 0
	v_mfma_f32_16x16x32_bf16 v[124:127], v[132:135], v[194:197], v[124:127]
	v_mfma_f32_16x16x32_bf16 v[120:123], v[140:143], v[194:197], v[120:123]
	v_mfma_f32_16x16x32_bf16 v[108:111], v[132:135], v[202:205], v[108:111]
	v_mfma_f32_16x16x32_bf16 v[104:107], v[140:143], v[202:205], v[104:107]
	v_mfma_f32_16x16x32_bf16 v[92:95], v[132:135], v[210:213], v[92:95]
	v_mfma_f32_16x16x32_bf16 v[88:91], v[140:143], v[210:213], v[88:91]
	v_mfma_f32_16x16x32_bf16 v[76:79], v[132:135], v[218:221], v[76:79]
	v_mfma_f32_16x16x32_bf16 v[72:75], v[140:143], v[218:221], v[72:75]
	s_setprio 0
	s_setprio 1
	v_mfma_f32_16x16x32_bf16 v[116:119], v[144:147], v[180:183], 0
	v_mfma_f32_16x16x32_bf16 v[112:115], v[172:175], v[180:183], 0
	v_mfma_f32_16x16x32_bf16 v[100:103], v[144:147], v[198:201], 0
	v_mfma_f32_16x16x32_bf16 v[96:99], v[172:175], v[198:201], 0
	v_mfma_f32_16x16x32_bf16 v[84:87], v[144:147], v[206:209], 0
	v_mfma_f32_16x16x32_bf16 v[80:83], v[172:175], v[206:209], 0
	v_mfma_f32_16x16x32_bf16 v[68:71], v[144:147], v[214:217], 0
	v_mfma_f32_16x16x32_bf16 v[64:67], v[172:175], v[214:217], 0
	v_mfma_f32_16x16x32_bf16 v[116:119], v[148:151], v[194:197], v[116:119]
	v_mfma_f32_16x16x32_bf16 v[112:115], v[176:179], v[194:197], v[112:115]
	v_mfma_f32_16x16x32_bf16 v[100:103], v[148:151], v[202:205], v[100:103]
	v_mfma_f32_16x16x32_bf16 v[96:99], v[176:179], v[202:205], v[96:99]
	v_mfma_f32_16x16x32_bf16 v[84:87], v[148:151], v[210:213], v[84:87]
	v_mfma_f32_16x16x32_bf16 v[80:83], v[176:179], v[210:213], v[80:83]
	v_mfma_f32_16x16x32_bf16 v[68:71], v[148:151], v[218:221], v[68:71]
	v_mfma_f32_16x16x32_bf16 v[64:67], v[176:179], v[218:221], v[64:67]
	s_setprio 0
	s_barrier
	s_add_i32 s54, s75, s65
	v_lshl_add_u64 v[222:223], s[58:59], 0, v[154:155]
	s_mov_b32 m0, s54
	ds_read_b128 v[180:183], v191 offset:16384
	ds_read_b128 v[194:197], v191 offset:17408
	ds_read_b128 v[198:201], v191 offset:18432
	ds_read_b128 v[202:205], v191 offset:19456
	ds_read_b128 v[206:209], v191 offset:20480
	ds_read_b128 v[210:213], v191 offset:21504
	ds_read_b128 v[214:217], v191 offset:22528
	ds_read_b128 v[218:221], v191 offset:23552
	global_load_lds_dwordx4 v[222:223], off
	s_add_i32 m0, s54, 0x2000
	s_add_u32 s54, s58, 0xb0000
	v_lshl_add_u64 v[224:225], s[58:59], 0, v[162:163]
	s_addc_u32 s55, s59, 0
	s_add_i32 s82, s76, s65
	global_load_lds_dwordx4 v[224:225], off
	v_lshl_add_u64 v[226:227], s[54:55], 0, v[154:155]
	s_mov_b32 m0, s82
	v_lshl_add_u64 v[228:229], s[60:61], 0, v[160:161]
	global_load_lds_dwordx4 v[226:227], off
	v_lshl_add_u64 v[226:227], s[54:55], 0, v[162:163]
	s_add_i32 m0, s82, 0x2000
	s_nop 0
	global_load_lds_dwordx4 v[226:227], off
	v_lshl_add_u64 v[226:227], s[60:61], 0, v[152:153]
	s_mov_b32 m0, s66
	s_nop 0
	global_load_lds_dwordx4 v[226:227], off
	s_mov_b32 m0, s67
	s_nop 0
	global_load_lds_dwordx4 v[228:229], off
	s_waitcnt vmcnt(8)
	s_waitcnt lgkmcnt(0)
	s_barrier
	s_setprio 1
	s_waitcnt lgkmcnt(0)
	v_mfma_f32_16x16x32_bf16 v[60:63], v[128:131], v[180:183], 0
	v_mfma_f32_16x16x32_bf16 v[56:59], v[136:139], v[180:183], 0
	v_mfma_f32_16x16x32_bf16 v[44:47], v[128:131], v[198:201], 0
	v_mfma_f32_16x16x32_bf16 v[40:43], v[136:139], v[198:201], 0
	v_mfma_f32_16x16x32_bf16 v[28:31], v[128:131], v[206:209], 0
	v_mfma_f32_16x16x32_bf16 v[24:27], v[136:139], v[206:209], 0
	v_mfma_f32_16x16x32_bf16 v[12:15], v[128:131], v[214:217], 0
	v_mfma_f32_16x16x32_bf16 v[8:11], v[136:139], v[214:217], 0
	v_mfma_f32_16x16x32_bf16 v[60:63], v[132:135], v[194:197], v[60:63]
	v_mfma_f32_16x16x32_bf16 v[56:59], v[140:143], v[194:197], v[56:59]
	v_mfma_f32_16x16x32_bf16 v[44:47], v[132:135], v[202:205], v[44:47]
	v_mfma_f32_16x16x32_bf16 v[40:43], v[140:143], v[202:205], v[40:43]
	v_mfma_f32_16x16x32_bf16 v[28:31], v[132:135], v[210:213], v[28:31]
	v_mfma_f32_16x16x32_bf16 v[24:27], v[140:143], v[210:213], v[24:27]
	v_mfma_f32_16x16x32_bf16 v[12:15], v[132:135], v[218:221], v[12:15]
	v_mfma_f32_16x16x32_bf16 v[8:11], v[140:143], v[218:221], v[8:11]
	s_setprio 0
	s_setprio 1
	v_mfma_f32_16x16x32_bf16 v[52:55], v[144:147], v[180:183], 0
	v_mfma_f32_16x16x32_bf16 v[48:51], v[172:175], v[180:183], 0
	v_mfma_f32_16x16x32_bf16 v[36:39], v[144:147], v[198:201], 0
	v_mfma_f32_16x16x32_bf16 v[32:35], v[172:175], v[198:201], 0
	v_mfma_f32_16x16x32_bf16 v[20:23], v[144:147], v[206:209], 0
	v_mfma_f32_16x16x32_bf16 v[16:19], v[172:175], v[206:209], 0
	v_mfma_f32_16x16x32_bf16 v[4:7], v[144:147], v[214:217], 0
	v_mfma_f32_16x16x32_bf16 v[0:3], v[172:175], v[214:217], 0
	v_mfma_f32_16x16x32_bf16 v[52:55], v[148:151], v[194:197], v[52:55]
	v_mfma_f32_16x16x32_bf16 v[48:51], v[176:179], v[194:197], v[48:51]
	v_mfma_f32_16x16x32_bf16 v[36:39], v[148:151], v[202:205], v[36:39]
	v_mfma_f32_16x16x32_bf16 v[32:35], v[176:179], v[202:205], v[32:35]
	v_mfma_f32_16x16x32_bf16 v[20:23], v[148:151], v[210:213], v[20:23]
	v_mfma_f32_16x16x32_bf16 v[16:19], v[176:179], v[210:213], v[16:19]
	v_mfma_f32_16x16x32_bf16 v[4:7], v[148:151], v[218:221], v[4:7]
	v_mfma_f32_16x16x32_bf16 v[0:3], v[176:179], v[218:221], v[0:3]
	s_setprio 0
	s_barrier
	s_add_i32 s82, 0, 0x18000
	s_add_i32 s83, 0, 0x1c000
	v_add_u32_e32 v140, s82, v186
	v_add_u32_e32 v176, s83, v186
	ds_read_b128 v[128:131], v140
	ds_read_b128 v[132:135], v140 offset:1024
	ds_read_b128 v[136:139], v140 offset:2048
	ds_read_b128 v[140:143], v140 offset:3072
	ds_read_b128 v[144:147], v176
	ds_read_b128 v[148:151], v176 offset:1024
	ds_read_b128 v[172:175], v176 offset:2048
	ds_read_b128 v[176:179], v176 offset:3072
	s_add_u32 s54, s60, 0xb0000
	s_addc_u32 s55, s61, 0
	s_mov_b32 m0, s68
	v_lshl_add_u64 v[230:231], s[54:55], 0, v[152:153]
	ds_read_b128 v[180:183], v191 offset:32768
	ds_read_b128 v[194:197], v191 offset:33792
	ds_read_b128 v[198:201], v191 offset:34816
	ds_read_b128 v[202:205], v191 offset:35840
	ds_read_b128 v[206:209], v191 offset:36864
	ds_read_b128 v[210:213], v191 offset:37888
	ds_read_b128 v[214:217], v191 offset:38912
	ds_read_b128 v[218:221], v191 offset:39936
	global_load_lds_dwordx4 v[230:231], off
	v_lshl_add_u64 v[230:231], s[54:55], 0, v[160:161]
	s_mov_b32 m0, s69
	s_nop 0
	global_load_lds_dwordx4 v[230:231], off
	s_waitcnt vmcnt(8)
	s_waitcnt lgkmcnt(0)
	s_barrier
	s_setprio 1
	s_waitcnt lgkmcnt(0)
	v_mfma_f32_16x16x32_bf16 v[124:127], v[128:131], v[180:183], v[124:127]
	v_mfma_f32_16x16x32_bf16 v[120:123], v[136:139], v[180:183], v[120:123]
	v_mfma_f32_16x16x32_bf16 v[108:111], v[128:131], v[198:201], v[108:111]
	v_mfma_f32_16x16x32_bf16 v[104:107], v[136:139], v[198:201], v[104:107]
	v_mfma_f32_16x16x32_bf16 v[92:95], v[128:131], v[206:209], v[92:95]
	v_mfma_f32_16x16x32_bf16 v[88:91], v[136:139], v[206:209], v[88:91]
	v_mfma_f32_16x16x32_bf16 v[76:79], v[128:131], v[214:217], v[76:79]
	v_mfma_f32_16x16x32_bf16 v[72:75], v[136:139], v[214:217], v[72:75]
	v_mfma_f32_16x16x32_bf16 v[124:127], v[132:135], v[194:197], v[124:127]
	v_mfma_f32_16x16x32_bf16 v[120:123], v[140:143], v[194:197], v[120:123]
	v_mfma_f32_16x16x32_bf16 v[108:111], v[132:135], v[202:205], v[108:111]
	v_mfma_f32_16x16x32_bf16 v[104:107], v[140:143], v[202:205], v[104:107]
	v_mfma_f32_16x16x32_bf16 v[92:95], v[132:135], v[210:213], v[92:95]
	v_mfma_f32_16x16x32_bf16 v[88:91], v[140:143], v[210:213], v[88:91]
	v_mfma_f32_16x16x32_bf16 v[76:79], v[132:135], v[218:221], v[76:79]
	v_mfma_f32_16x16x32_bf16 v[72:75], v[140:143], v[218:221], v[72:75]
	s_setprio 0
	s_setprio 1
	v_mfma_f32_16x16x32_bf16 v[116:119], v[144:147], v[180:183], v[116:119]
	v_mfma_f32_16x16x32_bf16 v[112:115], v[172:175], v[180:183], v[112:115]
	v_mfma_f32_16x16x32_bf16 v[100:103], v[144:147], v[198:201], v[100:103]
	v_mfma_f32_16x16x32_bf16 v[96:99], v[172:175], v[198:201], v[96:99]
	v_mfma_f32_16x16x32_bf16 v[84:87], v[144:147], v[206:209], v[84:87]
	v_mfma_f32_16x16x32_bf16 v[80:83], v[172:175], v[206:209], v[80:83]
	v_mfma_f32_16x16x32_bf16 v[68:71], v[144:147], v[214:217], v[68:71]
	v_mfma_f32_16x16x32_bf16 v[64:67], v[172:175], v[214:217], v[64:67]
	v_mfma_f32_16x16x32_bf16 v[116:119], v[148:151], v[194:197], v[116:119]
	v_mfma_f32_16x16x32_bf16 v[112:115], v[176:179], v[194:197], v[112:115]
	v_mfma_f32_16x16x32_bf16 v[100:103], v[148:151], v[202:205], v[100:103]
	v_mfma_f32_16x16x32_bf16 v[96:99], v[176:179], v[202:205], v[96:99]
	v_mfma_f32_16x16x32_bf16 v[84:87], v[148:151], v[210:213], v[84:87]
	v_mfma_f32_16x16x32_bf16 v[80:83], v[176:179], v[210:213], v[80:83]
	v_mfma_f32_16x16x32_bf16 v[68:71], v[148:151], v[218:221], v[68:71]
	v_mfma_f32_16x16x32_bf16 v[64:67], v[176:179], v[218:221], v[64:67]
	s_setprio 0
	s_barrier
	s_add_i32 s54, s82, s65
	v_lshl_add_u64 v[222:223], v[222:223], 0, s[28:29]
	s_mov_b32 m0, s54
	ds_read_b128 v[180:183], v191 offset:49152
	ds_read_b128 v[194:197], v191 offset:50176
	ds_read_b128 v[198:201], v191 offset:51200
	ds_read_b128 v[202:205], v191 offset:52224
	ds_read_b128 v[206:209], v191 offset:53248
	ds_read_b128 v[210:213], v191 offset:54272
	ds_read_b128 v[214:217], v191 offset:55296
	ds_read_b128 v[218:221], v191 offset:56320
	global_load_lds_dwordx4 v[222:223], off
	s_add_i32 m0, s54, 0x2000
	s_add_u32 s54, s58, 0xb0080
	v_lshl_add_u64 v[222:223], v[224:225], 0, s[28:29]
	s_addc_u32 s55, s59, 0
	s_add_i32 s58, s83, s65
	global_load_lds_dwordx4 v[222:223], off
	v_lshl_add_u64 v[222:223], s[54:55], 0, v[154:155]
	s_mov_b32 m0, s58
	s_nop 0
	global_load_lds_dwordx4 v[222:223], off
	v_lshl_add_u64 v[222:223], s[54:55], 0, v[162:163]
	s_add_i32 m0, s58, 0x2000
	s_nop 0
	global_load_lds_dwordx4 v[222:223], off
	v_lshl_add_u64 v[222:223], v[226:227], 0, s[28:29]
	s_mov_b32 m0, s3
	s_nop 0
	global_load_lds_dwordx4 v[222:223], off
	v_lshl_add_u64 v[222:223], v[228:229], 0, s[28:29]
	s_mov_b32 m0, s71
	s_nop 0
	global_load_lds_dwordx4 v[222:223], off
	s_waitcnt vmcnt(8)
	s_waitcnt lgkmcnt(0)
	s_barrier
	s_setprio 1
	s_waitcnt lgkmcnt(0)
	v_mfma_f32_16x16x32_bf16 v[60:63], v[128:131], v[180:183], v[60:63]
	v_mfma_f32_16x16x32_bf16 v[56:59], v[136:139], v[180:183], v[56:59]
	v_mfma_f32_16x16x32_bf16 v[44:47], v[128:131], v[198:201], v[44:47]
	v_mfma_f32_16x16x32_bf16 v[40:43], v[136:139], v[198:201], v[40:43]
	v_mfma_f32_16x16x32_bf16 v[28:31], v[128:131], v[206:209], v[28:31]
	v_mfma_f32_16x16x32_bf16 v[24:27], v[136:139], v[206:209], v[24:27]
	v_mfma_f32_16x16x32_bf16 v[12:15], v[128:131], v[214:217], v[12:15]
	v_mfma_f32_16x16x32_bf16 v[8:11], v[136:139], v[214:217], v[8:11]
	v_mfma_f32_16x16x32_bf16 v[60:63], v[132:135], v[194:197], v[60:63]
	v_mfma_f32_16x16x32_bf16 v[56:59], v[140:143], v[194:197], v[56:59]
	v_mfma_f32_16x16x32_bf16 v[44:47], v[132:135], v[202:205], v[44:47]
	v_mfma_f32_16x16x32_bf16 v[40:43], v[140:143], v[202:205], v[40:43]
	v_mfma_f32_16x16x32_bf16 v[28:31], v[132:135], v[210:213], v[28:31]
	v_mfma_f32_16x16x32_bf16 v[24:27], v[140:143], v[210:213], v[24:27]
	v_mfma_f32_16x16x32_bf16 v[12:15], v[132:135], v[218:221], v[12:15]
	v_mfma_f32_16x16x32_bf16 v[8:11], v[140:143], v[218:221], v[8:11]
	s_setprio 0
	s_setprio 1
	v_mfma_f32_16x16x32_bf16 v[52:55], v[144:147], v[180:183], v[52:55]
	v_mfma_f32_16x16x32_bf16 v[48:51], v[172:175], v[180:183], v[48:51]
	v_mfma_f32_16x16x32_bf16 v[36:39], v[144:147], v[198:201], v[36:39]
	v_mfma_f32_16x16x32_bf16 v[32:35], v[172:175], v[198:201], v[32:35]
	v_mfma_f32_16x16x32_bf16 v[20:23], v[144:147], v[206:209], v[20:23]
	v_mfma_f32_16x16x32_bf16 v[16:19], v[172:175], v[206:209], v[16:19]
	v_mfma_f32_16x16x32_bf16 v[4:7], v[144:147], v[214:217], v[4:7]
	v_mfma_f32_16x16x32_bf16 v[0:3], v[172:175], v[214:217], v[0:3]
	v_mfma_f32_16x16x32_bf16 v[52:55], v[148:151], v[194:197], v[52:55]
	v_mfma_f32_16x16x32_bf16 v[48:51], v[176:179], v[194:197], v[48:51]
	v_mfma_f32_16x16x32_bf16 v[36:39], v[148:151], v[202:205], v[36:39]
	v_mfma_f32_16x16x32_bf16 v[32:35], v[176:179], v[202:205], v[32:35]
	v_mfma_f32_16x16x32_bf16 v[20:23], v[148:151], v[210:213], v[20:23]
	v_mfma_f32_16x16x32_bf16 v[16:19], v[176:179], v[210:213], v[16:19]
	v_mfma_f32_16x16x32_bf16 v[4:7], v[148:151], v[218:221], v[4:7]
	v_mfma_f32_16x16x32_bf16 v[0:3], v[176:179], v[218:221], v[0:3]
	s_setprio 0
	s_barrier
	s_add_i32 s81, s81, 2
	s_add_u32 s79, s79, 0x100
	s_addc_u32 s80, s80, 0
	s_cmp_gt_u32 s81, 41
	s_mov_b64 s[54:55], s[56:57]

.LBB0_873:
	s_ashr_i32 s49, s48, 31
	s_lshl_b64 s[50:51], s[48:49], 19
	s_add_u32 s50, s35, s50
	s_addc_u32 s51, s60, s51
	s_and_b64 s[52:53], s[10:11], exec
	s_cselect_b32 s49, s51, s59
	s_cselect_b32 s80, s50, s58
	s_ashr_i32 s47, s46, 31
	s_lshl_b64 s[52:53], s[46:47], 19
	s_add_u32 s52, s61, s52
	s_addc_u32 s53, s62, s53
	s_and_b64 s[82:83], s[10:11], exec
	s_cselect_b32 s81, s53, s57
	s_cselect_b32 s82, s52, s56
	s_lshl_b32 s47, s54, 8
	v_add_u32_e32 v0, s47, v151
	s_add_u32 s83, s56, 0x100
	v_ashrrev_i32_e32 v1, 31, v0
	s_addc_u32 s84, s57, 0
	v_lshl_add_u64 v[144:145], v[0:1], 4, s[20:21]
	s_add_u32 s54, s58, 0x40080
	s_addc_u32 s55, s59, 0
	s_mov_b32 s85, -2
	s_mov_b64 s[56:57], 0
	v_add_u32_e32 v146, s73, v149
	ds_read_b128 v[162:165], v146
	ds_read_b128 v[166:169], v146 offset:1024
	ds_read_b128 v[170:173], v146 offset:2048
	ds_read_b128 v[174:177], v146 offset:3072
	v_add_u32_e32 v146, s74, v149
	ds_read_b128 v[178:181], v146
	ds_read_b128 v[186:189], v146 offset:1024
	ds_read_b128 v[190:193], v146 offset:2048
	ds_read_b128 v[194:197], v146 offset:3072
	s_add_u32 s58, s54, 0xfffc0080
	s_addc_u32 s59, s55, -1
	s_and_b64 s[56:57], s[56:57], exec
	s_cselect_b32 s59, s49, s59
	s_cselect_b32 s58, s80, s58
	s_cselect_b32 s57, s81, s84
	s_cselect_b32 s56, s82, s83
	v_lshl_add_u64 v[182:183], s[54:55], 0, v[138:139]
	s_add_i32 m0, s64, 0xc000
	ds_read_b128 v[198:201], v154
	ds_read_b128 v[202:205], v154 offset:1024
	ds_read_b128 v[206:209], v154 offset:2048
	ds_read_b128 v[210:213], v154 offset:3072
	ds_read_b128 v[214:217], v154 offset:4096
	ds_read_b128 v[218:221], v154 offset:5120
	ds_read_b128 v[222:225], v154 offset:6144
	ds_read_b128 v[226:229], v154 offset:7168
	global_load_lds_dwordx4 v[182:183], off
	v_lshl_add_u64 v[182:183], s[54:55], 0, v[136:137]
	s_add_i32 m0, s64, 0xe000
	s_nop 0
	global_load_lds_dwordx4 v[182:183], off
	s_waitcnt vmcnt(8)
	s_waitcnt lgkmcnt(0)
	s_barrier
	s_setprio 1
	s_waitcnt lgkmcnt(0)
	v_mfma_f32_16x16x32_bf16 v[124:127], v[162:165], v[198:201], 0
	v_mfma_f32_16x16x32_bf16 v[120:123], v[170:173], v[198:201], 0
	v_mfma_f32_16x16x32_bf16 v[112:115], v[162:165], v[206:209], 0
	v_mfma_f32_16x16x32_bf16 v[104:107], v[170:173], v[206:209], 0
	v_mfma_f32_16x16x32_bf16 v[96:99], v[162:165], v[214:217], 0
	v_mfma_f32_16x16x32_bf16 v[88:91], v[170:173], v[214:217], 0
	v_mfma_f32_16x16x32_bf16 v[80:83], v[162:165], v[222:225], 0
	v_mfma_f32_16x16x32_bf16 v[72:75], v[170:173], v[222:225], 0
	v_mfma_f32_16x16x32_bf16 v[124:127], v[166:169], v[202:205], v[124:127]
	v_mfma_f32_16x16x32_bf16 v[120:123], v[174:177], v[202:205], v[120:123]
	v_mfma_f32_16x16x32_bf16 v[112:115], v[166:169], v[210:213], v[112:115]
	v_mfma_f32_16x16x32_bf16 v[104:107], v[174:177], v[210:213], v[104:107]
	v_mfma_f32_16x16x32_bf16 v[96:99], v[166:169], v[218:221], v[96:99]
	v_mfma_f32_16x16x32_bf16 v[88:91], v[174:177], v[218:221], v[88:91]
	v_mfma_f32_16x16x32_bf16 v[80:83], v[166:169], v[226:229], v[80:83]
	v_mfma_f32_16x16x32_bf16 v[72:75], v[174:177], v[226:229], v[72:75]
	s_setprio 0
	s_setprio 1
	v_mfma_f32_16x16x32_bf16 v[116:119], v[178:181], v[198:201], 0
	v_mfma_f32_16x16x32_bf16 v[108:111], v[190:193], v[198:201], 0
	v_mfma_f32_16x16x32_bf16 v[100:103], v[178:181], v[206:209], 0
	v_mfma_f32_16x16x32_bf16 v[92:95], v[190:193], v[206:209], 0
	v_mfma_f32_16x16x32_bf16 v[84:87], v[178:181], v[214:217], 0
	v_mfma_f32_16x16x32_bf16 v[76:79], v[190:193], v[214:217], 0
	v_mfma_f32_16x16x32_bf16 v[68:71], v[178:181], v[222:225], 0
	v_mfma_f32_16x16x32_bf16 v[64:67], v[190:193], v[222:225], 0
	v_mfma_f32_16x16x32_bf16 v[116:119], v[186:189], v[202:205], v[116:119]
	v_mfma_f32_16x16x32_bf16 v[108:111], v[194:197], v[202:205], v[108:111]
	v_mfma_f32_16x16x32_bf16 v[100:103], v[186:189], v[210:213], v[100:103]
	v_mfma_f32_16x16x32_bf16 v[92:95], v[194:197], v[210:213], v[92:95]
	v_mfma_f32_16x16x32_bf16 v[84:87], v[186:189], v[218:221], v[84:87]
	v_mfma_f32_16x16x32_bf16 v[76:79], v[194:197], v[218:221], v[76:79]
	v_mfma_f32_16x16x32_bf16 v[68:71], v[186:189], v[226:229], v[68:71]
	v_mfma_f32_16x16x32_bf16 v[64:67], v[194:197], v[226:229], v[64:67]
	s_setprio 0
	s_barrier
	s_add_i32 s86, s73, s63
	v_lshl_add_u64 v[182:183], s[56:57], 0, v[130:131]
	s_mov_b32 m0, s86
	ds_read_b128 v[198:201], v154 offset:16384
	ds_read_b128 v[202:205], v154 offset:17408
	ds_read_b128 v[206:209], v154 offset:18432
	ds_read_b128 v[210:213], v154 offset:19456
	ds_read_b128 v[214:217], v154 offset:20480
	ds_read_b128 v[218:221], v154 offset:21504
	ds_read_b128 v[222:225], v154 offset:22528
	ds_read_b128 v[226:229], v154 offset:23552
	global_load_lds_dwordx4 v[182:183], off
	s_add_i32 m0, s86, 0x2000
	s_add_u32 s86, s56, 0x40000
	v_lshl_add_u64 v[230:231], s[56:57], 0, v[134:135]
	s_addc_u32 s87, s57, 0
	s_add_i32 s88, s74, s63
	global_load_lds_dwordx4 v[230:231], off
	v_lshl_add_u64 v[232:233], s[86:87], 0, v[130:131]
	s_mov_b32 m0, s88
	v_lshl_add_u64 v[234:235], s[58:59], 0, v[132:133]
	global_load_lds_dwordx4 v[232:233], off
	v_lshl_add_u64 v[232:233], s[86:87], 0, v[134:135]
	s_add_i32 m0, s88, 0x2000
	s_nop 0
	global_load_lds_dwordx4 v[232:233], off
	v_lshl_add_u64 v[232:233], s[58:59], 0, v[128:129]
	s_mov_b32 m0, s64
	s_nop 0
	global_load_lds_dwordx4 v[232:233], off
	s_mov_b32 m0, s65
	s_nop 0
	global_load_lds_dwordx4 v[234:235], off
	s_waitcnt vmcnt(8)
	s_waitcnt lgkmcnt(0)
	s_barrier
	s_setprio 1
	s_waitcnt lgkmcnt(0)
	v_mfma_f32_16x16x32_bf16 v[60:63], v[162:165], v[198:201], 0
	v_mfma_f32_16x16x32_bf16 v[56:59], v[170:173], v[198:201], 0
	v_mfma_f32_16x16x32_bf16 v[48:51], v[162:165], v[206:209], 0
	v_mfma_f32_16x16x32_bf16 v[40:43], v[170:173], v[206:209], 0
	v_mfma_f32_16x16x32_bf16 v[32:35], v[162:165], v[214:217], 0
	v_mfma_f32_16x16x32_bf16 v[24:27], v[170:173], v[214:217], 0
	v_mfma_f32_16x16x32_bf16 v[16:19], v[162:165], v[222:225], 0
	v_mfma_f32_16x16x32_bf16 v[8:11], v[170:173], v[222:225], 0
	v_mfma_f32_16x16x32_bf16 v[60:63], v[166:169], v[202:205], v[60:63]
	v_mfma_f32_16x16x32_bf16 v[56:59], v[174:177], v[202:205], v[56:59]
	v_mfma_f32_16x16x32_bf16 v[48:51], v[166:169], v[210:213], v[48:51]
	v_mfma_f32_16x16x32_bf16 v[40:43], v[174:177], v[210:213], v[40:43]
	v_mfma_f32_16x16x32_bf16 v[32:35], v[166:169], v[218:221], v[32:35]
	v_mfma_f32_16x16x32_bf16 v[24:27], v[174:177], v[218:221], v[24:27]
	v_mfma_f32_16x16x32_bf16 v[16:19], v[166:169], v[226:229], v[16:19]
	v_mfma_f32_16x16x32_bf16 v[8:11], v[174:177], v[226:229], v[8:11]
	s_setprio 0
	s_setprio 1
	v_mfma_f32_16x16x32_bf16 v[52:55], v[178:181], v[198:201], 0
	v_mfma_f32_16x16x32_bf16 v[44:47], v[190:193], v[198:201], 0
	v_mfma_f32_16x16x32_bf16 v[36:39], v[178:181], v[206:209], 0
	v_mfma_f32_16x16x32_bf16 v[28:31], v[190:193], v[206:209], 0
	v_mfma_f32_16x16x32_bf16 v[20:23], v[178:181], v[214:217], 0
	v_mfma_f32_16x16x32_bf16 v[12:15], v[190:193], v[214:217], 0
	v_mfma_f32_16x16x32_bf16 v[4:7], v[178:181], v[222:225], 0
	v_mfma_f32_16x16x32_bf16 v[0:3], v[190:193], v[222:225], 0
	v_mfma_f32_16x16x32_bf16 v[52:55], v[186:189], v[202:205], v[52:55]
	v_mfma_f32_16x16x32_bf16 v[44:47], v[194:197], v[202:205], v[44:47]
	v_mfma_f32_16x16x32_bf16 v[36:39], v[186:189], v[210:213], v[36:39]
	v_mfma_f32_16x16x32_bf16 v[28:31], v[194:197], v[210:213], v[28:31]
	v_mfma_f32_16x16x32_bf16 v[20:23], v[186:189], v[218:221], v[20:23]
	v_mfma_f32_16x16x32_bf16 v[12:15], v[194:197], v[218:221], v[12:15]
	v_mfma_f32_16x16x32_bf16 v[4:7], v[186:189], v[226:229], v[4:7]
	v_mfma_f32_16x16x32_bf16 v[0:3], v[194:197], v[226:229], v[0:3]
	s_setprio 0
	s_barrier
	s_add_i32 s86, 0, 0x18000
	v_add_u32_e32 v146, s86, v149
	s_add_i32 s87, 0, 0x1c000
	ds_read_b128 v[162:165], v146
	ds_read_b128 v[166:169], v146 offset:1024
	ds_read_b128 v[170:173], v146 offset:2048
	ds_read_b128 v[174:177], v146 offset:3072
	v_add_u32_e32 v146, s87, v149
	ds_read_b128 v[178:181], v146
	ds_read_b128 v[186:189], v146 offset:1024
	ds_read_b128 v[190:193], v146 offset:2048
	ds_read_b128 v[194:197], v146 offset:3072
	s_add_u32 s58, s58, 0x40000
	s_addc_u32 s59, s59, 0
	s_mov_b32 m0, s66
	v_lshl_add_u64 v[236:237], s[58:59], 0, v[128:129]
	ds_read_b128 v[198:201], v154 offset:32768
	ds_read_b128 v[202:205], v154 offset:33792
	ds_read_b128 v[206:209], v154 offset:34816
	ds_read_b128 v[210:213], v154 offset:35840
	ds_read_b128 v[214:217], v154 offset:36864
	ds_read_b128 v[218:221], v154 offset:37888
	ds_read_b128 v[222:225], v154 offset:38912
	ds_read_b128 v[226:229], v154 offset:39936
	global_load_lds_dwordx4 v[236:237], off
	v_lshl_add_u64 v[236:237], s[58:59], 0, v[132:133]
	s_mov_b32 m0, s67
	s_nop 0
	global_load_lds_dwordx4 v[236:237], off
	s_waitcnt vmcnt(8)
	s_waitcnt lgkmcnt(0)
	s_barrier
	s_setprio 1
	s_waitcnt lgkmcnt(0)
	v_mfma_f32_16x16x32_bf16 v[124:127], v[162:165], v[198:201], v[124:127]
	v_mfma_f32_16x16x32_bf16 v[120:123], v[170:173], v[198:201], v[120:123]
	v_mfma_f32_16x16x32_bf16 v[112:115], v[162:165], v[206:209], v[112:115]
	v_mfma_f32_16x16x32_bf16 v[104:107], v[170:173], v[206:209], v[104:107]
	v_mfma_f32_16x16x32_bf16 v[96:99], v[162:165], v[214:217], v[96:99]
	v_mfma_f32_16x16x32_bf16 v[88:91], v[170:173], v[214:217], v[88:91]
	v_mfma_f32_16x16x32_bf16 v[80:83], v[162:165], v[222:225], v[80:83]
	v_mfma_f32_16x16x32_bf16 v[72:75], v[170:173], v[222:225], v[72:75]
	v_mfma_f32_16x16x32_bf16 v[124:127], v[166:169], v[202:205], v[124:127]
	v_mfma_f32_16x16x32_bf16 v[120:123], v[174:177], v[202:205], v[120:123]
	v_mfma_f32_16x16x32_bf16 v[112:115], v[166:169], v[210:213], v[112:115]
	v_mfma_f32_16x16x32_bf16 v[104:107], v[174:177], v[210:213], v[104:107]
	v_mfma_f32_16x16x32_bf16 v[96:99], v[166:169], v[218:221], v[96:99]
	v_mfma_f32_16x16x32_bf16 v[88:91], v[174:177], v[218:221], v[88:91]
	v_mfma_f32_16x16x32_bf16 v[80:83], v[166:169], v[226:229], v[80:83]
	v_mfma_f32_16x16x32_bf16 v[72:75], v[174:177], v[226:229], v[72:75]
	s_setprio 0
	s_setprio 1
	v_mfma_f32_16x16x32_bf16 v[116:119], v[178:181], v[198:201], v[116:119]
	v_mfma_f32_16x16x32_bf16 v[108:111], v[190:193], v[198:201], v[108:111]
	v_mfma_f32_16x16x32_bf16 v[100:103], v[178:181], v[206:209], v[100:103]
	v_mfma_f32_16x16x32_bf16 v[92:95], v[190:193], v[206:209], v[92:95]
	v_mfma_f32_16x16x32_bf16 v[84:87], v[178:181], v[214:217], v[84:87]
	v_mfma_f32_16x16x32_bf16 v[76:79], v[190:193], v[214:217], v[76:79]
	v_mfma_f32_16x16x32_bf16 v[68:71], v[178:181], v[222:225], v[68:71]
	v_mfma_f32_16x16x32_bf16 v[64:67], v[190:193], v[222:225], v[64:67]
	v_mfma_f32_16x16x32_bf16 v[116:119], v[186:189], v[202:205], v[116:119]
	v_mfma_f32_16x16x32_bf16 v[108:111], v[194:197], v[202:205], v[108:111]
	v_mfma_f32_16x16x32_bf16 v[100:103], v[186:189], v[210:213], v[100:103]
	v_mfma_f32_16x16x32_bf16 v[92:95], v[194:197], v[210:213], v[92:95]
	v_mfma_f32_16x16x32_bf16 v[84:87], v[186:189], v[218:221], v[84:87]
	v_mfma_f32_16x16x32_bf16 v[76:79], v[194:197], v[218:221], v[76:79]
	v_mfma_f32_16x16x32_bf16 v[68:71], v[186:189], v[226:229], v[68:71]
	v_mfma_f32_16x16x32_bf16 v[64:67], v[194:197], v[226:229], v[64:67]
	s_setprio 0
	s_barrier
	s_add_i32 s58, s86, s63
	v_lshl_add_u64 v[182:183], v[182:183], 0, s[22:23]
	s_mov_b32 m0, s58
	ds_read_b128 v[198:201], v154 offset:49152
	ds_read_b128 v[202:205], v154 offset:50176
	ds_read_b128 v[206:209], v154 offset:51200
	ds_read_b128 v[210:213], v154 offset:52224
	ds_read_b128 v[214:217], v154 offset:53248
	ds_read_b128 v[218:221], v154 offset:54272
	ds_read_b128 v[222:225], v154 offset:55296
	ds_read_b128 v[226:229], v154 offset:56320
	global_load_lds_dwordx4 v[182:183], off
	s_add_i32 m0, s58, 0x2000
	s_add_u32 s56, s56, 0x40080
	v_lshl_add_u64 v[182:183], v[230:231], 0, s[22:23]
	s_addc_u32 s57, s57, 0
	s_add_i32 s58, s87, s63
	global_load_lds_dwordx4 v[182:183], off
	v_lshl_add_u64 v[182:183], s[56:57], 0, v[130:131]
	s_mov_b32 m0, s58
	s_nop 0
	global_load_lds_dwordx4 v[182:183], off
	v_lshl_add_u64 v[182:183], s[56:57], 0, v[134:135]
	s_add_i32 m0, s58, 0x2000
	s_nop 0
	global_load_lds_dwordx4 v[182:183], off
	v_lshl_add_u64 v[182:183], v[232:233], 0, s[22:23]
	s_mov_b32 m0, s69
	s_nop 0
	global_load_lds_dwordx4 v[182:183], off
	v_lshl_add_u64 v[182:183], v[234:235], 0, s[22:23]
	s_mov_b32 m0, s70
	s_nop 0
	global_load_lds_dwordx4 v[182:183], off
	s_waitcnt vmcnt(8)
	s_waitcnt lgkmcnt(0)
	s_barrier
	s_setprio 1
	s_waitcnt lgkmcnt(0)
	v_mfma_f32_16x16x32_bf16 v[60:63], v[162:165], v[198:201], v[60:63]
	v_mfma_f32_16x16x32_bf16 v[56:59], v[170:173], v[198:201], v[56:59]
	v_mfma_f32_16x16x32_bf16 v[48:51], v[162:165], v[206:209], v[48:51]
	v_mfma_f32_16x16x32_bf16 v[40:43], v[170:173], v[206:209], v[40:43]
	v_mfma_f32_16x16x32_bf16 v[32:35], v[162:165], v[214:217], v[32:35]
	v_mfma_f32_16x16x32_bf16 v[24:27], v[170:173], v[214:217], v[24:27]
	v_mfma_f32_16x16x32_bf16 v[16:19], v[162:165], v[222:225], v[16:19]
	v_mfma_f32_16x16x32_bf16 v[8:11], v[170:173], v[222:225], v[8:11]
	v_mfma_f32_16x16x32_bf16 v[60:63], v[166:169], v[202:205], v[60:63]
	v_mfma_f32_16x16x32_bf16 v[56:59], v[174:177], v[202:205], v[56:59]
	v_mfma_f32_16x16x32_bf16 v[48:51], v[166:169], v[210:213], v[48:51]
	v_mfma_f32_16x16x32_bf16 v[40:43], v[174:177], v[210:213], v[40:43]
	v_mfma_f32_16x16x32_bf16 v[32:35], v[166:169], v[218:221], v[32:35]
	v_mfma_f32_16x16x32_bf16 v[24:27], v[174:177], v[218:221], v[24:27]
	v_mfma_f32_16x16x32_bf16 v[16:19], v[166:169], v[226:229], v[16:19]
	v_mfma_f32_16x16x32_bf16 v[8:11], v[174:177], v[226:229], v[8:11]
	s_setprio 0
	s_setprio 1
	v_mfma_f32_16x16x32_bf16 v[52:55], v[178:181], v[198:201], v[52:55]
	v_mfma_f32_16x16x32_bf16 v[44:47], v[190:193], v[198:201], v[44:47]
	v_mfma_f32_16x16x32_bf16 v[36:39], v[178:181], v[206:209], v[36:39]
	v_mfma_f32_16x16x32_bf16 v[28:31], v[190:193], v[206:209], v[28:31]
	v_mfma_f32_16x16x32_bf16 v[20:23], v[178:181], v[214:217], v[20:23]
	v_mfma_f32_16x16x32_bf16 v[12:15], v[190:193], v[214:217], v[12:15]
	v_mfma_f32_16x16x32_bf16 v[4:7], v[178:181], v[222:225], v[4:7]
	v_mfma_f32_16x16x32_bf16 v[0:3], v[190:193], v[222:225], v[0:3]
	v_mfma_f32_16x16x32_bf16 v[52:55], v[186:189], v[202:205], v[52:55]
	v_mfma_f32_16x16x32_bf16 v[44:47], v[194:197], v[202:205], v[44:47]
	v_mfma_f32_16x16x32_bf16 v[36:39], v[186:189], v[210:213], v[36:39]
	v_mfma_f32_16x16x32_bf16 v[28:31], v[194:197], v[210:213], v[28:31]
	v_mfma_f32_16x16x32_bf16 v[20:23], v[186:189], v[218:221], v[20:23]
	v_mfma_f32_16x16x32_bf16 v[12:15], v[194:197], v[218:221], v[12:15]
	v_mfma_f32_16x16x32_bf16 v[4:7], v[186:189], v[226:229], v[4:7]
	v_mfma_f32_16x16x32_bf16 v[0:3], v[194:197], v[226:229], v[0:3]
	s_setprio 0
	s_barrier
	s_add_i32 s85, s85, 2
	s_add_u32 s83, s83, 0x100
	s_addc_u32 s84, s84, 0
	s_add_u32 s54, s54, 0x100
	s_addc_u32 s55, s55, 0
	s_branch .LBB0_875

.LBB0_1010:
	s_ashr_i32 s51, s50, 31
	s_lshl_b64 s[52:53], s[50:51], 19
	s_add_u32 s52, s33, s52
	s_addc_u32 s53, s35, s53
	s_and_b64 s[54:55], s[12:13], exec
	s_cselect_b32 s15, s53, s61
	s_cselect_b32 s51, s52, s60
	s_ashr_i32 s49, s48, 31
	s_lshl_b64 s[54:55], s[48:49], 19
	s_add_u32 s54, s64, s54
	s_addc_u32 s55, s65, s55
	s_and_b64 s[62:63], s[12:13], exec
	s_cselect_b32 s49, s55, s59
	s_cselect_b32 s57, s54, s58
	s_add_u32 s78, s58, 0x100
	s_addc_u32 s79, s59, 0
	s_add_u32 s58, s60, 0x40080
	s_addc_u32 s59, s61, 0
	s_mov_b32 s80, -2
	s_waitcnt lgkmcnt(0)
	ds_read_b128 v[128:131], v188
	ds_read_b128 v[132:135], v188 offset:1024
	ds_read_b128 v[136:139], v188 offset:2048
	ds_read_b128 v[140:143], v188 offset:3072
	ds_read_b128 v[144:147], v189
	ds_read_b128 v[148:151], v189 offset:1024
	ds_read_b128 v[172:175], v189 offset:2048
	ds_read_b128 v[176:179], v189 offset:3072
	s_add_u32 s60, s58, 0xfffc0080
	s_addc_u32 s61, s59, -1
	s_cmp_eq_u32 s80, 12
	s_cselect_b32 s63, s15, s61
	s_cselect_b32 s62, s51, s60
	s_cselect_b32 s61, s49, s79
	s_cselect_b32 s60, s57, s78
	v_lshl_add_u64 v[220:221], s[58:59], 0, v[166:167]
	s_add_i32 m0, s67, 0xc000
	ds_read_b128 v[180:183], v190
	ds_read_b128 v[192:195], v190 offset:1024
	ds_read_b128 v[196:199], v190 offset:2048
	ds_read_b128 v[200:203], v190 offset:3072
	ds_read_b128 v[204:207], v190 offset:4096
	ds_read_b128 v[208:211], v190 offset:5120
	ds_read_b128 v[212:215], v190 offset:6144
	ds_read_b128 v[216:219], v190 offset:7168
	global_load_lds_dwordx4 v[220:221], off
	v_lshl_add_u64 v[220:221], s[58:59], 0, v[164:165]
	s_add_i32 m0, s67, 0xe000
	s_nop 0
	global_load_lds_dwordx4 v[220:221], off
	s_waitcnt vmcnt(8)
	s_waitcnt lgkmcnt(0)
	s_barrier
	s_setprio 1
	s_waitcnt lgkmcnt(0)
	v_mfma_f32_16x16x32_bf16 v[124:127], v[128:131], v[180:183], 0
	v_mfma_f32_16x16x32_bf16 v[120:123], v[136:139], v[180:183], 0
	v_mfma_f32_16x16x32_bf16 v[108:111], v[128:131], v[196:199], 0
	v_mfma_f32_16x16x32_bf16 v[104:107], v[136:139], v[196:199], 0
	v_mfma_f32_16x16x32_bf16 v[92:95], v[128:131], v[204:207], 0
	v_mfma_f32_16x16x32_bf16 v[88:91], v[136:139], v[204:207], 0
	v_mfma_f32_16x16x32_bf16 v[76:79], v[128:131], v[212:215], 0
	v_mfma_f32_16x16x32_bf16 v[72:75], v[136:139], v[212:215], 0
	v_mfma_f32_16x16x32_bf16 v[124:127], v[132:135], v[192:195], v[124:127]
	v_mfma_f32_16x16x32_bf16 v[120:123], v[140:143], v[192:195], v[120:123]
	v_mfma_f32_16x16x32_bf16 v[108:111], v[132:135], v[200:203], v[108:111]
	v_mfma_f32_16x16x32_bf16 v[104:107], v[140:143], v[200:203], v[104:107]
	v_mfma_f32_16x16x32_bf16 v[92:95], v[132:135], v[208:211], v[92:95]
	v_mfma_f32_16x16x32_bf16 v[88:91], v[140:143], v[208:211], v[88:91]
	v_mfma_f32_16x16x32_bf16 v[76:79], v[132:135], v[216:219], v[76:79]
	v_mfma_f32_16x16x32_bf16 v[72:75], v[140:143], v[216:219], v[72:75]
	s_setprio 0
	s_setprio 1
	v_mfma_f32_16x16x32_bf16 v[116:119], v[144:147], v[180:183], 0
	v_mfma_f32_16x16x32_bf16 v[112:115], v[172:175], v[180:183], 0
	v_mfma_f32_16x16x32_bf16 v[100:103], v[144:147], v[196:199], 0
	v_mfma_f32_16x16x32_bf16 v[96:99], v[172:175], v[196:199], 0
	v_mfma_f32_16x16x32_bf16 v[84:87], v[144:147], v[204:207], 0
	v_mfma_f32_16x16x32_bf16 v[80:83], v[172:175], v[204:207], 0
	v_mfma_f32_16x16x32_bf16 v[68:71], v[144:147], v[212:215], 0
	v_mfma_f32_16x16x32_bf16 v[64:67], v[172:175], v[212:215], 0
	v_mfma_f32_16x16x32_bf16 v[116:119], v[148:151], v[192:195], v[116:119]
	v_mfma_f32_16x16x32_bf16 v[112:115], v[176:179], v[192:195], v[112:115]
	v_mfma_f32_16x16x32_bf16 v[100:103], v[148:151], v[200:203], v[100:103]
	v_mfma_f32_16x16x32_bf16 v[96:99], v[176:179], v[200:203], v[96:99]
	v_mfma_f32_16x16x32_bf16 v[84:87], v[148:151], v[208:211], v[84:87]
	v_mfma_f32_16x16x32_bf16 v[80:83], v[176:179], v[208:211], v[80:83]
	v_mfma_f32_16x16x32_bf16 v[68:71], v[148:151], v[216:219], v[68:71]
	v_mfma_f32_16x16x32_bf16 v[64:67], v[176:179], v[216:219], v[64:67]
	s_setprio 0
	s_barrier
	s_add_i32 s81, s76, s66
	v_lshl_add_u64 v[220:221], s[60:61], 0, v[154:155]
	s_mov_b32 m0, s81
	ds_read_b128 v[180:183], v190 offset:16384
	ds_read_b128 v[192:195], v190 offset:17408
	ds_read_b128 v[196:199], v190 offset:18432
	ds_read_b128 v[200:203], v190 offset:19456
	ds_read_b128 v[204:207], v190 offset:20480
	ds_read_b128 v[208:211], v190 offset:21504
	ds_read_b128 v[212:215], v190 offset:22528
	ds_read_b128 v[216:219], v190 offset:23552
	global_load_lds_dwordx4 v[220:221], off
	s_add_i32 m0, s81, 0x2000
	s_add_u32 s82, s60, 0x40000
	v_lshl_add_u64 v[222:223], s[60:61], 0, v[162:163]
	s_addc_u32 s83, s61, 0
	s_add_i32 s81, s77, s66
	global_load_lds_dwordx4 v[222:223], off
	v_lshl_add_u64 v[224:225], s[82:83], 0, v[154:155]
	s_mov_b32 m0, s81
	v_lshl_add_u64 v[226:227], s[62:63], 0, v[160:161]
	global_load_lds_dwordx4 v[224:225], off
	v_lshl_add_u64 v[224:225], s[82:83], 0, v[162:163]
	s_add_i32 m0, s81, 0x2000
	s_nop 0
	global_load_lds_dwordx4 v[224:225], off
	v_lshl_add_u64 v[224:225], s[62:63], 0, v[152:153]
	s_mov_b32 m0, s67
	s_nop 0
	global_load_lds_dwordx4 v[224:225], off
	s_mov_b32 m0, s68
	s_nop 0
	global_load_lds_dwordx4 v[226:227], off
	s_waitcnt vmcnt(8)
	s_waitcnt lgkmcnt(0)
	s_barrier
	s_setprio 1
	s_waitcnt lgkmcnt(0)
	v_mfma_f32_16x16x32_bf16 v[60:63], v[128:131], v[180:183], 0
	v_mfma_f32_16x16x32_bf16 v[56:59], v[136:139], v[180:183], 0
	v_mfma_f32_16x16x32_bf16 v[44:47], v[128:131], v[196:199], 0
	v_mfma_f32_16x16x32_bf16 v[40:43], v[136:139], v[196:199], 0
	v_mfma_f32_16x16x32_bf16 v[28:31], v[128:131], v[204:207], 0
	v_mfma_f32_16x16x32_bf16 v[24:27], v[136:139], v[204:207], 0
	v_mfma_f32_16x16x32_bf16 v[12:15], v[128:131], v[212:215], 0
	v_mfma_f32_16x16x32_bf16 v[8:11], v[136:139], v[212:215], 0
	v_mfma_f32_16x16x32_bf16 v[60:63], v[132:135], v[192:195], v[60:63]
	v_mfma_f32_16x16x32_bf16 v[56:59], v[140:143], v[192:195], v[56:59]
	v_mfma_f32_16x16x32_bf16 v[44:47], v[132:135], v[200:203], v[44:47]
	v_mfma_f32_16x16x32_bf16 v[40:43], v[140:143], v[200:203], v[40:43]
	v_mfma_f32_16x16x32_bf16 v[28:31], v[132:135], v[208:211], v[28:31]
	v_mfma_f32_16x16x32_bf16 v[24:27], v[140:143], v[208:211], v[24:27]
	v_mfma_f32_16x16x32_bf16 v[12:15], v[132:135], v[216:219], v[12:15]
	v_mfma_f32_16x16x32_bf16 v[8:11], v[140:143], v[216:219], v[8:11]
	s_setprio 0
	s_setprio 1
	v_mfma_f32_16x16x32_bf16 v[52:55], v[144:147], v[180:183], 0
	v_mfma_f32_16x16x32_bf16 v[48:51], v[172:175], v[180:183], 0
	v_mfma_f32_16x16x32_bf16 v[36:39], v[144:147], v[196:199], 0
	v_mfma_f32_16x16x32_bf16 v[32:35], v[172:175], v[196:199], 0
	v_mfma_f32_16x16x32_bf16 v[20:23], v[144:147], v[204:207], 0
	v_mfma_f32_16x16x32_bf16 v[16:19], v[172:175], v[204:207], 0
	v_mfma_f32_16x16x32_bf16 v[4:7], v[144:147], v[212:215], 0
	v_mfma_f32_16x16x32_bf16 v[0:3], v[172:175], v[212:215], 0
	v_mfma_f32_16x16x32_bf16 v[52:55], v[148:151], v[192:195], v[52:55]
	v_mfma_f32_16x16x32_bf16 v[48:51], v[176:179], v[192:195], v[48:51]
	v_mfma_f32_16x16x32_bf16 v[36:39], v[148:151], v[200:203], v[36:39]
	v_mfma_f32_16x16x32_bf16 v[32:35], v[176:179], v[200:203], v[32:35]
	v_mfma_f32_16x16x32_bf16 v[20:23], v[148:151], v[208:211], v[20:23]
	v_mfma_f32_16x16x32_bf16 v[16:19], v[176:179], v[208:211], v[16:19]
	v_mfma_f32_16x16x32_bf16 v[4:7], v[148:151], v[216:219], v[4:7]
	v_mfma_f32_16x16x32_bf16 v[0:3], v[176:179], v[216:219], v[0:3]
	s_setprio 0
	s_barrier
	s_add_i32 s81, 0, 0x18000
	s_add_i32 s82, 0, 0x1c000
	v_add_u32_e32 v140, s81, v185
	v_add_u32_e32 v176, s82, v185
	ds_read_b128 v[128:131], v140
	ds_read_b128 v[132:135], v140 offset:1024
	ds_read_b128 v[136:139], v140 offset:2048
	ds_read_b128 v[140:143], v140 offset:3072
	ds_read_b128 v[144:147], v176
	ds_read_b128 v[148:151], v176 offset:1024
	ds_read_b128 v[172:175], v176 offset:2048
	ds_read_b128 v[176:179], v176 offset:3072
	s_add_u32 s62, s62, 0x40000
	s_addc_u32 s63, s63, 0
	s_mov_b32 m0, s69
	v_lshl_add_u64 v[228:229], s[62:63], 0, v[152:153]
	ds_read_b128 v[180:183], v190 offset:32768
	ds_read_b128 v[192:195], v190 offset:33792
	ds_read_b128 v[196:199], v190 offset:34816
	ds_read_b128 v[200:203], v190 offset:35840
	ds_read_b128 v[204:207], v190 offset:36864
	ds_read_b128 v[208:211], v190 offset:37888
	ds_read_b128 v[212:215], v190 offset:38912
	ds_read_b128 v[216:219], v190 offset:39936
	global_load_lds_dwordx4 v[228:229], off
	v_lshl_add_u64 v[228:229], s[62:63], 0, v[160:161]
	s_mov_b32 m0, s70
	s_nop 0
	global_load_lds_dwordx4 v[228:229], off
	s_waitcnt vmcnt(8)
	s_waitcnt lgkmcnt(0)
	s_barrier
	s_setprio 1
	s_waitcnt lgkmcnt(0)
	v_mfma_f32_16x16x32_bf16 v[124:127], v[128:131], v[180:183], v[124:127]
	v_mfma_f32_16x16x32_bf16 v[120:123], v[136:139], v[180:183], v[120:123]
	v_mfma_f32_16x16x32_bf16 v[108:111], v[128:131], v[196:199], v[108:111]
	v_mfma_f32_16x16x32_bf16 v[104:107], v[136:139], v[196:199], v[104:107]
	v_mfma_f32_16x16x32_bf16 v[92:95], v[128:131], v[204:207], v[92:95]
	v_mfma_f32_16x16x32_bf16 v[88:91], v[136:139], v[204:207], v[88:91]
	v_mfma_f32_16x16x32_bf16 v[76:79], v[128:131], v[212:215], v[76:79]
	v_mfma_f32_16x16x32_bf16 v[72:75], v[136:139], v[212:215], v[72:75]
	v_mfma_f32_16x16x32_bf16 v[124:127], v[132:135], v[192:195], v[124:127]
	v_mfma_f32_16x16x32_bf16 v[120:123], v[140:143], v[192:195], v[120:123]
	v_mfma_f32_16x16x32_bf16 v[108:111], v[132:135], v[200:203], v[108:111]
	v_mfma_f32_16x16x32_bf16 v[104:107], v[140:143], v[200:203], v[104:107]
	v_mfma_f32_16x16x32_bf16 v[92:95], v[132:135], v[208:211], v[92:95]
	v_mfma_f32_16x16x32_bf16 v[88:91], v[140:143], v[208:211], v[88:91]
	v_mfma_f32_16x16x32_bf16 v[76:79], v[132:135], v[216:219], v[76:79]
	v_mfma_f32_16x16x32_bf16 v[72:75], v[140:143], v[216:219], v[72:75]
	s_setprio 0
	s_setprio 1
	v_mfma_f32_16x16x32_bf16 v[116:119], v[144:147], v[180:183], v[116:119]
	v_mfma_f32_16x16x32_bf16 v[112:115], v[172:175], v[180:183], v[112:115]
	v_mfma_f32_16x16x32_bf16 v[100:103], v[144:147], v[196:199], v[100:103]
	v_mfma_f32_16x16x32_bf16 v[96:99], v[172:175], v[196:199], v[96:99]
	v_mfma_f32_16x16x32_bf16 v[84:87], v[144:147], v[204:207], v[84:87]
	v_mfma_f32_16x16x32_bf16 v[80:83], v[172:175], v[204:207], v[80:83]
	v_mfma_f32_16x16x32_bf16 v[68:71], v[144:147], v[212:215], v[68:71]
	v_mfma_f32_16x16x32_bf16 v[64:67], v[172:175], v[212:215], v[64:67]
	v_mfma_f32_16x16x32_bf16 v[116:119], v[148:151], v[192:195], v[116:119]
	v_mfma_f32_16x16x32_bf16 v[112:115], v[176:179], v[192:195], v[112:115]
	v_mfma_f32_16x16x32_bf16 v[100:103], v[148:151], v[200:203], v[100:103]
	v_mfma_f32_16x16x32_bf16 v[96:99], v[176:179], v[200:203], v[96:99]
	v_mfma_f32_16x16x32_bf16 v[84:87], v[148:151], v[208:211], v[84:87]
	v_mfma_f32_16x16x32_bf16 v[80:83], v[176:179], v[208:211], v[80:83]
	v_mfma_f32_16x16x32_bf16 v[68:71], v[148:151], v[216:219], v[68:71]
	v_mfma_f32_16x16x32_bf16 v[64:67], v[176:179], v[216:219], v[64:67]
	s_setprio 0
	s_barrier
	s_add_i32 s62, s81, s66
	v_lshl_add_u64 v[220:221], v[220:221], 0, s[26:27]
	s_mov_b32 m0, s62
	ds_read_b128 v[180:183], v190 offset:49152
	ds_read_b128 v[192:195], v190 offset:50176
	ds_read_b128 v[196:199], v190 offset:51200
	ds_read_b128 v[200:203], v190 offset:52224
	ds_read_b128 v[204:207], v190 offset:53248
	ds_read_b128 v[208:211], v190 offset:54272
	ds_read_b128 v[212:215], v190 offset:55296
	ds_read_b128 v[216:219], v190 offset:56320
	global_load_lds_dwordx4 v[220:221], off
	s_add_i32 m0, s62, 0x2000
	s_add_u32 s60, s60, 0x40080
	v_lshl_add_u64 v[220:221], v[222:223], 0, s[26:27]
	s_addc_u32 s61, s61, 0
	s_add_i32 s62, s82, s66
	global_load_lds_dwordx4 v[220:221], off
	v_lshl_add_u64 v[220:221], s[60:61], 0, v[154:155]
	s_mov_b32 m0, s62
	s_nop 0
	global_load_lds_dwordx4 v[220:221], off
	v_lshl_add_u64 v[220:221], s[60:61], 0, v[162:163]
	s_add_i32 m0, s62, 0x2000
	s_nop 0
	global_load_lds_dwordx4 v[220:221], off
	v_lshl_add_u64 v[220:221], v[224:225], 0, s[26:27]
	s_mov_b32 m0, s3
	s_nop 0
	global_load_lds_dwordx4 v[220:221], off
	v_lshl_add_u64 v[220:221], v[226:227], 0, s[26:27]
	s_mov_b32 m0, s72
	s_nop 0
	global_load_lds_dwordx4 v[220:221], off
	s_waitcnt vmcnt(8)
	s_waitcnt lgkmcnt(0)
	s_barrier
	s_setprio 1
	s_waitcnt lgkmcnt(0)
	v_mfma_f32_16x16x32_bf16 v[60:63], v[128:131], v[180:183], v[60:63]
	v_mfma_f32_16x16x32_bf16 v[56:59], v[136:139], v[180:183], v[56:59]
	v_mfma_f32_16x16x32_bf16 v[44:47], v[128:131], v[196:199], v[44:47]
	v_mfma_f32_16x16x32_bf16 v[40:43], v[136:139], v[196:199], v[40:43]
	v_mfma_f32_16x16x32_bf16 v[28:31], v[128:131], v[204:207], v[28:31]
	v_mfma_f32_16x16x32_bf16 v[24:27], v[136:139], v[204:207], v[24:27]
	v_mfma_f32_16x16x32_bf16 v[12:15], v[128:131], v[212:215], v[12:15]
	v_mfma_f32_16x16x32_bf16 v[8:11], v[136:139], v[212:215], v[8:11]
	v_mfma_f32_16x16x32_bf16 v[60:63], v[132:135], v[192:195], v[60:63]
	v_mfma_f32_16x16x32_bf16 v[56:59], v[140:143], v[192:195], v[56:59]
	v_mfma_f32_16x16x32_bf16 v[44:47], v[132:135], v[200:203], v[44:47]
	v_mfma_f32_16x16x32_bf16 v[40:43], v[140:143], v[200:203], v[40:43]
	v_mfma_f32_16x16x32_bf16 v[28:31], v[132:135], v[208:211], v[28:31]
	v_mfma_f32_16x16x32_bf16 v[24:27], v[140:143], v[208:211], v[24:27]
	v_mfma_f32_16x16x32_bf16 v[12:15], v[132:135], v[216:219], v[12:15]
	v_mfma_f32_16x16x32_bf16 v[8:11], v[140:143], v[216:219], v[8:11]
	s_setprio 0
	s_setprio 1
	v_mfma_f32_16x16x32_bf16 v[52:55], v[144:147], v[180:183], v[52:55]
	v_mfma_f32_16x16x32_bf16 v[48:51], v[172:175], v[180:183], v[48:51]
	v_mfma_f32_16x16x32_bf16 v[36:39], v[144:147], v[196:199], v[36:39]
	v_mfma_f32_16x16x32_bf16 v[32:35], v[172:175], v[196:199], v[32:35]
	v_mfma_f32_16x16x32_bf16 v[20:23], v[144:147], v[204:207], v[20:23]
	v_mfma_f32_16x16x32_bf16 v[16:19], v[172:175], v[204:207], v[16:19]
	v_mfma_f32_16x16x32_bf16 v[4:7], v[144:147], v[212:215], v[4:7]
	v_mfma_f32_16x16x32_bf16 v[0:3], v[172:175], v[212:215], v[0:3]
	v_mfma_f32_16x16x32_bf16 v[52:55], v[148:151], v[192:195], v[52:55]
	v_mfma_f32_16x16x32_bf16 v[48:51], v[176:179], v[192:195], v[48:51]
	v_mfma_f32_16x16x32_bf16 v[36:39], v[148:151], v[200:203], v[36:39]
	v_mfma_f32_16x16x32_bf16 v[32:35], v[176:179], v[200:203], v[32:35]
	v_mfma_f32_16x16x32_bf16 v[20:23], v[148:151], v[208:211], v[20:23]
	v_mfma_f32_16x16x32_bf16 v[16:19], v[176:179], v[208:211], v[16:19]
	v_mfma_f32_16x16x32_bf16 v[4:7], v[148:151], v[216:219], v[4:7]
	v_mfma_f32_16x16x32_bf16 v[0:3], v[176:179], v[216:219], v[0:3]
	s_setprio 0
	s_barrier
	s_add_i32 s80, s80, 2
	s_add_u32 s78, s78, 0x100
	s_addc_u32 s79, s79, 0
	s_add_u32 s58, s58, 0x100
	s_addc_u32 s59, s59, 0
	s_cmp_gt_u32 s80, 13

.LBB0_1096:
	s_ashr_i32 s25, s24, 31
	s_lshl_b64 s[26:27], s[24:25], 19
	s_add_u32 s26, s3, s26
	s_addc_u32 s27, s33, s27
	s_and_b64 s[28:29], s[6:7], exec
	s_cselect_b32 s25, s27, s47
	s_cselect_b32 s65, s26, s46
	s_ashr_i32 s23, s22, 31
	s_lshl_b64 s[28:29], s[22:23], 19
	s_add_u32 s28, s35, s28
	s_addc_u32 s29, s48, s29
	s_and_b64 s[66:67], s[6:7], exec
	s_cselect_b32 s66, s29, s45
	s_cselect_b32 s67, s28, s44
	s_lshl_b32 s23, s30, 8
	v_add_u32_e32 v0, s23, v148
	s_add_u32 s68, s44, 0x100
	v_ashrrev_i32_e32 v1, 31, v0
	s_addc_u32 s69, s45, 0
	v_lshl_add_u64 v[144:145], v[0:1], 4, s[12:13]
	s_add_u32 s30, s46, 0x40080
	s_addc_u32 s31, s47, 0
	s_mov_b32 s70, -2
	s_mov_b64 s[44:45], 0
	v_add_u32_e32 v153, s61, v147
	ds_read_b128 v[160:163], v153
	ds_read_b128 v[164:167], v153 offset:1024
	ds_read_b128 v[168:171], v153 offset:2048
	ds_read_b128 v[172:175], v153 offset:3072
	v_add_u32_e32 v153, s62, v147
	ds_read_b128 v[176:179], v153
	ds_read_b128 v[180:183], v153 offset:1024
	ds_read_b128 v[184:187], v153 offset:2048
	ds_read_b128 v[188:191], v153 offset:3072
	s_add_u32 s46, s30, 0xfffc0080
	s_addc_u32 s47, s31, -1
	s_and_b64 s[44:45], s[44:45], exec
	s_cselect_b32 s47, s25, s47
	s_cselect_b32 s46, s65, s46
	s_cselect_b32 s45, s66, s69
	s_cselect_b32 s44, s67, s68
	v_lshl_add_u64 v[154:155], s[30:31], 0, v[138:139]
	s_add_i32 m0, s52, 0xc000
	ds_read_b128 v[192:195], v150
	ds_read_b128 v[196:199], v150 offset:1024
	ds_read_b128 v[200:203], v150 offset:2048
	ds_read_b128 v[204:207], v150 offset:3072
	ds_read_b128 v[208:211], v150 offset:4096
	ds_read_b128 v[212:215], v150 offset:5120
	ds_read_b128 v[216:219], v150 offset:6144
	ds_read_b128 v[220:223], v150 offset:7168
	global_load_lds_dwordx4 v[154:155], off
	v_lshl_add_u64 v[154:155], s[30:31], 0, v[136:137]
	s_add_i32 m0, s52, 0xe000
	s_nop 0
	global_load_lds_dwordx4 v[154:155], off
	s_waitcnt vmcnt(8)
	s_waitcnt lgkmcnt(0)
	s_barrier
	s_setprio 1
	s_waitcnt lgkmcnt(0)
	v_mfma_f32_16x16x32_bf16 v[124:127], v[160:163], v[192:195], 0
	v_mfma_f32_16x16x32_bf16 v[116:119], v[168:171], v[192:195], 0
	v_mfma_f32_16x16x32_bf16 v[108:111], v[160:163], v[200:203], 0
	v_mfma_f32_16x16x32_bf16 v[100:103], v[168:171], v[200:203], 0
	v_mfma_f32_16x16x32_bf16 v[92:95], v[160:163], v[208:211], 0
	v_mfma_f32_16x16x32_bf16 v[84:87], v[168:171], v[208:211], 0
	v_mfma_f32_16x16x32_bf16 v[76:79], v[160:163], v[216:219], 0
	v_mfma_f32_16x16x32_bf16 v[68:71], v[168:171], v[216:219], 0
	v_mfma_f32_16x16x32_bf16 v[124:127], v[164:167], v[196:199], v[124:127]
	v_mfma_f32_16x16x32_bf16 v[116:119], v[172:175], v[196:199], v[116:119]
	v_mfma_f32_16x16x32_bf16 v[108:111], v[164:167], v[204:207], v[108:111]
	v_mfma_f32_16x16x32_bf16 v[100:103], v[172:175], v[204:207], v[100:103]
	v_mfma_f32_16x16x32_bf16 v[92:95], v[164:167], v[212:215], v[92:95]
	v_mfma_f32_16x16x32_bf16 v[84:87], v[172:175], v[212:215], v[84:87]
	v_mfma_f32_16x16x32_bf16 v[76:79], v[164:167], v[220:223], v[76:79]
	v_mfma_f32_16x16x32_bf16 v[68:71], v[172:175], v[220:223], v[68:71]
	s_setprio 0
	s_setprio 1
	v_mfma_f32_16x16x32_bf16 v[120:123], v[176:179], v[192:195], 0
	v_mfma_f32_16x16x32_bf16 v[112:115], v[184:187], v[192:195], 0
	v_mfma_f32_16x16x32_bf16 v[104:107], v[176:179], v[200:203], 0
	v_mfma_f32_16x16x32_bf16 v[96:99], v[184:187], v[200:203], 0
	v_mfma_f32_16x16x32_bf16 v[88:91], v[176:179], v[208:211], 0
	v_mfma_f32_16x16x32_bf16 v[80:83], v[184:187], v[208:211], 0
	v_mfma_f32_16x16x32_bf16 v[72:75], v[176:179], v[216:219], 0
	v_mfma_f32_16x16x32_bf16 v[64:67], v[184:187], v[216:219], 0
	v_mfma_f32_16x16x32_bf16 v[120:123], v[180:183], v[196:199], v[120:123]
	v_mfma_f32_16x16x32_bf16 v[112:115], v[188:191], v[196:199], v[112:115]
	v_mfma_f32_16x16x32_bf16 v[104:107], v[180:183], v[204:207], v[104:107]
	v_mfma_f32_16x16x32_bf16 v[96:99], v[188:191], v[204:207], v[96:99]
	v_mfma_f32_16x16x32_bf16 v[88:91], v[180:183], v[212:215], v[88:91]
	v_mfma_f32_16x16x32_bf16 v[80:83], v[188:191], v[212:215], v[80:83]
	v_mfma_f32_16x16x32_bf16 v[72:75], v[180:183], v[220:223], v[72:75]
	v_mfma_f32_16x16x32_bf16 v[64:67], v[188:191], v[220:223], v[64:67]
	s_setprio 0
	s_barrier
	s_add_i32 s71, s61, s49
	v_lshl_add_u64 v[154:155], s[44:45], 0, v[132:133]
	s_mov_b32 m0, s71
	ds_read_b128 v[192:195], v150 offset:16384
	ds_read_b128 v[196:199], v150 offset:17408
	ds_read_b128 v[200:203], v150 offset:18432
	ds_read_b128 v[204:207], v150 offset:19456
	ds_read_b128 v[208:211], v150 offset:20480
	ds_read_b128 v[212:215], v150 offset:21504
	ds_read_b128 v[216:219], v150 offset:22528
	ds_read_b128 v[220:223], v150 offset:23552
	global_load_lds_dwordx4 v[154:155], off
	s_add_i32 m0, s71, 0x2000
	s_add_u32 s72, s44, 0x40000
	v_lshl_add_u64 v[224:225], s[44:45], 0, v[128:129]
	s_addc_u32 s73, s45, 0
	s_add_i32 s71, s62, s49
	global_load_lds_dwordx4 v[224:225], off
	v_lshl_add_u64 v[226:227], s[72:73], 0, v[132:133]
	s_mov_b32 m0, s71
	v_lshl_add_u64 v[228:229], s[46:47], 0, v[130:131]
	global_load_lds_dwordx4 v[226:227], off
	v_lshl_add_u64 v[226:227], s[72:73], 0, v[128:129]
	s_add_i32 m0, s71, 0x2000
	s_nop 0
	global_load_lds_dwordx4 v[226:227], off
	v_lshl_add_u64 v[226:227], s[46:47], 0, v[134:135]
	s_mov_b32 m0, s52
	s_nop 0
	global_load_lds_dwordx4 v[226:227], off
	s_mov_b32 m0, s53
	s_nop 0
	global_load_lds_dwordx4 v[228:229], off
	s_waitcnt vmcnt(8)
	s_waitcnt lgkmcnt(0)
	s_barrier
	s_setprio 1
	s_waitcnt lgkmcnt(0)
	v_mfma_f32_16x16x32_bf16 v[60:63], v[160:163], v[192:195], 0
	v_mfma_f32_16x16x32_bf16 v[52:55], v[168:171], v[192:195], 0
	v_mfma_f32_16x16x32_bf16 v[44:47], v[160:163], v[200:203], 0
	v_mfma_f32_16x16x32_bf16 v[36:39], v[168:171], v[200:203], 0
	v_mfma_f32_16x16x32_bf16 v[28:31], v[160:163], v[208:211], 0
	v_mfma_f32_16x16x32_bf16 v[20:23], v[168:171], v[208:211], 0
	v_mfma_f32_16x16x32_bf16 v[12:15], v[160:163], v[216:219], 0
	v_mfma_f32_16x16x32_bf16 v[4:7], v[168:171], v[216:219], 0
	v_mfma_f32_16x16x32_bf16 v[60:63], v[164:167], v[196:199], v[60:63]
	v_mfma_f32_16x16x32_bf16 v[52:55], v[172:175], v[196:199], v[52:55]
	v_mfma_f32_16x16x32_bf16 v[44:47], v[164:167], v[204:207], v[44:47]
	v_mfma_f32_16x16x32_bf16 v[36:39], v[172:175], v[204:207], v[36:39]
	v_mfma_f32_16x16x32_bf16 v[28:31], v[164:167], v[212:215], v[28:31]
	v_mfma_f32_16x16x32_bf16 v[20:23], v[172:175], v[212:215], v[20:23]
	v_mfma_f32_16x16x32_bf16 v[12:15], v[164:167], v[220:223], v[12:15]
	v_mfma_f32_16x16x32_bf16 v[4:7], v[172:175], v[220:223], v[4:7]
	s_setprio 0
	s_setprio 1
	v_mfma_f32_16x16x32_bf16 v[56:59], v[176:179], v[192:195], 0
	v_mfma_f32_16x16x32_bf16 v[48:51], v[184:187], v[192:195], 0
	v_mfma_f32_16x16x32_bf16 v[40:43], v[176:179], v[200:203], 0
	v_mfma_f32_16x16x32_bf16 v[32:35], v[184:187], v[200:203], 0
	v_mfma_f32_16x16x32_bf16 v[24:27], v[176:179], v[208:211], 0
	v_mfma_f32_16x16x32_bf16 v[16:19], v[184:187], v[208:211], 0
	v_mfma_f32_16x16x32_bf16 v[8:11], v[176:179], v[216:219], 0
	v_mfma_f32_16x16x32_bf16 v[0:3], v[184:187], v[216:219], 0
	v_mfma_f32_16x16x32_bf16 v[56:59], v[180:183], v[196:199], v[56:59]
	v_mfma_f32_16x16x32_bf16 v[48:51], v[188:191], v[196:199], v[48:51]
	v_mfma_f32_16x16x32_bf16 v[40:43], v[180:183], v[204:207], v[40:43]
	v_mfma_f32_16x16x32_bf16 v[32:35], v[188:191], v[204:207], v[32:35]
	v_mfma_f32_16x16x32_bf16 v[24:27], v[180:183], v[212:215], v[24:27]
	v_mfma_f32_16x16x32_bf16 v[16:19], v[188:191], v[212:215], v[16:19]
	v_mfma_f32_16x16x32_bf16 v[8:11], v[180:183], v[220:223], v[8:11]
	v_mfma_f32_16x16x32_bf16 v[0:3], v[188:191], v[220:223], v[0:3]
	s_setprio 0
	s_barrier
	s_add_i32 s71, 0, 0x18000
	v_add_u32_e32 v153, s71, v147
	s_add_i32 s72, 0, 0x1c000
	ds_read_b128 v[160:163], v153
	ds_read_b128 v[164:167], v153 offset:1024
	ds_read_b128 v[168:171], v153 offset:2048
	ds_read_b128 v[172:175], v153 offset:3072
	v_add_u32_e32 v153, s72, v147
	ds_read_b128 v[176:179], v153
	ds_read_b128 v[180:183], v153 offset:1024
	ds_read_b128 v[184:187], v153 offset:2048
	ds_read_b128 v[188:191], v153 offset:3072
	s_add_u32 s46, s46, 0x40000
	s_addc_u32 s47, s47, 0
	s_mov_b32 m0, s54
	v_lshl_add_u64 v[230:231], s[46:47], 0, v[134:135]
	ds_read_b128 v[192:195], v150 offset:32768
	ds_read_b128 v[196:199], v150 offset:33792
	ds_read_b128 v[200:203], v150 offset:34816
	ds_read_b128 v[204:207], v150 offset:35840
	ds_read_b128 v[208:211], v150 offset:36864
	ds_read_b128 v[212:215], v150 offset:37888
	ds_read_b128 v[216:219], v150 offset:38912
	ds_read_b128 v[220:223], v150 offset:39936
	global_load_lds_dwordx4 v[230:231], off
	v_lshl_add_u64 v[230:231], s[46:47], 0, v[130:131]
	s_mov_b32 m0, s55
	s_nop 0
	global_load_lds_dwordx4 v[230:231], off
	s_waitcnt vmcnt(8)
	s_waitcnt lgkmcnt(0)
	s_barrier
	s_setprio 1
	s_waitcnt lgkmcnt(0)
	v_mfma_f32_16x16x32_bf16 v[124:127], v[160:163], v[192:195], v[124:127]
	v_mfma_f32_16x16x32_bf16 v[116:119], v[168:171], v[192:195], v[116:119]
	v_mfma_f32_16x16x32_bf16 v[108:111], v[160:163], v[200:203], v[108:111]
	v_mfma_f32_16x16x32_bf16 v[100:103], v[168:171], v[200:203], v[100:103]
	v_mfma_f32_16x16x32_bf16 v[92:95], v[160:163], v[208:211], v[92:95]
	v_mfma_f32_16x16x32_bf16 v[84:87], v[168:171], v[208:211], v[84:87]
	v_mfma_f32_16x16x32_bf16 v[76:79], v[160:163], v[216:219], v[76:79]
	v_mfma_f32_16x16x32_bf16 v[68:71], v[168:171], v[216:219], v[68:71]
	v_mfma_f32_16x16x32_bf16 v[124:127], v[164:167], v[196:199], v[124:127]
	v_mfma_f32_16x16x32_bf16 v[116:119], v[172:175], v[196:199], v[116:119]
	v_mfma_f32_16x16x32_bf16 v[108:111], v[164:167], v[204:207], v[108:111]
	v_mfma_f32_16x16x32_bf16 v[100:103], v[172:175], v[204:207], v[100:103]
	v_mfma_f32_16x16x32_bf16 v[92:95], v[164:167], v[212:215], v[92:95]
	v_mfma_f32_16x16x32_bf16 v[84:87], v[172:175], v[212:215], v[84:87]
	v_mfma_f32_16x16x32_bf16 v[76:79], v[164:167], v[220:223], v[76:79]
	v_mfma_f32_16x16x32_bf16 v[68:71], v[172:175], v[220:223], v[68:71]
	s_setprio 0
	s_setprio 1
	v_mfma_f32_16x16x32_bf16 v[120:123], v[176:179], v[192:195], v[120:123]
	v_mfma_f32_16x16x32_bf16 v[112:115], v[184:187], v[192:195], v[112:115]
	v_mfma_f32_16x16x32_bf16 v[104:107], v[176:179], v[200:203], v[104:107]
	v_mfma_f32_16x16x32_bf16 v[96:99], v[184:187], v[200:203], v[96:99]
	v_mfma_f32_16x16x32_bf16 v[88:91], v[176:179], v[208:211], v[88:91]
	v_mfma_f32_16x16x32_bf16 v[80:83], v[184:187], v[208:211], v[80:83]
	v_mfma_f32_16x16x32_bf16 v[72:75], v[176:179], v[216:219], v[72:75]
	v_mfma_f32_16x16x32_bf16 v[64:67], v[184:187], v[216:219], v[64:67]
	v_mfma_f32_16x16x32_bf16 v[120:123], v[180:183], v[196:199], v[120:123]
	v_mfma_f32_16x16x32_bf16 v[112:115], v[188:191], v[196:199], v[112:115]
	v_mfma_f32_16x16x32_bf16 v[104:107], v[180:183], v[204:207], v[104:107]
	v_mfma_f32_16x16x32_bf16 v[96:99], v[188:191], v[204:207], v[96:99]
	v_mfma_f32_16x16x32_bf16 v[88:91], v[180:183], v[212:215], v[88:91]
	v_mfma_f32_16x16x32_bf16 v[80:83], v[188:191], v[212:215], v[80:83]
	v_mfma_f32_16x16x32_bf16 v[72:75], v[180:183], v[220:223], v[72:75]
	v_mfma_f32_16x16x32_bf16 v[64:67], v[188:191], v[220:223], v[64:67]
	s_setprio 0
	s_barrier
	s_add_i32 s46, s71, s49
	v_lshl_add_u64 v[154:155], v[154:155], 0, s[14:15]
	s_mov_b32 m0, s46
	ds_read_b128 v[192:195], v150 offset:49152
	ds_read_b128 v[196:199], v150 offset:50176
	ds_read_b128 v[200:203], v150 offset:51200
	ds_read_b128 v[204:207], v150 offset:52224
	ds_read_b128 v[208:211], v150 offset:53248
	ds_read_b128 v[212:215], v150 offset:54272
	ds_read_b128 v[216:219], v150 offset:55296
	ds_read_b128 v[220:223], v150 offset:56320
	global_load_lds_dwordx4 v[154:155], off
	s_add_i32 m0, s46, 0x2000
	s_add_u32 s44, s44, 0x40080
	v_lshl_add_u64 v[154:155], v[224:225], 0, s[14:15]
	s_addc_u32 s45, s45, 0
	s_add_i32 s46, s72, s49
	global_load_lds_dwordx4 v[154:155], off
	v_lshl_add_u64 v[154:155], s[44:45], 0, v[132:133]
	s_mov_b32 m0, s46
	s_nop 0
	global_load_lds_dwordx4 v[154:155], off
	v_lshl_add_u64 v[154:155], s[44:45], 0, v[128:129]
	s_add_i32 m0, s46, 0x2000
	s_nop 0
	global_load_lds_dwordx4 v[154:155], off
	v_lshl_add_u64 v[154:155], v[226:227], 0, s[14:15]
	s_mov_b32 m0, s57
	s_nop 0
	global_load_lds_dwordx4 v[154:155], off
	v_lshl_add_u64 v[154:155], v[228:229], 0, s[14:15]
	s_mov_b32 m0, s58
	s_nop 0
	global_load_lds_dwordx4 v[154:155], off
	s_waitcnt vmcnt(8)
	s_waitcnt lgkmcnt(0)
	s_barrier
	s_setprio 1
	s_waitcnt lgkmcnt(0)
	v_mfma_f32_16x16x32_bf16 v[60:63], v[160:163], v[192:195], v[60:63]
	v_mfma_f32_16x16x32_bf16 v[52:55], v[168:171], v[192:195], v[52:55]
	v_mfma_f32_16x16x32_bf16 v[44:47], v[160:163], v[200:203], v[44:47]
	v_mfma_f32_16x16x32_bf16 v[36:39], v[168:171], v[200:203], v[36:39]
	v_mfma_f32_16x16x32_bf16 v[28:31], v[160:163], v[208:211], v[28:31]
	v_mfma_f32_16x16x32_bf16 v[20:23], v[168:171], v[208:211], v[20:23]
	v_mfma_f32_16x16x32_bf16 v[12:15], v[160:163], v[216:219], v[12:15]
	v_mfma_f32_16x16x32_bf16 v[4:7], v[168:171], v[216:219], v[4:7]
	v_mfma_f32_16x16x32_bf16 v[60:63], v[164:167], v[196:199], v[60:63]
	v_mfma_f32_16x16x32_bf16 v[52:55], v[172:175], v[196:199], v[52:55]
	v_mfma_f32_16x16x32_bf16 v[44:47], v[164:167], v[204:207], v[44:47]
	v_mfma_f32_16x16x32_bf16 v[36:39], v[172:175], v[204:207], v[36:39]
	v_mfma_f32_16x16x32_bf16 v[28:31], v[164:167], v[212:215], v[28:31]
	v_mfma_f32_16x16x32_bf16 v[20:23], v[172:175], v[212:215], v[20:23]
	v_mfma_f32_16x16x32_bf16 v[12:15], v[164:167], v[220:223], v[12:15]
	v_mfma_f32_16x16x32_bf16 v[4:7], v[172:175], v[220:223], v[4:7]
	s_setprio 0
	s_setprio 1
	v_mfma_f32_16x16x32_bf16 v[56:59], v[176:179], v[192:195], v[56:59]
	v_mfma_f32_16x16x32_bf16 v[48:51], v[184:187], v[192:195], v[48:51]
	v_mfma_f32_16x16x32_bf16 v[40:43], v[176:179], v[200:203], v[40:43]
	v_mfma_f32_16x16x32_bf16 v[32:35], v[184:187], v[200:203], v[32:35]
	v_mfma_f32_16x16x32_bf16 v[24:27], v[176:179], v[208:211], v[24:27]
	v_mfma_f32_16x16x32_bf16 v[16:19], v[184:187], v[208:211], v[16:19]
	v_mfma_f32_16x16x32_bf16 v[8:11], v[176:179], v[216:219], v[8:11]
	v_mfma_f32_16x16x32_bf16 v[0:3], v[184:187], v[216:219], v[0:3]
	v_mfma_f32_16x16x32_bf16 v[56:59], v[180:183], v[196:199], v[56:59]
	v_mfma_f32_16x16x32_bf16 v[48:51], v[188:191], v[196:199], v[48:51]
	v_mfma_f32_16x16x32_bf16 v[40:43], v[180:183], v[204:207], v[40:43]
	v_mfma_f32_16x16x32_bf16 v[32:35], v[188:191], v[204:207], v[32:35]
	v_mfma_f32_16x16x32_bf16 v[24:27], v[180:183], v[212:215], v[24:27]
	v_mfma_f32_16x16x32_bf16 v[16:19], v[188:191], v[212:215], v[16:19]
	v_mfma_f32_16x16x32_bf16 v[8:11], v[180:183], v[220:223], v[8:11]
	v_mfma_f32_16x16x32_bf16 v[0:3], v[188:191], v[220:223], v[0:3]
	s_setprio 0
	s_barrier
	s_add_i32 s70, s70, 2
	s_add_u32 s68, s68, 0x100
	s_addc_u32 s69, s69, 0
	s_add_u32 s30, s30, 0x100
	s_addc_u32 s31, s31, 0
	s_branch .LBB0_1098

.LBB0_1180:
	s_add_u32 s72, s50, 0x100
	s_addc_u32 s73, s51, 0
	s_mov_b32 s74, -2
	s_waitcnt lgkmcnt(0)
	ds_read_b128 v[128:131], v188
	ds_read_b128 v[132:135], v188 offset:1024
	ds_read_b128 v[136:139], v188 offset:2048
	ds_read_b128 v[140:143], v188 offset:3072
	ds_read_b128 v[144:147], v189
	ds_read_b128 v[148:151], v189 offset:1024
	ds_read_b128 v[172:175], v189 offset:2048
	ds_read_b128 v[176:179], v189 offset:3072
	s_add_u32 s50, s48, 0x100
	s_addc_u32 s51, s49, 0
	s_cmp_eq_u32 s74, 40
	s_cselect_b32 s55, s11, s51
	s_cselect_b32 s54, s10, s50
	s_cselect_b32 s53, s47, s73
	s_cselect_b32 s52, s46, s72
	v_lshl_add_u64 v[220:221], s[48:49], 0, v[166:167]
	s_add_i32 m0, s59, 0xc000
	ds_read_b128 v[180:183], v190
	ds_read_b128 v[192:195], v190 offset:1024
	ds_read_b128 v[196:199], v190 offset:2048
	ds_read_b128 v[200:203], v190 offset:3072
	ds_read_b128 v[204:207], v190 offset:4096
	ds_read_b128 v[208:211], v190 offset:5120
	ds_read_b128 v[212:215], v190 offset:6144
	ds_read_b128 v[216:219], v190 offset:7168
	global_load_lds_dwordx4 v[220:221], off
	v_lshl_add_u64 v[220:221], s[48:49], 0, v[164:165]
	s_add_i32 m0, s59, 0xe000
	s_nop 0
	global_load_lds_dwordx4 v[220:221], off
	s_waitcnt vmcnt(8)
	s_waitcnt lgkmcnt(0)
	s_barrier
	s_setprio 1
	s_waitcnt lgkmcnt(0)
	v_mfma_f32_16x16x32_bf16 v[124:127], v[128:131], v[180:183], 0
	v_mfma_f32_16x16x32_bf16 v[120:123], v[136:139], v[180:183], 0
	v_mfma_f32_16x16x32_bf16 v[108:111], v[128:131], v[196:199], 0
	v_mfma_f32_16x16x32_bf16 v[104:107], v[136:139], v[196:199], 0
	v_mfma_f32_16x16x32_bf16 v[92:95], v[128:131], v[204:207], 0
	v_mfma_f32_16x16x32_bf16 v[88:91], v[136:139], v[204:207], 0
	v_mfma_f32_16x16x32_bf16 v[76:79], v[128:131], v[212:215], 0
	v_mfma_f32_16x16x32_bf16 v[72:75], v[136:139], v[212:215], 0
	v_mfma_f32_16x16x32_bf16 v[124:127], v[132:135], v[192:195], v[124:127]
	v_mfma_f32_16x16x32_bf16 v[120:123], v[140:143], v[192:195], v[120:123]
	v_mfma_f32_16x16x32_bf16 v[108:111], v[132:135], v[200:203], v[108:111]
	v_mfma_f32_16x16x32_bf16 v[104:107], v[140:143], v[200:203], v[104:107]
	v_mfma_f32_16x16x32_bf16 v[92:95], v[132:135], v[208:211], v[92:95]
	v_mfma_f32_16x16x32_bf16 v[88:91], v[140:143], v[208:211], v[88:91]
	v_mfma_f32_16x16x32_bf16 v[76:79], v[132:135], v[216:219], v[76:79]
	v_mfma_f32_16x16x32_bf16 v[72:75], v[140:143], v[216:219], v[72:75]
	s_setprio 0
	s_setprio 1
	v_mfma_f32_16x16x32_bf16 v[116:119], v[144:147], v[180:183], 0
	v_mfma_f32_16x16x32_bf16 v[112:115], v[172:175], v[180:183], 0
	v_mfma_f32_16x16x32_bf16 v[100:103], v[144:147], v[196:199], 0
	v_mfma_f32_16x16x32_bf16 v[96:99], v[172:175], v[196:199], 0
	v_mfma_f32_16x16x32_bf16 v[84:87], v[144:147], v[204:207], 0
	v_mfma_f32_16x16x32_bf16 v[80:83], v[172:175], v[204:207], 0
	v_mfma_f32_16x16x32_bf16 v[68:71], v[144:147], v[212:215], 0
	v_mfma_f32_16x16x32_bf16 v[64:67], v[172:175], v[212:215], 0
	v_mfma_f32_16x16x32_bf16 v[116:119], v[148:151], v[192:195], v[116:119]
	v_mfma_f32_16x16x32_bf16 v[112:115], v[176:179], v[192:195], v[112:115]
	v_mfma_f32_16x16x32_bf16 v[100:103], v[148:151], v[200:203], v[100:103]
	v_mfma_f32_16x16x32_bf16 v[96:99], v[176:179], v[200:203], v[96:99]
	v_mfma_f32_16x16x32_bf16 v[84:87], v[148:151], v[208:211], v[84:87]
	v_mfma_f32_16x16x32_bf16 v[80:83], v[176:179], v[208:211], v[80:83]
	v_mfma_f32_16x16x32_bf16 v[68:71], v[148:151], v[216:219], v[68:71]
	v_mfma_f32_16x16x32_bf16 v[64:67], v[176:179], v[216:219], v[64:67]
	s_setprio 0
	s_barrier
	s_add_i32 s48, s68, s58
	v_lshl_add_u64 v[220:221], s[52:53], 0, v[154:155]
	s_mov_b32 m0, s48
	ds_read_b128 v[180:183], v190 offset:16384
	ds_read_b128 v[192:195], v190 offset:17408
	ds_read_b128 v[196:199], v190 offset:18432
	ds_read_b128 v[200:203], v190 offset:19456
	ds_read_b128 v[204:207], v190 offset:20480
	ds_read_b128 v[208:211], v190 offset:21504
	ds_read_b128 v[212:215], v190 offset:22528
	ds_read_b128 v[216:219], v190 offset:23552
	global_load_lds_dwordx4 v[220:221], off
	s_add_i32 m0, s48, 0x2000
	s_add_u32 s48, s52, 0xb0000
	v_lshl_add_u64 v[222:223], s[52:53], 0, v[162:163]
	s_addc_u32 s49, s53, 0
	s_add_i32 s75, s69, s58
	global_load_lds_dwordx4 v[222:223], off
	v_lshl_add_u64 v[224:225], s[48:49], 0, v[154:155]
	s_mov_b32 m0, s75
	v_lshl_add_u64 v[226:227], s[54:55], 0, v[160:161]
	global_load_lds_dwordx4 v[224:225], off
	v_lshl_add_u64 v[224:225], s[48:49], 0, v[162:163]
	s_add_i32 m0, s75, 0x2000
	s_nop 0
	global_load_lds_dwordx4 v[224:225], off
	v_lshl_add_u64 v[224:225], s[54:55], 0, v[152:153]
	s_mov_b32 m0, s59
	s_nop 0
	global_load_lds_dwordx4 v[224:225], off
	s_mov_b32 m0, s60
	s_nop 0
	global_load_lds_dwordx4 v[226:227], off
	s_waitcnt vmcnt(8)
	s_waitcnt lgkmcnt(0)
	s_barrier
	s_setprio 1
	s_waitcnt lgkmcnt(0)
	v_mfma_f32_16x16x32_bf16 v[60:63], v[128:131], v[180:183], 0
	v_mfma_f32_16x16x32_bf16 v[56:59], v[136:139], v[180:183], 0
	v_mfma_f32_16x16x32_bf16 v[44:47], v[128:131], v[196:199], 0
	v_mfma_f32_16x16x32_bf16 v[40:43], v[136:139], v[196:199], 0
	v_mfma_f32_16x16x32_bf16 v[28:31], v[128:131], v[204:207], 0
	v_mfma_f32_16x16x32_bf16 v[24:27], v[136:139], v[204:207], 0
	v_mfma_f32_16x16x32_bf16 v[12:15], v[128:131], v[212:215], 0
	v_mfma_f32_16x16x32_bf16 v[8:11], v[136:139], v[212:215], 0
	v_mfma_f32_16x16x32_bf16 v[60:63], v[132:135], v[192:195], v[60:63]
	v_mfma_f32_16x16x32_bf16 v[56:59], v[140:143], v[192:195], v[56:59]
	v_mfma_f32_16x16x32_bf16 v[44:47], v[132:135], v[200:203], v[44:47]
	v_mfma_f32_16x16x32_bf16 v[40:43], v[140:143], v[200:203], v[40:43]
	v_mfma_f32_16x16x32_bf16 v[28:31], v[132:135], v[208:211], v[28:31]
	v_mfma_f32_16x16x32_bf16 v[24:27], v[140:143], v[208:211], v[24:27]
	v_mfma_f32_16x16x32_bf16 v[12:15], v[132:135], v[216:219], v[12:15]
	v_mfma_f32_16x16x32_bf16 v[8:11], v[140:143], v[216:219], v[8:11]
	s_setprio 0
	s_setprio 1
	v_mfma_f32_16x16x32_bf16 v[52:55], v[144:147], v[180:183], 0
	v_mfma_f32_16x16x32_bf16 v[48:51], v[172:175], v[180:183], 0
	v_mfma_f32_16x16x32_bf16 v[36:39], v[144:147], v[196:199], 0
	v_mfma_f32_16x16x32_bf16 v[32:35], v[172:175], v[196:199], 0
	v_mfma_f32_16x16x32_bf16 v[20:23], v[144:147], v[204:207], 0
	v_mfma_f32_16x16x32_bf16 v[16:19], v[172:175], v[204:207], 0
	v_mfma_f32_16x16x32_bf16 v[4:7], v[144:147], v[212:215], 0
	v_mfma_f32_16x16x32_bf16 v[0:3], v[172:175], v[212:215], 0
	v_mfma_f32_16x16x32_bf16 v[52:55], v[148:151], v[192:195], v[52:55]
	v_mfma_f32_16x16x32_bf16 v[48:51], v[176:179], v[192:195], v[48:51]
	v_mfma_f32_16x16x32_bf16 v[36:39], v[148:151], v[200:203], v[36:39]
	v_mfma_f32_16x16x32_bf16 v[32:35], v[176:179], v[200:203], v[32:35]
	v_mfma_f32_16x16x32_bf16 v[20:23], v[148:151], v[208:211], v[20:23]
	v_mfma_f32_16x16x32_bf16 v[16:19], v[176:179], v[208:211], v[16:19]
	v_mfma_f32_16x16x32_bf16 v[4:7], v[148:151], v[216:219], v[4:7]
	v_mfma_f32_16x16x32_bf16 v[0:3], v[176:179], v[216:219], v[0:3]
	s_setprio 0
	s_barrier
	s_add_i32 s75, 0, 0x18000
	s_add_i32 s76, 0, 0x1c000
	v_add_u32_e32 v140, s75, v185
	v_add_u32_e32 v176, s76, v185
	ds_read_b128 v[128:131], v140
	ds_read_b128 v[132:135], v140 offset:1024
	ds_read_b128 v[136:139], v140 offset:2048
	ds_read_b128 v[140:143], v140 offset:3072
	ds_read_b128 v[144:147], v176
	ds_read_b128 v[148:151], v176 offset:1024
	ds_read_b128 v[172:175], v176 offset:2048
	ds_read_b128 v[176:179], v176 offset:3072
	s_add_u32 s48, s54, 0xb0000
	s_addc_u32 s49, s55, 0
	s_mov_b32 m0, s61
	v_lshl_add_u64 v[228:229], s[48:49], 0, v[152:153]
	ds_read_b128 v[180:183], v190 offset:32768
	ds_read_b128 v[192:195], v190 offset:33792
	ds_read_b128 v[196:199], v190 offset:34816
	ds_read_b128 v[200:203], v190 offset:35840
	ds_read_b128 v[204:207], v190 offset:36864
	ds_read_b128 v[208:211], v190 offset:37888
	ds_read_b128 v[212:215], v190 offset:38912
	ds_read_b128 v[216:219], v190 offset:39936
	global_load_lds_dwordx4 v[228:229], off
	v_lshl_add_u64 v[228:229], s[48:49], 0, v[160:161]
	s_mov_b32 m0, s62
	s_nop 0
	global_load_lds_dwordx4 v[228:229], off
	s_waitcnt vmcnt(8)
	s_waitcnt lgkmcnt(0)
	s_barrier
	s_setprio 1
	s_waitcnt lgkmcnt(0)
	v_mfma_f32_16x16x32_bf16 v[124:127], v[128:131], v[180:183], v[124:127]
	v_mfma_f32_16x16x32_bf16 v[120:123], v[136:139], v[180:183], v[120:123]
	v_mfma_f32_16x16x32_bf16 v[108:111], v[128:131], v[196:199], v[108:111]
	v_mfma_f32_16x16x32_bf16 v[104:107], v[136:139], v[196:199], v[104:107]
	v_mfma_f32_16x16x32_bf16 v[92:95], v[128:131], v[204:207], v[92:95]
	v_mfma_f32_16x16x32_bf16 v[88:91], v[136:139], v[204:207], v[88:91]
	v_mfma_f32_16x16x32_bf16 v[76:79], v[128:131], v[212:215], v[76:79]
	v_mfma_f32_16x16x32_bf16 v[72:75], v[136:139], v[212:215], v[72:75]
	v_mfma_f32_16x16x32_bf16 v[124:127], v[132:135], v[192:195], v[124:127]
	v_mfma_f32_16x16x32_bf16 v[120:123], v[140:143], v[192:195], v[120:123]
	v_mfma_f32_16x16x32_bf16 v[108:111], v[132:135], v[200:203], v[108:111]
	v_mfma_f32_16x16x32_bf16 v[104:107], v[140:143], v[200:203], v[104:107]
	v_mfma_f32_16x16x32_bf16 v[92:95], v[132:135], v[208:211], v[92:95]
	v_mfma_f32_16x16x32_bf16 v[88:91], v[140:143], v[208:211], v[88:91]
	v_mfma_f32_16x16x32_bf16 v[76:79], v[132:135], v[216:219], v[76:79]
	v_mfma_f32_16x16x32_bf16 v[72:75], v[140:143], v[216:219], v[72:75]
	s_setprio 0
	s_setprio 1
	v_mfma_f32_16x16x32_bf16 v[116:119], v[144:147], v[180:183], v[116:119]
	v_mfma_f32_16x16x32_bf16 v[112:115], v[172:175], v[180:183], v[112:115]
	v_mfma_f32_16x16x32_bf16 v[100:103], v[144:147], v[196:199], v[100:103]
	v_mfma_f32_16x16x32_bf16 v[96:99], v[172:175], v[196:199], v[96:99]
	v_mfma_f32_16x16x32_bf16 v[84:87], v[144:147], v[204:207], v[84:87]
	v_mfma_f32_16x16x32_bf16 v[80:83], v[172:175], v[204:207], v[80:83]
	v_mfma_f32_16x16x32_bf16 v[68:71], v[144:147], v[212:215], v[68:71]
	v_mfma_f32_16x16x32_bf16 v[64:67], v[172:175], v[212:215], v[64:67]
	v_mfma_f32_16x16x32_bf16 v[116:119], v[148:151], v[192:195], v[116:119]
	v_mfma_f32_16x16x32_bf16 v[112:115], v[176:179], v[192:195], v[112:115]
	v_mfma_f32_16x16x32_bf16 v[100:103], v[148:151], v[200:203], v[100:103]
	v_mfma_f32_16x16x32_bf16 v[96:99], v[176:179], v[200:203], v[96:99]
	v_mfma_f32_16x16x32_bf16 v[84:87], v[148:151], v[208:211], v[84:87]
	v_mfma_f32_16x16x32_bf16 v[80:83], v[176:179], v[208:211], v[80:83]
	v_mfma_f32_16x16x32_bf16 v[68:71], v[148:151], v[216:219], v[68:71]
	v_mfma_f32_16x16x32_bf16 v[64:67], v[176:179], v[216:219], v[64:67]
	s_setprio 0
	s_barrier
	s_add_i32 s48, s75, s58
	v_lshl_add_u64 v[220:221], v[220:221], 0, s[22:23]
	s_mov_b32 m0, s48
	ds_read_b128 v[180:183], v190 offset:49152
	ds_read_b128 v[192:195], v190 offset:50176
	ds_read_b128 v[196:199], v190 offset:51200
	ds_read_b128 v[200:203], v190 offset:52224
	ds_read_b128 v[204:207], v190 offset:53248
	ds_read_b128 v[208:211], v190 offset:54272
	ds_read_b128 v[212:215], v190 offset:55296
	ds_read_b128 v[216:219], v190 offset:56320
	global_load_lds_dwordx4 v[220:221], off
	s_add_i32 m0, s48, 0x2000
	s_add_u32 s48, s52, 0xb0080
	v_lshl_add_u64 v[220:221], v[222:223], 0, s[22:23]
	s_addc_u32 s49, s53, 0
	s_add_i32 s52, s76, s58
	global_load_lds_dwordx4 v[220:221], off
	v_lshl_add_u64 v[220:221], s[48:49], 0, v[154:155]
	s_mov_b32 m0, s52
	s_nop 0
	global_load_lds_dwordx4 v[220:221], off
	v_lshl_add_u64 v[220:221], s[48:49], 0, v[162:163]
	s_add_i32 m0, s52, 0x2000
	s_nop 0
	global_load_lds_dwordx4 v[220:221], off
	v_lshl_add_u64 v[220:221], v[224:225], 0, s[22:23]
	s_mov_b32 m0, s3
	s_nop 0
	global_load_lds_dwordx4 v[220:221], off
	v_lshl_add_u64 v[220:221], v[226:227], 0, s[22:23]
	s_mov_b32 m0, s64
	s_nop 0
	global_load_lds_dwordx4 v[220:221], off
	s_waitcnt vmcnt(8)
	s_waitcnt lgkmcnt(0)
	s_barrier
	s_setprio 1
	s_waitcnt lgkmcnt(0)
	v_mfma_f32_16x16x32_bf16 v[60:63], v[128:131], v[180:183], v[60:63]
	v_mfma_f32_16x16x32_bf16 v[56:59], v[136:139], v[180:183], v[56:59]
	v_mfma_f32_16x16x32_bf16 v[44:47], v[128:131], v[196:199], v[44:47]
	v_mfma_f32_16x16x32_bf16 v[40:43], v[136:139], v[196:199], v[40:43]
	v_mfma_f32_16x16x32_bf16 v[28:31], v[128:131], v[204:207], v[28:31]
	v_mfma_f32_16x16x32_bf16 v[24:27], v[136:139], v[204:207], v[24:27]
	v_mfma_f32_16x16x32_bf16 v[12:15], v[128:131], v[212:215], v[12:15]
	v_mfma_f32_16x16x32_bf16 v[8:11], v[136:139], v[212:215], v[8:11]
	v_mfma_f32_16x16x32_bf16 v[60:63], v[132:135], v[192:195], v[60:63]
	v_mfma_f32_16x16x32_bf16 v[56:59], v[140:143], v[192:195], v[56:59]
	v_mfma_f32_16x16x32_bf16 v[44:47], v[132:135], v[200:203], v[44:47]
	v_mfma_f32_16x16x32_bf16 v[40:43], v[140:143], v[200:203], v[40:43]
	v_mfma_f32_16x16x32_bf16 v[28:31], v[132:135], v[208:211], v[28:31]
	v_mfma_f32_16x16x32_bf16 v[24:27], v[140:143], v[208:211], v[24:27]
	v_mfma_f32_16x16x32_bf16 v[12:15], v[132:135], v[216:219], v[12:15]
	v_mfma_f32_16x16x32_bf16 v[8:11], v[140:143], v[216:219], v[8:11]
	s_setprio 0
	s_setprio 1
	v_mfma_f32_16x16x32_bf16 v[52:55], v[144:147], v[180:183], v[52:55]
	v_mfma_f32_16x16x32_bf16 v[48:51], v[172:175], v[180:183], v[48:51]
	v_mfma_f32_16x16x32_bf16 v[36:39], v[144:147], v[196:199], v[36:39]
	v_mfma_f32_16x16x32_bf16 v[32:35], v[172:175], v[196:199], v[32:35]
	v_mfma_f32_16x16x32_bf16 v[20:23], v[144:147], v[204:207], v[20:23]
	v_mfma_f32_16x16x32_bf16 v[16:19], v[172:175], v[204:207], v[16:19]
	v_mfma_f32_16x16x32_bf16 v[4:7], v[144:147], v[212:215], v[4:7]
	v_mfma_f32_16x16x32_bf16 v[0:3], v[172:175], v[212:215], v[0:3]
	v_mfma_f32_16x16x32_bf16 v[52:55], v[148:151], v[192:195], v[52:55]
	v_mfma_f32_16x16x32_bf16 v[48:51], v[176:179], v[192:195], v[48:51]
	v_mfma_f32_16x16x32_bf16 v[36:39], v[148:151], v[200:203], v[36:39]
	v_mfma_f32_16x16x32_bf16 v[32:35], v[176:179], v[200:203], v[32:35]
	v_mfma_f32_16x16x32_bf16 v[20:23], v[148:151], v[208:211], v[20:23]
	v_mfma_f32_16x16x32_bf16 v[16:19], v[176:179], v[208:211], v[16:19]
	v_mfma_f32_16x16x32_bf16 v[4:7], v[148:151], v[216:219], v[4:7]
	v_mfma_f32_16x16x32_bf16 v[0:3], v[176:179], v[216:219], v[0:3]
	s_setprio 0
	s_barrier
	s_add_i32 s74, s74, 2
	s_add_u32 s72, s72, 0x100
	s_addc_u32 s73, s73, 0
	s_cmp_gt_u32 s74, 41
	s_mov_b64 s[48:49], s[50:51]
